# LORA_UP epilogue: w0/a0 bias quads loaded once per tile, per-group load+vmcnt(0) pairs replaced by register copies
# speedup vs baseline: 1.0033x; 1.0033x over previous
; __device__ __forceinline__ u32x4 pack8(f32x4 a, f32x4 b) { u32x4 w; w.x = cvt_pk_bf16(a[0], a[1]); w.y = cvt_pk_bf16(a[2], a[3]); w.z = cvt_pk_bf16(b[0], b[1]); w.w = cvt_pk_bf16(b[2], b[3]); return w; }
; __device__ __forceinline__ float sigmoidf_(float x) { return 1.0f / (1.0f + __expf(-x)); }
; #define EPI_END } asm volatile("" ::: "memory"); }
;     __device__ __forceinline__ void operator()(const f32x4 (&acc)[2][2][4][2], const pg8::Unit& u, int wr, int wc, int fr, int fq) const {
;     ...
;             const int grp = u.pn >> 3;
;             EPI_BEGIN { const int c = col & 2047; const size_t off = (size_t)row * 2048 + c;
;                 if (grp == 0) { const f32x4 b0 = *(const f32x4*)(p0 + c), b1 = *(const f32x4*)(p0 + c + 4);
; #pragma unroll
;                     for (int e = 0; e < 4; ++e) { v0[e] = __expf(-0.6065306597126334f * sigmoidf_(v0[e] + b0[e])); v1[e] = __expf(-0.6065306597126334f * sigmoidf_(v1[e] + b1[e])); }
;                     *(f32x4*)(f0 + off) = v0; *(f32x4*)(f0 + off + 4) = v1;
;                 } else if (grp == 1) { const f32x4 b0 = *(const f32x4*)(p1 + c), b1 = *(const f32x4*)(p1 + c + 4);
; #pragma unroll
;                     for (int e = 0; e < 4; ++e) { v0[e] = sigmoidf_(v0[e] + b0[e]); v1[e] = sigmoidf_(v1[e] + b1[e]); }
;                     *(f32x4*)(f1 + off) = v0; *(f32x4*)(f1 + off + 4) = v1;
;                 } else { *(u32x4*)(o0 + off) = pack8(v0, v1); } } EPI_END
.LBB0_995:
	s_and_b64 vcc, exec, s[18:19]
	s_cbranch_vccz .LBB0_1048
	s_cmp_gt_u32 s4, 7
	s_cselect_b64 s[18:19], -1, 0
	s_and_b32 s20, s4, -8
	v_ashrrev_i32_e32 v159, 31, v158
	v_and_b32_e32 v180, 0x778, v156
	v_lshlrev_b32_e32 v166, 2, v180
	s_waitcnt lgkmcnt(0)
	global_load_dwordx4 v[190:193], v166, s[66:67]
	global_load_dwordx4 v[194:197], v166, s[66:67] offset:16
	global_load_dwordx4 v[198:201], v166, s[66:67] offset:512
	global_load_dwordx4 v[202:205], v166, s[66:67] offset:528
	global_load_dwordx4 v[224:227], v166, s[78:79]
	global_load_dwordx4 v[228:231], v166, s[78:79] offset:16
	global_load_dwordx4 v[232:235], v166, s[78:79] offset:512
	global_load_dwordx4 v[236:239], v166, s[78:79] offset:528
	s_waitcnt vmcnt(0)
	s_cmp_lg_u32 s20, 8
	v_lshlrev_b64 v[160:161], 11, v[158:159]
	s_cselect_b64 s[20:21], -1, 0
	v_or_b32_e32 v162, v160, v180
	v_mov_b32_e32 v163, v161
	s_mov_b64 s[22:23], -1
	s_and_b64 vcc, exec, s[18:19]
	s_cbranch_vccz .LBB0_1002
	s_and_b64 vcc, exec, s[20:21]
	s_cbranch_vccz .LBB0_999
	v_lshl_add_u64 v[132:133], v[162:163], 1, s[94:95]
	v_cvt_pk_bf16_f32 v128, v124, v125
	v_cvt_pk_bf16_f32 v129, v126, v127
	v_cvt_pk_bf16_f32 v130, v120, v121
	s_waitcnt lgkmcnt(0)
	v_cvt_pk_bf16_f32 v131, v122, v123
	global_store_dwordx4 v[132:133], v[128:131], off
	s_mov_b64 s[22:23], 0
.LBB0_999:
	s_andn2_b64 vcc, exec, s[22:23]
	s_cbranch_vccnz .LBB0_1001
	v_lshlrev_b32_e32 v128, 2, v180
	s_waitcnt lgkmcnt(0)
	s_nop 1
	v_mov_b32_e32 v130, v228
	v_mov_b32_e32 v131, v229
	v_mov_b32_e32 v132, v230
	v_mov_b32_e32 v133, v231
	v_mov_b32_e32 v134, v224
	v_mov_b32_e32 v135, v225
	v_mov_b32_e32 v136, v226
	v_mov_b32_e32 v137, v227
	v_add_f32_e32 v129, v120, v130
	v_add_f32_e32 v130, v121, v131
	v_add_f32_e32 v131, v122, v132
	v_mul_f32_e32 v129, 0xbfb8aa3b, v129
	v_mul_f32_e32 v130, 0xbfb8aa3b, v130
	v_mul_f32_e32 v131, 0xbfb8aa3b, v131
	v_add_f32_e32 v128, v124, v134
	v_exp_f32_e32 v134, v129
	v_add_f32_e32 v129, v125, v135
	v_exp_f32_e32 v135, v130
	v_add_f32_e32 v130, v126, v136
	v_exp_f32_e32 v136, v131
	v_add_f32_e32 v131, v127, v137
	v_mul_f32_e32 v130, 0xbfb8aa3b, v130
	v_mul_f32_e32 v131, 0xbfb8aa3b, v131
	v_exp_f32_e32 v130, v130
	v_exp_f32_e32 v131, v131
	v_mul_f32_e32 v128, 0xbfb8aa3b, v128
	v_mul_f32_e32 v129, 0xbfb8aa3b, v129
	v_exp_f32_e32 v128, v128
	v_pk_add_f32 v[130:131], v[130:131], 1.0 op_sel_hi:[1,0]
	v_exp_f32_e32 v129, v129
	v_div_scale_f32 v132, s[22:23], v131, v131, 1.0
	v_rcp_f32_e32 v137, v132
	v_pk_add_f32 v[128:129], v[128:129], 1.0 op_sel_hi:[1,0]
	v_fma_f32 v155, -v132, v137, 1.0
	v_fmac_f32_e32 v137, v155, v137
	v_div_scale_f32 v155, vcc, 1.0, v131, 1.0
	v_mul_f32_e32 v157, v155, v137
	v_fma_f32 v164, -v132, v157, v155
	v_fmac_f32_e32 v157, v164, v137
	v_fma_f32 v132, -v132, v157, v155
	v_div_fmas_f32 v132, v132, v137, v157
	v_div_fixup_f32 v131, v132, v131, 1.0
	v_div_scale_f32 v132, s[22:23], v130, v130, 1.0
	v_rcp_f32_e32 v137, v132
	s_nop 0
	v_fma_f32 v155, -v132, v137, 1.0
	v_fmac_f32_e32 v137, v155, v137
	v_div_scale_f32 v155, vcc, 1.0, v130, 1.0
	v_mul_f32_e32 v157, v155, v137
	v_fma_f32 v164, -v132, v157, v155
	v_fmac_f32_e32 v157, v164, v137
	v_fma_f32 v132, -v132, v157, v155
	v_div_fmas_f32 v132, v132, v137, v157
	v_div_fixup_f32 v130, v132, v130, 1.0
	v_div_scale_f32 v132, s[22:23], v129, v129, 1.0
	v_rcp_f32_e32 v137, v132
	s_nop 0
	v_fma_f32 v155, -v132, v137, 1.0
	v_fmac_f32_e32 v137, v155, v137
	v_div_scale_f32 v155, vcc, 1.0, v129, 1.0
	v_mul_f32_e32 v157, v155, v137
	v_fma_f32 v164, -v132, v157, v155
	v_fmac_f32_e32 v157, v164, v137
	v_fma_f32 v132, -v132, v157, v155
	v_div_fmas_f32 v132, v132, v137, v157
	v_div_fixup_f32 v129, v132, v129, 1.0
	v_div_scale_f32 v132, s[22:23], v128, v128, 1.0
	v_rcp_f32_e32 v137, v132
	s_nop 0
	v_fma_f32 v155, -v132, v137, 1.0
	v_fmac_f32_e32 v137, v155, v137
	v_div_scale_f32 v155, vcc, 1.0, v128, 1.0
	v_mul_f32_e32 v157, v155, v137
	v_fma_f32 v164, -v132, v157, v155
	v_fmac_f32_e32 v157, v164, v137
	v_fma_f32 v132, -v132, v157, v155
	v_div_fmas_f32 v132, v132, v137, v157
	v_div_fixup_f32 v128, v132, v128, 1.0
	v_add_f32_e32 v132, v123, v133
	v_mul_f32_e32 v132, 0xbfb8aa3b, v132
	v_exp_f32_e32 v137, v132
	v_pk_add_f32 v[132:133], v[134:135], 1.0 op_sel_hi:[1,0]
	v_pk_add_f32 v[134:135], v[136:137], 1.0 op_sel_hi:[1,0]
	s_nop 0
	v_div_scale_f32 v136, s[22:23], v135, v135, 1.0
	v_rcp_f32_e32 v137, v136
	s_nop 0
	v_fma_f32 v155, -v136, v137, 1.0
	v_fmac_f32_e32 v137, v155, v137
	v_div_scale_f32 v155, vcc, 1.0, v135, 1.0
	v_mul_f32_e32 v157, v155, v137
	v_fma_f32 v164, -v136, v157, v155
	v_fmac_f32_e32 v157, v164, v137
	v_fma_f32 v136, -v136, v157, v155
	v_div_fmas_f32 v136, v136, v137, v157
	v_div_fixup_f32 v135, v136, v135, 1.0
	v_div_scale_f32 v136, s[22:23], v134, v134, 1.0
	v_rcp_f32_e32 v137, v136
	s_nop 0
	v_fma_f32 v155, -v136, v137, 1.0
	v_fmac_f32_e32 v137, v155, v137
	v_div_scale_f32 v155, vcc, 1.0, v134, 1.0
	v_mul_f32_e32 v157, v155, v137
	v_fma_f32 v164, -v136, v157, v155
	v_fmac_f32_e32 v157, v164, v137
	v_fma_f32 v136, -v136, v157, v155
	v_div_fmas_f32 v136, v136, v137, v157
	v_div_fixup_f32 v134, v136, v134, 1.0
	v_div_scale_f32 v136, s[22:23], v133, v133, 1.0
	v_rcp_f32_e32 v137, v136
	s_nop 0
	v_fma_f32 v155, -v136, v137, 1.0
	v_fmac_f32_e32 v137, v155, v137
	v_div_scale_f32 v155, vcc, 1.0, v133, 1.0
	v_mul_f32_e32 v157, v155, v137
	v_fma_f32 v164, -v136, v157, v155
	v_fmac_f32_e32 v157, v164, v137
	v_fma_f32 v136, -v136, v157, v155
	v_div_fmas_f32 v136, v136, v137, v157
	v_div_fixup_f32 v133, v136, v133, 1.0
	v_div_scale_f32 v136, s[22:23], v132, v132, 1.0
	v_rcp_f32_e32 v137, v136
	v_readlane_b32 s22, v255, 36
	v_readlane_b32 s23, v255, 37
	v_fma_f32 v155, -v136, v137, 1.0
	v_fmac_f32_e32 v137, v155, v137
	v_div_scale_f32 v155, vcc, 1.0, v132, 1.0
	v_mul_f32_e32 v157, v155, v137
	v_fma_f32 v164, -v136, v157, v155
	v_fmac_f32_e32 v157, v164, v137
	v_fma_f32 v136, -v136, v157, v155
	v_div_fmas_f32 v136, v136, v137, v157
	v_div_fixup_f32 v132, v136, v132, 1.0
	v_lshl_add_u64 v[136:137], v[162:163], 2, s[22:23]
	global_store_dwordx4 v[136:137], v[128:131], off
	global_store_dwordx4 v[136:137], v[132:135], off offset:16

; __device__ __forceinline__ float sigmoidf_(float x) { return 1.0f / (1.0f + __expf(-x)); }
;     __device__ __forceinline__ void operator()(const f32x4 (&acc)[2][2][4][2], const pg8::Unit& u, int wr, int wc, int fr, int fq) const {
;     ...
;                 if (grp == 0) { const f32x4 b0 = *(const f32x4*)(p0 + c), b1 = *(const f32x4*)(p0 + c + 4);
; #pragma unroll
;                     for (int e = 0; e < 4; ++e) { v0[e] = __expf(-0.6065306597126334f * sigmoidf_(v0[e] + b0[e])); v1[e] = __expf(-0.6065306597126334f * sigmoidf_(v1[e] + b1[e])); }
;                     *(f32x4*)(f0 + off) = v0; *(f32x4*)(f0 + off + 4) = v1;
.LBB0_1002:
	s_andn2_b64 vcc, exec, s[22:23]
	v_lshlrev_b32_e32 v155, 2, v180
	s_cbranch_vccnz .LBB0_1004
	s_waitcnt lgkmcnt(0)
	s_nop 1
	v_mov_b32_e32 v130, v194
	v_mov_b32_e32 v131, v195
	v_mov_b32_e32 v132, v196
	v_mov_b32_e32 v133, v197
	v_mov_b32_e32 v134, v190
	v_mov_b32_e32 v135, v191
	v_mov_b32_e32 v136, v192
	v_mov_b32_e32 v137, v193
	v_add_f32_e32 v128, v124, v134
	v_mul_f32_e32 v128, 0xbfb8aa3b, v128
	v_exp_f32_e32 v128, v128
	s_nop 0
	v_add_f32_e32 v128, 1.0, v128
	v_div_scale_f32 v129, s[22:23], v128, v128, 1.0
	v_rcp_f32_e32 v134, v129
	s_nop 0
	v_fma_f32 v157, -v129, v134, 1.0
	v_fmac_f32_e32 v134, v157, v134
	v_div_scale_f32 v157, vcc, 1.0, v128, 1.0
	v_mul_f32_e32 v164, v157, v134
	v_fma_f32 v165, -v129, v164, v157
	v_fmac_f32_e32 v164, v165, v134
	v_fma_f32 v129, -v129, v164, v157
	v_div_fmas_f32 v129, v129, v134, v164
	v_div_fixup_f32 v128, v129, v128, 1.0
	v_add_f32_e32 v129, v120, v130
	v_mul_f32_e32 v129, 0xbfb8aa3b, v129
	v_exp_f32_e32 v129, v129
	v_mul_f32_e32 v128, 0xbf1b4598, v128
	v_mul_f32_e32 v128, 0x3fb8aa3b, v128
	v_exp_f32_e32 v128, v128
	v_add_f32_e32 v129, 1.0, v129
	v_div_scale_f32 v130, s[22:23], v129, v129, 1.0
	v_rcp_f32_e32 v134, v130
	s_nop 0
	v_fma_f32 v157, -v130, v134, 1.0
	v_fmac_f32_e32 v134, v157, v134
	v_div_scale_f32 v157, vcc, 1.0, v129, 1.0
	v_mul_f32_e32 v164, v157, v134
	v_fma_f32 v165, -v130, v164, v157
	v_fmac_f32_e32 v164, v165, v134
	v_fma_f32 v130, -v130, v164, v157
	v_div_fmas_f32 v130, v130, v134, v164
	v_div_fixup_f32 v129, v130, v129, 1.0
	v_mul_f32_e32 v129, 0xbf1b4598, v129
	v_mul_f32_e32 v129, 0x3fb8aa3b, v129
	v_exp_f32_e32 v134, v129
	v_add_f32_e32 v129, v125, v135
	v_mul_f32_e32 v129, 0xbfb8aa3b, v129
	v_exp_f32_e32 v129, v129
	s_nop 0
	v_add_f32_e32 v129, 1.0, v129
	v_div_scale_f32 v130, s[22:23], v129, v129, 1.0
	v_rcp_f32_e32 v135, v130
	s_nop 0
	v_fma_f32 v157, -v130, v135, 1.0
	v_fmac_f32_e32 v135, v157, v135
	v_div_scale_f32 v157, vcc, 1.0, v129, 1.0
	v_mul_f32_e32 v164, v157, v135
	v_fma_f32 v165, -v130, v164, v157
	v_fmac_f32_e32 v164, v165, v135
	v_fma_f32 v130, -v130, v164, v157
	v_div_fmas_f32 v130, v130, v135, v164
	v_div_fixup_f32 v129, v130, v129, 1.0
	v_add_f32_e32 v130, v121, v131
	v_mul_f32_e32 v130, 0xbfb8aa3b, v130
	v_exp_f32_e32 v130, v130
	v_mul_f32_e32 v129, 0xbf1b4598, v129
	v_mul_f32_e32 v129, 0x3fb8aa3b, v129
	v_exp_f32_e32 v129, v129
	v_add_f32_e32 v130, 1.0, v130
	v_div_scale_f32 v131, s[22:23], v130, v130, 1.0
	v_rcp_f32_e32 v135, v131
	s_nop 0
	v_fma_f32 v157, -v131, v135, 1.0
	v_fmac_f32_e32 v135, v157, v135
	v_div_scale_f32 v157, vcc, 1.0, v130, 1.0
	v_mul_f32_e32 v164, v157, v135
	v_fma_f32 v165, -v131, v164, v157
	v_fmac_f32_e32 v164, v165, v135
	v_fma_f32 v131, -v131, v164, v157
	v_div_fmas_f32 v131, v131, v135, v164
	v_div_fixup_f32 v130, v131, v130, 1.0
	v_mul_f32_e32 v130, 0xbf1b4598, v130
	v_mul_f32_e32 v130, 0x3fb8aa3b, v130
	v_exp_f32_e32 v135, v130
	v_add_f32_e32 v130, v126, v136
	v_mul_f32_e32 v130, 0xbfb8aa3b, v130
	v_exp_f32_e32 v130, v130
	s_nop 0
	v_add_f32_e32 v130, 1.0, v130
	v_div_scale_f32 v131, s[22:23], v130, v130, 1.0
	v_rcp_f32_e32 v136, v131
	s_nop 0
	v_fma_f32 v157, -v131, v136, 1.0
	v_fmac_f32_e32 v136, v157, v136
	v_div_scale_f32 v157, vcc, 1.0, v130, 1.0
	v_mul_f32_e32 v164, v157, v136
	v_fma_f32 v165, -v131, v164, v157
	v_fmac_f32_e32 v164, v165, v136
	v_fma_f32 v131, -v131, v164, v157
	v_div_fmas_f32 v131, v131, v136, v164
	v_div_fixup_f32 v130, v131, v130, 1.0
	v_add_f32_e32 v131, v122, v132
	v_mul_f32_e32 v131, 0xbfb8aa3b, v131
	v_exp_f32_e32 v131, v131
	v_mul_f32_e32 v130, 0xbf1b4598, v130
	v_mul_f32_e32 v130, 0x3fb8aa3b, v130
	v_exp_f32_e32 v130, v130
	v_add_f32_e32 v131, 1.0, v131
	v_div_scale_f32 v132, s[22:23], v131, v131, 1.0
	v_rcp_f32_e32 v136, v132
	s_nop 0
	v_fma_f32 v157, -v132, v136, 1.0
	v_fmac_f32_e32 v136, v157, v136
	v_div_scale_f32 v157, vcc, 1.0, v131, 1.0
	v_mul_f32_e32 v164, v157, v136
	v_fma_f32 v165, -v132, v164, v157
	v_fmac_f32_e32 v164, v165, v136
	v_fma_f32 v132, -v132, v164, v157
	v_div_fmas_f32 v132, v132, v136, v164
	v_div_fixup_f32 v131, v132, v131, 1.0
	v_mul_f32_e32 v131, 0xbf1b4598, v131
	v_mul_f32_e32 v131, 0x3fb8aa3b, v131
	v_exp_f32_e32 v136, v131
	v_add_f32_e32 v131, v127, v137
	v_mul_f32_e32 v131, 0xbfb8aa3b, v131
	v_exp_f32_e32 v131, v131
	s_nop 0
	v_add_f32_e32 v131, 1.0, v131
	v_div_scale_f32 v132, s[22:23], v131, v131, 1.0
	v_rcp_f32_e32 v137, v132
	s_nop 0
	v_fma_f32 v157, -v132, v137, 1.0
	v_fmac_f32_e32 v137, v157, v137
	v_div_scale_f32 v157, vcc, 1.0, v131, 1.0
	v_mul_f32_e32 v164, v157, v137
	v_fma_f32 v165, -v132, v164, v157
	v_fmac_f32_e32 v164, v165, v137
	v_fma_f32 v132, -v132, v164, v157
	v_div_fmas_f32 v132, v132, v137, v164
	v_div_fixup_f32 v131, v132, v131, 1.0
	v_add_f32_e32 v132, v123, v133
	v_mul_f32_e32 v132, 0xbfb8aa3b, v132
	v_exp_f32_e32 v132, v132
	v_mul_f32_e32 v131, 0xbf1b4598, v131
	v_mul_f32_e32 v131, 0x3fb8aa3b, v131
	v_exp_f32_e32 v131, v131
	v_add_f32_e32 v132, 1.0, v132
	v_div_scale_f32 v133, s[22:23], v132, v132, 1.0
	v_rcp_f32_e32 v137, v133
	s_nop 0
	v_fma_f32 v157, -v133, v137, 1.0
	v_fmac_f32_e32 v137, v157, v137
	v_div_scale_f32 v157, vcc, 1.0, v132, 1.0
	v_mul_f32_e32 v164, v157, v137
	v_fma_f32 v165, -v133, v164, v157
	v_fmac_f32_e32 v164, v165, v137
	v_fma_f32 v133, -v133, v164, v157
	v_div_fmas_f32 v133, v133, v137, v164
	v_div_fixup_f32 v132, v133, v132, 1.0
	v_mul_f32_e32 v132, 0xbf1b4598, v132
	v_mul_f32_e32 v132, 0x3fb8aa3b, v132
	v_exp_f32_e32 v137, v132
	v_lshl_add_u64 v[132:133], v[162:163], 2, s[50:51]
	global_store_dwordx4 v[132:133], v[128:131], off
	global_store_dwordx4 v[132:133], v[134:137], off offset:16

; __device__ __forceinline__ float sigmoidf_(float x) { return 1.0f / (1.0f + __expf(-x)); }
;     __device__ __forceinline__ void operator()(const f32x4 (&acc)[2][2][4][2], const pg8::Unit& u, int wr, int wc, int fr, int fq) const {
;     ...
;                 } else if (grp == 1) { const f32x4 b0 = *(const f32x4*)(p1 + c), b1 = *(const f32x4*)(p1 + c + 4);
; #pragma unroll
;                     for (int e = 0; e < 4; ++e) { v0[e] = sigmoidf_(v0[e] + b0[e]); v1[e] = sigmoidf_(v1[e] + b1[e]); }
;                     *(f32x4*)(f1 + off) = v0; *(f32x4*)(f1 + off + 4) = v1;
.LBB0_1007:
	s_andn2_b64 vcc, exec, s[18:19]
	s_cbranch_vccnz .LBB0_1009
	s_waitcnt lgkmcnt(0)
	s_nop 1
	v_mov_b32_e32 v130, v236
	v_mov_b32_e32 v131, v237
	v_mov_b32_e32 v132, v238
	v_mov_b32_e32 v133, v239
	v_mov_b32_e32 v134, v232
	v_mov_b32_e32 v135, v233
	v_mov_b32_e32 v136, v234
	v_mov_b32_e32 v137, v235
	v_add_f32_e32 v129, v112, v130
	v_add_f32_e32 v130, v113, v131
	v_add_f32_e32 v131, v114, v132
	v_mul_f32_e32 v129, 0xbfb8aa3b, v129
	v_mul_f32_e32 v130, 0xbfb8aa3b, v130
	v_mul_f32_e32 v131, 0xbfb8aa3b, v131
	v_add_f32_e32 v128, v116, v134
	v_exp_f32_e32 v134, v129
	v_add_f32_e32 v129, v117, v135
	v_exp_f32_e32 v135, v130
	v_add_f32_e32 v130, v118, v136
	v_exp_f32_e32 v136, v131
	v_add_f32_e32 v131, v119, v137
	v_mul_f32_e32 v130, 0xbfb8aa3b, v130
	v_mul_f32_e32 v131, 0xbfb8aa3b, v131
	v_exp_f32_e32 v130, v130
	v_exp_f32_e32 v131, v131
	v_mul_f32_e32 v128, 0xbfb8aa3b, v128
	v_mul_f32_e32 v129, 0xbfb8aa3b, v129
	v_exp_f32_e32 v128, v128
	v_pk_add_f32 v[130:131], v[130:131], 1.0 op_sel_hi:[1,0]
	v_exp_f32_e32 v129, v129
	v_div_scale_f32 v132, s[18:19], v131, v131, 1.0
	v_rcp_f32_e32 v137, v132
	v_pk_add_f32 v[128:129], v[128:129], 1.0 op_sel_hi:[1,0]
	v_fma_f32 v157, -v132, v137, 1.0
	v_fmac_f32_e32 v137, v157, v137
	v_div_scale_f32 v157, vcc, 1.0, v131, 1.0
	v_mul_f32_e32 v162, v157, v137
	v_fma_f32 v163, -v132, v162, v157
	v_fmac_f32_e32 v162, v163, v137
	v_fma_f32 v132, -v132, v162, v157
	v_div_fmas_f32 v132, v132, v137, v162
	v_div_fixup_f32 v131, v132, v131, 1.0
	v_div_scale_f32 v132, s[18:19], v130, v130, 1.0
	v_rcp_f32_e32 v137, v132
	s_nop 0
	v_fma_f32 v157, -v132, v137, 1.0
	v_fmac_f32_e32 v137, v157, v137
	v_div_scale_f32 v157, vcc, 1.0, v130, 1.0
	v_mul_f32_e32 v162, v157, v137
	v_fma_f32 v163, -v132, v162, v157
	v_fmac_f32_e32 v162, v163, v137
	v_fma_f32 v132, -v132, v162, v157
	v_div_fmas_f32 v132, v132, v137, v162
	v_div_fixup_f32 v130, v132, v130, 1.0
	v_div_scale_f32 v132, s[18:19], v129, v129, 1.0
	v_rcp_f32_e32 v137, v132
	s_nop 0
	v_fma_f32 v157, -v132, v137, 1.0
	v_fmac_f32_e32 v137, v157, v137
	v_div_scale_f32 v157, vcc, 1.0, v129, 1.0
	v_mul_f32_e32 v162, v157, v137
	v_fma_f32 v163, -v132, v162, v157
	v_fmac_f32_e32 v162, v163, v137
	v_fma_f32 v132, -v132, v162, v157
	v_div_fmas_f32 v132, v132, v137, v162
	v_div_fixup_f32 v129, v132, v129, 1.0
	v_div_scale_f32 v132, s[18:19], v128, v128, 1.0
	v_rcp_f32_e32 v137, v132
	s_nop 0
	v_fma_f32 v157, -v132, v137, 1.0
	v_fmac_f32_e32 v137, v157, v137
	v_div_scale_f32 v157, vcc, 1.0, v128, 1.0
	v_mul_f32_e32 v162, v157, v137
	v_fma_f32 v163, -v132, v162, v157
	v_fmac_f32_e32 v162, v163, v137
	v_fma_f32 v132, -v132, v162, v157
	v_div_fmas_f32 v132, v132, v137, v162
	v_div_fixup_f32 v128, v132, v128, 1.0
	v_add_f32_e32 v132, v115, v133
	v_mul_f32_e32 v132, 0xbfb8aa3b, v132
	v_exp_f32_e32 v137, v132
	v_pk_add_f32 v[132:133], v[134:135], 1.0 op_sel_hi:[1,0]
	v_pk_add_f32 v[134:135], v[136:137], 1.0 op_sel_hi:[1,0]
	s_nop 0
	v_div_scale_f32 v136, s[18:19], v135, v135, 1.0
	v_rcp_f32_e32 v137, v136
	s_nop 0
	v_fma_f32 v157, -v136, v137, 1.0
	v_fmac_f32_e32 v137, v157, v137
	v_div_scale_f32 v157, vcc, 1.0, v135, 1.0
	v_mul_f32_e32 v162, v157, v137
	v_fma_f32 v163, -v136, v162, v157
	v_fmac_f32_e32 v162, v163, v137
	v_fma_f32 v136, -v136, v162, v157
	v_div_fmas_f32 v136, v136, v137, v162
	v_div_fixup_f32 v135, v136, v135, 1.0
	v_div_scale_f32 v136, s[18:19], v134, v134, 1.0
	v_rcp_f32_e32 v137, v136
	s_nop 0
	v_fma_f32 v157, -v136, v137, 1.0
	v_fmac_f32_e32 v137, v157, v137
	v_div_scale_f32 v157, vcc, 1.0, v134, 1.0
	v_mul_f32_e32 v162, v157, v137
	v_fma_f32 v163, -v136, v162, v157
	v_fmac_f32_e32 v162, v163, v137
	v_fma_f32 v136, -v136, v162, v157
	v_div_fmas_f32 v136, v136, v137, v162
	v_div_fixup_f32 v134, v136, v134, 1.0
	v_div_scale_f32 v136, s[18:19], v133, v133, 1.0
	v_rcp_f32_e32 v137, v136
	s_nop 0
	v_fma_f32 v157, -v136, v137, 1.0
	v_fmac_f32_e32 v137, v157, v137
	v_div_scale_f32 v157, vcc, 1.0, v133, 1.0
	v_mul_f32_e32 v162, v157, v137
	v_fma_f32 v163, -v136, v162, v157
	v_fmac_f32_e32 v162, v163, v137
	v_fma_f32 v136, -v136, v162, v157
	v_div_fmas_f32 v136, v136, v137, v162
	v_div_fixup_f32 v133, v136, v133, 1.0
	v_div_scale_f32 v136, s[18:19], v132, v132, 1.0
	v_rcp_f32_e32 v137, v136
	v_readlane_b32 s18, v255, 36
	v_readlane_b32 s19, v255, 37
	v_fma_f32 v157, -v136, v137, 1.0
	v_fmac_f32_e32 v137, v157, v137
	v_div_scale_f32 v157, vcc, 1.0, v132, 1.0
	v_mul_f32_e32 v162, v157, v137
	v_fma_f32 v163, -v136, v162, v157
	v_fmac_f32_e32 v162, v163, v137
	v_fma_f32 v136, -v136, v162, v157
	v_div_fmas_f32 v136, v136, v137, v162
	v_div_fixup_f32 v132, v136, v132, 1.0
	v_lshl_add_u64 v[136:137], v[160:161], 0, v[180:181]
	v_lshl_add_u64 v[136:137], v[136:137], 2, s[18:19]
	global_store_dwordx4 v[136:137], v[128:131], off offset:512
	global_store_dwordx4 v[136:137], v[132:135], off offset:528

; __device__ __forceinline__ float sigmoidf_(float x) { return 1.0f / (1.0f + __expf(-x)); }
;     __device__ __forceinline__ void operator()(const f32x4 (&acc)[2][2][4][2], const pg8::Unit& u, int wr, int wc, int fr, int fq) const {
;     ...
;                 if (grp == 0) { const f32x4 b0 = *(const f32x4*)(p0 + c), b1 = *(const f32x4*)(p0 + c + 4);
; #pragma unroll
;                     for (int e = 0; e < 4; ++e) { v0[e] = __expf(-0.6065306597126334f * sigmoidf_(v0[e] + b0[e])); v1[e] = __expf(-0.6065306597126334f * sigmoidf_(v1[e] + b1[e])); }
;                     *(f32x4*)(f0 + off) = v0; *(f32x4*)(f0 + off + 4) = v1;
.LBB0_1010:
	s_andn2_b64 vcc, exec, s[22:23]
	s_cbranch_vccnz .LBB0_1012
	s_waitcnt lgkmcnt(0)
	s_nop 1
	v_mov_b32_e32 v130, v202
	v_mov_b32_e32 v131, v203
	v_mov_b32_e32 v132, v204
	v_mov_b32_e32 v133, v205
	v_mov_b32_e32 v134, v198
	v_mov_b32_e32 v135, v199
	v_mov_b32_e32 v136, v200
	v_mov_b32_e32 v137, v201
	v_add_f32_e32 v128, v116, v134
	v_mul_f32_e32 v128, 0xbfb8aa3b, v128
	v_exp_f32_e32 v128, v128
	s_nop 0
	v_add_f32_e32 v128, 1.0, v128
	v_div_scale_f32 v129, s[18:19], v128, v128, 1.0
	v_rcp_f32_e32 v134, v129
	s_nop 0
	v_fma_f32 v157, -v129, v134, 1.0
	v_fmac_f32_e32 v134, v157, v134
	v_div_scale_f32 v157, vcc, 1.0, v128, 1.0
	v_mul_f32_e32 v162, v157, v134
	v_fma_f32 v163, -v129, v162, v157
	v_fmac_f32_e32 v162, v163, v134
	v_fma_f32 v129, -v129, v162, v157
	v_div_fmas_f32 v129, v129, v134, v162
	v_div_fixup_f32 v128, v129, v128, 1.0
	v_add_f32_e32 v129, v112, v130
	v_mul_f32_e32 v129, 0xbfb8aa3b, v129
	v_exp_f32_e32 v129, v129
	v_mul_f32_e32 v128, 0xbf1b4598, v128
	v_mul_f32_e32 v128, 0x3fb8aa3b, v128
	v_exp_f32_e32 v128, v128
	v_add_f32_e32 v129, 1.0, v129
	v_div_scale_f32 v130, s[18:19], v129, v129, 1.0
	v_rcp_f32_e32 v134, v130
	s_nop 0
	v_fma_f32 v157, -v130, v134, 1.0
	v_fmac_f32_e32 v134, v157, v134
	v_div_scale_f32 v157, vcc, 1.0, v129, 1.0
	v_mul_f32_e32 v162, v157, v134
	v_fma_f32 v163, -v130, v162, v157
	v_fmac_f32_e32 v162, v163, v134
	v_fma_f32 v130, -v130, v162, v157
	v_div_fmas_f32 v130, v130, v134, v162
	v_div_fixup_f32 v129, v130, v129, 1.0
	v_mul_f32_e32 v129, 0xbf1b4598, v129
	v_mul_f32_e32 v129, 0x3fb8aa3b, v129
	v_exp_f32_e32 v134, v129
	v_add_f32_e32 v129, v117, v135
	v_mul_f32_e32 v129, 0xbfb8aa3b, v129
	v_exp_f32_e32 v129, v129
	s_nop 0
	v_add_f32_e32 v129, 1.0, v129
	v_div_scale_f32 v130, s[18:19], v129, v129, 1.0
	v_rcp_f32_e32 v135, v130
	s_nop 0
	v_fma_f32 v157, -v130, v135, 1.0
	v_fmac_f32_e32 v135, v157, v135
	v_div_scale_f32 v157, vcc, 1.0, v129, 1.0
	v_mul_f32_e32 v162, v157, v135
	v_fma_f32 v163, -v130, v162, v157
	v_fmac_f32_e32 v162, v163, v135
	v_fma_f32 v130, -v130, v162, v157
	v_div_fmas_f32 v130, v130, v135, v162
	v_div_fixup_f32 v129, v130, v129, 1.0
	v_add_f32_e32 v130, v113, v131
	v_mul_f32_e32 v130, 0xbfb8aa3b, v130
	v_exp_f32_e32 v130, v130
	v_mul_f32_e32 v129, 0xbf1b4598, v129
	v_mul_f32_e32 v129, 0x3fb8aa3b, v129
	v_exp_f32_e32 v129, v129
	v_add_f32_e32 v130, 1.0, v130
	v_div_scale_f32 v131, s[18:19], v130, v130, 1.0
	v_rcp_f32_e32 v135, v131
	s_nop 0
	v_fma_f32 v157, -v131, v135, 1.0
	v_fmac_f32_e32 v135, v157, v135
	v_div_scale_f32 v157, vcc, 1.0, v130, 1.0
	v_mul_f32_e32 v162, v157, v135
	v_fma_f32 v163, -v131, v162, v157
	v_fmac_f32_e32 v162, v163, v135
	v_fma_f32 v131, -v131, v162, v157
	v_div_fmas_f32 v131, v131, v135, v162
	v_div_fixup_f32 v130, v131, v130, 1.0
	v_mul_f32_e32 v130, 0xbf1b4598, v130
	v_mul_f32_e32 v130, 0x3fb8aa3b, v130
	v_exp_f32_e32 v135, v130
	v_add_f32_e32 v130, v118, v136
	v_mul_f32_e32 v130, 0xbfb8aa3b, v130
	v_exp_f32_e32 v130, v130
	s_nop 0
	v_add_f32_e32 v130, 1.0, v130
	v_div_scale_f32 v131, s[18:19], v130, v130, 1.0
	v_rcp_f32_e32 v136, v131
	s_nop 0
	v_fma_f32 v157, -v131, v136, 1.0
	v_fmac_f32_e32 v136, v157, v136
	v_div_scale_f32 v157, vcc, 1.0, v130, 1.0
	v_mul_f32_e32 v162, v157, v136
	v_fma_f32 v163, -v131, v162, v157
	v_fmac_f32_e32 v162, v163, v136
	v_fma_f32 v131, -v131, v162, v157
	v_div_fmas_f32 v131, v131, v136, v162
	v_div_fixup_f32 v130, v131, v130, 1.0
	v_add_f32_e32 v131, v114, v132
	v_mul_f32_e32 v131, 0xbfb8aa3b, v131
	v_exp_f32_e32 v131, v131
	v_mul_f32_e32 v130, 0xbf1b4598, v130
	v_mul_f32_e32 v130, 0x3fb8aa3b, v130
	v_exp_f32_e32 v130, v130
	v_add_f32_e32 v131, 1.0, v131
	v_div_scale_f32 v132, s[18:19], v131, v131, 1.0
	v_rcp_f32_e32 v136, v132
	s_nop 0
	v_fma_f32 v157, -v132, v136, 1.0
	v_fmac_f32_e32 v136, v157, v136
	v_div_scale_f32 v157, vcc, 1.0, v131, 1.0
	v_mul_f32_e32 v162, v157, v136
	v_fma_f32 v163, -v132, v162, v157
	v_fmac_f32_e32 v162, v163, v136
	v_fma_f32 v132, -v132, v162, v157
	v_div_fmas_f32 v132, v132, v136, v162
	v_div_fixup_f32 v131, v132, v131, 1.0
	v_mul_f32_e32 v131, 0xbf1b4598, v131
	v_mul_f32_e32 v131, 0x3fb8aa3b, v131
	v_exp_f32_e32 v136, v131
	v_add_f32_e32 v131, v119, v137
	v_mul_f32_e32 v131, 0xbfb8aa3b, v131
	v_exp_f32_e32 v131, v131
	s_nop 0
	v_add_f32_e32 v131, 1.0, v131
	v_div_scale_f32 v132, s[18:19], v131, v131, 1.0
	v_rcp_f32_e32 v137, v132
	s_nop 0
	v_fma_f32 v157, -v132, v137, 1.0
	v_fmac_f32_e32 v137, v157, v137
	v_div_scale_f32 v157, vcc, 1.0, v131, 1.0
	v_mul_f32_e32 v162, v157, v137
	v_fma_f32 v163, -v132, v162, v157
	v_fmac_f32_e32 v162, v163, v137
	v_fma_f32 v132, -v132, v162, v157
	v_div_fmas_f32 v132, v132, v137, v162
	v_div_fixup_f32 v131, v132, v131, 1.0
	v_add_f32_e32 v132, v115, v133
	v_mul_f32_e32 v132, 0xbfb8aa3b, v132
	v_exp_f32_e32 v132, v132
	v_mul_f32_e32 v131, 0xbf1b4598, v131
	v_mul_f32_e32 v131, 0x3fb8aa3b, v131
	v_exp_f32_e32 v131, v131
	v_add_f32_e32 v132, 1.0, v132
	v_div_scale_f32 v133, s[18:19], v132, v132, 1.0
	v_rcp_f32_e32 v137, v133
	s_nop 0
	v_fma_f32 v157, -v133, v137, 1.0
	v_fmac_f32_e32 v137, v157, v137
	v_div_scale_f32 v157, vcc, 1.0, v132, 1.0
	v_mul_f32_e32 v162, v157, v137
	v_fma_f32 v163, -v133, v162, v157
	v_fmac_f32_e32 v162, v163, v137
	v_fma_f32 v133, -v133, v162, v157
	v_div_fmas_f32 v133, v133, v137, v162
	v_div_fixup_f32 v132, v133, v132, 1.0
	v_mul_f32_e32 v132, 0xbf1b4598, v132
	v_mul_f32_e32 v132, 0x3fb8aa3b, v132
	v_exp_f32_e32 v137, v132
	v_lshl_add_u64 v[132:133], v[160:161], 0, v[180:181]
	v_lshl_add_u64 v[132:133], v[132:133], 2, s[50:51]
	global_store_dwordx4 v[132:133], v[128:131], off offset:512
	global_store_dwordx4 v[132:133], v[134:137], off offset:528

; __device__ __forceinline__ float sigmoidf_(float x) { return 1.0f / (1.0f + __expf(-x)); }
;     __device__ __forceinline__ void operator()(const f32x4 (&acc)[2][2][4][2], const pg8::Unit& u, int wr, int wc, int fr, int fq) const {
;     ...
;                 if (grp == 0) { const f32x4 b0 = *(const f32x4*)(p0 + c), b1 = *(const f32x4*)(p0 + c + 4);
; #pragma unroll
;                     for (int e = 0; e < 4; ++e) { v0[e] = __expf(-0.6065306597126334f * sigmoidf_(v0[e] + b0[e])); v1[e] = __expf(-0.6065306597126334f * sigmoidf_(v1[e] + b1[e])); }
;                     *(f32x4*)(f0 + off) = v0; *(f32x4*)(f0 + off + 4) = v1;
.LBB0_1016:
	s_waitcnt lgkmcnt(0)
	s_nop 1
	v_mov_b32_e32 v130, v202
	v_mov_b32_e32 v131, v203
	v_mov_b32_e32 v132, v204
	v_mov_b32_e32 v133, v205
	v_mov_b32_e32 v134, v198
	v_mov_b32_e32 v135, v199
	v_mov_b32_e32 v136, v200
	v_mov_b32_e32 v137, v201
	v_add_f32_e32 v128, v100, v134
	v_mul_f32_e32 v128, 0xbfb8aa3b, v128
	v_exp_f32_e32 v128, v128
	s_nop 0
	v_add_f32_e32 v128, 1.0, v128
	v_div_scale_f32 v129, s[18:19], v128, v128, 1.0
	v_rcp_f32_e32 v134, v129
	s_nop 0
	v_fma_f32 v157, -v129, v134, 1.0
	v_fmac_f32_e32 v134, v157, v134
	v_div_scale_f32 v157, vcc, 1.0, v128, 1.0
	v_mul_f32_e32 v162, v157, v134
	v_fma_f32 v163, -v129, v162, v157
	v_fmac_f32_e32 v162, v163, v134
	v_fma_f32 v129, -v129, v162, v157
	v_div_fmas_f32 v129, v129, v134, v162
	v_div_fixup_f32 v128, v129, v128, 1.0
	v_add_f32_e32 v129, v96, v130
	v_mul_f32_e32 v129, 0xbfb8aa3b, v129
	v_exp_f32_e32 v129, v129
	v_mul_f32_e32 v128, 0xbf1b4598, v128
	v_mul_f32_e32 v128, 0x3fb8aa3b, v128
	v_exp_f32_e32 v128, v128
	v_add_f32_e32 v129, 1.0, v129
	v_div_scale_f32 v130, s[18:19], v129, v129, 1.0
	v_rcp_f32_e32 v134, v130
	s_nop 0
	v_fma_f32 v157, -v130, v134, 1.0
	v_fmac_f32_e32 v134, v157, v134
	v_div_scale_f32 v157, vcc, 1.0, v129, 1.0
	v_mul_f32_e32 v162, v157, v134
	v_fma_f32 v163, -v130, v162, v157
	v_fmac_f32_e32 v162, v163, v134
	v_fma_f32 v130, -v130, v162, v157
	v_div_fmas_f32 v130, v130, v134, v162
	v_div_fixup_f32 v129, v130, v129, 1.0
	v_mul_f32_e32 v129, 0xbf1b4598, v129
	v_mul_f32_e32 v129, 0x3fb8aa3b, v129
	v_exp_f32_e32 v134, v129
	v_add_f32_e32 v129, v101, v135
	v_mul_f32_e32 v129, 0xbfb8aa3b, v129
	v_exp_f32_e32 v129, v129
	s_nop 0
	v_add_f32_e32 v129, 1.0, v129
	v_div_scale_f32 v130, s[18:19], v129, v129, 1.0
	v_rcp_f32_e32 v135, v130
	s_nop 0
	v_fma_f32 v157, -v130, v135, 1.0
	v_fmac_f32_e32 v135, v157, v135
	v_div_scale_f32 v157, vcc, 1.0, v129, 1.0
	v_mul_f32_e32 v162, v157, v135
	v_fma_f32 v163, -v130, v162, v157
	v_fmac_f32_e32 v162, v163, v135
	v_fma_f32 v130, -v130, v162, v157
	v_div_fmas_f32 v130, v130, v135, v162
	v_div_fixup_f32 v129, v130, v129, 1.0
	v_add_f32_e32 v130, v97, v131
	v_mul_f32_e32 v130, 0xbfb8aa3b, v130
	v_exp_f32_e32 v130, v130
	v_mul_f32_e32 v129, 0xbf1b4598, v129
	v_mul_f32_e32 v129, 0x3fb8aa3b, v129
	v_exp_f32_e32 v129, v129
	v_add_f32_e32 v130, 1.0, v130
	v_div_scale_f32 v131, s[18:19], v130, v130, 1.0
	v_rcp_f32_e32 v135, v131
	s_nop 0
	v_fma_f32 v157, -v131, v135, 1.0
	v_fmac_f32_e32 v135, v157, v135
	v_div_scale_f32 v157, vcc, 1.0, v130, 1.0
	v_mul_f32_e32 v162, v157, v135
	v_fma_f32 v163, -v131, v162, v157
	v_fmac_f32_e32 v162, v163, v135
	v_fma_f32 v131, -v131, v162, v157
	v_div_fmas_f32 v131, v131, v135, v162
	v_div_fixup_f32 v130, v131, v130, 1.0
	v_mul_f32_e32 v130, 0xbf1b4598, v130
	v_mul_f32_e32 v130, 0x3fb8aa3b, v130
	v_exp_f32_e32 v135, v130
	v_add_f32_e32 v130, v102, v136
	v_mul_f32_e32 v130, 0xbfb8aa3b, v130
	v_exp_f32_e32 v130, v130
	s_nop 0
	v_add_f32_e32 v130, 1.0, v130
	v_div_scale_f32 v131, s[18:19], v130, v130, 1.0
	v_rcp_f32_e32 v136, v131
	s_nop 0
	v_fma_f32 v157, -v131, v136, 1.0
	v_fmac_f32_e32 v136, v157, v136
	v_div_scale_f32 v157, vcc, 1.0, v130, 1.0
	v_mul_f32_e32 v162, v157, v136
	v_fma_f32 v163, -v131, v162, v157
	v_fmac_f32_e32 v162, v163, v136
	v_fma_f32 v131, -v131, v162, v157
	v_div_fmas_f32 v131, v131, v136, v162
	v_div_fixup_f32 v130, v131, v130, 1.0
	v_add_f32_e32 v131, v98, v132
	v_mul_f32_e32 v131, 0xbfb8aa3b, v131
	v_exp_f32_e32 v131, v131
	v_mul_f32_e32 v130, 0xbf1b4598, v130
	v_mul_f32_e32 v130, 0x3fb8aa3b, v130
	v_exp_f32_e32 v130, v130
	v_add_f32_e32 v131, 1.0, v131
	v_div_scale_f32 v132, s[18:19], v131, v131, 1.0
	v_rcp_f32_e32 v136, v132
	s_nop 0
	v_fma_f32 v157, -v132, v136, 1.0
	v_fmac_f32_e32 v136, v157, v136
	v_div_scale_f32 v157, vcc, 1.0, v131, 1.0
	v_mul_f32_e32 v162, v157, v136
	v_fma_f32 v163, -v132, v162, v157
	v_fmac_f32_e32 v162, v163, v136
	v_fma_f32 v132, -v132, v162, v157
	v_div_fmas_f32 v132, v132, v136, v162
	v_div_fixup_f32 v131, v132, v131, 1.0
	v_mul_f32_e32 v131, 0xbf1b4598, v131
	v_mul_f32_e32 v131, 0x3fb8aa3b, v131
	v_exp_f32_e32 v136, v131
	v_add_f32_e32 v131, v103, v137
	v_mul_f32_e32 v131, 0xbfb8aa3b, v131
	v_exp_f32_e32 v131, v131
	s_nop 0
	v_add_f32_e32 v131, 1.0, v131
	v_div_scale_f32 v132, s[18:19], v131, v131, 1.0
	v_rcp_f32_e32 v137, v132
	s_nop 0
	v_fma_f32 v157, -v132, v137, 1.0
	v_fmac_f32_e32 v137, v157, v137
	v_div_scale_f32 v157, vcc, 1.0, v131, 1.0
	v_mul_f32_e32 v162, v157, v137
	v_fma_f32 v163, -v132, v162, v157
	v_fmac_f32_e32 v162, v163, v137
	v_fma_f32 v132, -v132, v162, v157
	v_div_fmas_f32 v132, v132, v137, v162
	v_div_fixup_f32 v131, v132, v131, 1.0
	v_add_f32_e32 v132, v99, v133
	v_mul_f32_e32 v132, 0xbfb8aa3b, v132
	v_exp_f32_e32 v132, v132
	v_mul_f32_e32 v131, 0xbf1b4598, v131
	v_mul_f32_e32 v131, 0x3fb8aa3b, v131
	v_exp_f32_e32 v131, v131
	v_add_f32_e32 v132, 1.0, v132
	v_div_scale_f32 v133, s[18:19], v132, v132, 1.0
	v_rcp_f32_e32 v137, v133
	s_nop 0
	v_fma_f32 v157, -v133, v137, 1.0
	v_fmac_f32_e32 v137, v157, v137
	v_div_scale_f32 v157, vcc, 1.0, v132, 1.0
	v_mul_f32_e32 v162, v157, v137
	v_fma_f32 v163, -v133, v162, v157
	v_fmac_f32_e32 v162, v163, v137
	v_fma_f32 v133, -v133, v162, v157
	v_div_fmas_f32 v133, v133, v137, v162
	v_div_fixup_f32 v132, v133, v132, 1.0
	v_mul_f32_e32 v132, 0xbf1b4598, v132
	v_mul_f32_e32 v132, 0x3fb8aa3b, v132
	v_exp_f32_e32 v137, v132
	v_lshl_add_u64 v[132:133], v[160:161], 0, v[180:181]
	v_lshl_add_u64 v[132:133], v[132:133], 2, s[50:51]
	global_store_dwordx4 v[132:133], v[128:131], off offset:512
	global_store_dwordx4 v[132:133], v[134:137], off offset:528

; __device__ __forceinline__ float sigmoidf_(float x) { return 1.0f / (1.0f + __expf(-x)); }
;     __device__ __forceinline__ void operator()(const f32x4 (&acc)[2][2][4][2], const pg8::Unit& u, int wr, int wc, int fr, int fq) const {
;     ...
;                 if (grp == 0) { const f32x4 b0 = *(const f32x4*)(p0 + c), b1 = *(const f32x4*)(p0 + c + 4);
; #pragma unroll
;                     for (int e = 0; e < 4; ++e) { v0[e] = __expf(-0.6065306597126334f * sigmoidf_(v0[e] + b0[e])); v1[e] = __expf(-0.6065306597126334f * sigmoidf_(v1[e] + b1[e])); }
;                     *(f32x4*)(f0 + off) = v0; *(f32x4*)(f0 + off + 4) = v1;
.LBB0_1021:
	s_waitcnt lgkmcnt(0)
	s_nop 1
	v_mov_b32_e32 v130, v202
	v_mov_b32_e32 v131, v203
	v_mov_b32_e32 v132, v204
	v_mov_b32_e32 v133, v205
	v_mov_b32_e32 v134, v198
	v_mov_b32_e32 v135, v199
	v_mov_b32_e32 v136, v200
	v_mov_b32_e32 v137, v201
	v_add_f32_e32 v128, v84, v134
	v_mul_f32_e32 v128, 0xbfb8aa3b, v128
	v_exp_f32_e32 v128, v128
	s_nop 0
	v_add_f32_e32 v128, 1.0, v128
	v_div_scale_f32 v129, s[18:19], v128, v128, 1.0
	v_rcp_f32_e32 v134, v129
	s_nop 0
	v_fma_f32 v157, -v129, v134, 1.0
	v_fmac_f32_e32 v134, v157, v134
	v_div_scale_f32 v157, vcc, 1.0, v128, 1.0
	v_mul_f32_e32 v162, v157, v134
	v_fma_f32 v163, -v129, v162, v157
	v_fmac_f32_e32 v162, v163, v134
	v_fma_f32 v129, -v129, v162, v157
	v_div_fmas_f32 v129, v129, v134, v162
	v_div_fixup_f32 v128, v129, v128, 1.0
	v_add_f32_e32 v129, v80, v130
	v_mul_f32_e32 v129, 0xbfb8aa3b, v129
	v_exp_f32_e32 v129, v129
	v_mul_f32_e32 v128, 0xbf1b4598, v128
	v_mul_f32_e32 v128, 0x3fb8aa3b, v128
	v_exp_f32_e32 v128, v128
	v_add_f32_e32 v129, 1.0, v129
	v_div_scale_f32 v130, s[18:19], v129, v129, 1.0
	v_rcp_f32_e32 v134, v130
	s_nop 0
	v_fma_f32 v157, -v130, v134, 1.0
	v_fmac_f32_e32 v134, v157, v134
	v_div_scale_f32 v157, vcc, 1.0, v129, 1.0
	v_mul_f32_e32 v162, v157, v134
	v_fma_f32 v163, -v130, v162, v157
	v_fmac_f32_e32 v162, v163, v134
	v_fma_f32 v130, -v130, v162, v157
	v_div_fmas_f32 v130, v130, v134, v162
	v_div_fixup_f32 v129, v130, v129, 1.0
	v_mul_f32_e32 v129, 0xbf1b4598, v129
	v_mul_f32_e32 v129, 0x3fb8aa3b, v129
	v_exp_f32_e32 v134, v129
	v_add_f32_e32 v129, v85, v135
	v_mul_f32_e32 v129, 0xbfb8aa3b, v129
	v_exp_f32_e32 v129, v129
	s_nop 0
	v_add_f32_e32 v129, 1.0, v129
	v_div_scale_f32 v130, s[18:19], v129, v129, 1.0
	v_rcp_f32_e32 v135, v130
	s_nop 0
	v_fma_f32 v157, -v130, v135, 1.0
	v_fmac_f32_e32 v135, v157, v135
	v_div_scale_f32 v157, vcc, 1.0, v129, 1.0
	v_mul_f32_e32 v162, v157, v135
	v_fma_f32 v163, -v130, v162, v157
	v_fmac_f32_e32 v162, v163, v135
	v_fma_f32 v130, -v130, v162, v157
	v_div_fmas_f32 v130, v130, v135, v162
	v_div_fixup_f32 v129, v130, v129, 1.0
	v_add_f32_e32 v130, v81, v131
	v_mul_f32_e32 v130, 0xbfb8aa3b, v130
	v_exp_f32_e32 v130, v130
	v_mul_f32_e32 v129, 0xbf1b4598, v129
	v_mul_f32_e32 v129, 0x3fb8aa3b, v129
	v_exp_f32_e32 v129, v129
	v_add_f32_e32 v130, 1.0, v130
	v_div_scale_f32 v131, s[18:19], v130, v130, 1.0
	v_rcp_f32_e32 v135, v131
	s_nop 0
	v_fma_f32 v157, -v131, v135, 1.0
	v_fmac_f32_e32 v135, v157, v135
	v_div_scale_f32 v157, vcc, 1.0, v130, 1.0
	v_mul_f32_e32 v162, v157, v135
	v_fma_f32 v163, -v131, v162, v157
	v_fmac_f32_e32 v162, v163, v135
	v_fma_f32 v131, -v131, v162, v157
	v_div_fmas_f32 v131, v131, v135, v162
	v_div_fixup_f32 v130, v131, v130, 1.0
	v_mul_f32_e32 v130, 0xbf1b4598, v130
	v_mul_f32_e32 v130, 0x3fb8aa3b, v130
	v_exp_f32_e32 v135, v130
	v_add_f32_e32 v130, v86, v136
	v_mul_f32_e32 v130, 0xbfb8aa3b, v130
	v_exp_f32_e32 v130, v130
	s_nop 0
	v_add_f32_e32 v130, 1.0, v130
	v_div_scale_f32 v131, s[18:19], v130, v130, 1.0
	v_rcp_f32_e32 v136, v131
	s_nop 0
	v_fma_f32 v157, -v131, v136, 1.0
	v_fmac_f32_e32 v136, v157, v136
	v_div_scale_f32 v157, vcc, 1.0, v130, 1.0
	v_mul_f32_e32 v162, v157, v136
	v_fma_f32 v163, -v131, v162, v157
	v_fmac_f32_e32 v162, v163, v136
	v_fma_f32 v131, -v131, v162, v157
	v_div_fmas_f32 v131, v131, v136, v162
	v_div_fixup_f32 v130, v131, v130, 1.0
	v_add_f32_e32 v131, v82, v132
	v_mul_f32_e32 v131, 0xbfb8aa3b, v131
	v_exp_f32_e32 v131, v131
	v_mul_f32_e32 v130, 0xbf1b4598, v130
	v_mul_f32_e32 v130, 0x3fb8aa3b, v130
	v_exp_f32_e32 v130, v130
	v_add_f32_e32 v131, 1.0, v131
	v_div_scale_f32 v132, s[18:19], v131, v131, 1.0
	v_rcp_f32_e32 v136, v132
	s_nop 0
	v_fma_f32 v157, -v132, v136, 1.0
	v_fmac_f32_e32 v136, v157, v136
	v_div_scale_f32 v157, vcc, 1.0, v131, 1.0
	v_mul_f32_e32 v162, v157, v136
	v_fma_f32 v163, -v132, v162, v157
	v_fmac_f32_e32 v162, v163, v136
	v_fma_f32 v132, -v132, v162, v157
	v_div_fmas_f32 v132, v132, v136, v162
	v_div_fixup_f32 v131, v132, v131, 1.0
	v_mul_f32_e32 v131, 0xbf1b4598, v131
	v_mul_f32_e32 v131, 0x3fb8aa3b, v131
	v_exp_f32_e32 v136, v131
	v_add_f32_e32 v131, v87, v137
	v_mul_f32_e32 v131, 0xbfb8aa3b, v131
	v_exp_f32_e32 v131, v131
	s_nop 0
	v_add_f32_e32 v131, 1.0, v131
	v_div_scale_f32 v132, s[18:19], v131, v131, 1.0
	v_rcp_f32_e32 v137, v132
	s_nop 0
	v_fma_f32 v157, -v132, v137, 1.0
	v_fmac_f32_e32 v137, v157, v137
	v_div_scale_f32 v157, vcc, 1.0, v131, 1.0
	v_mul_f32_e32 v162, v157, v137
	v_fma_f32 v163, -v132, v162, v157
	v_fmac_f32_e32 v162, v163, v137
	v_fma_f32 v132, -v132, v162, v157
	v_div_fmas_f32 v132, v132, v137, v162
	v_div_fixup_f32 v131, v132, v131, 1.0
	v_add_f32_e32 v132, v83, v133
	v_mul_f32_e32 v132, 0xbfb8aa3b, v132
	v_exp_f32_e32 v132, v132
	v_mul_f32_e32 v131, 0xbf1b4598, v131
	v_mul_f32_e32 v131, 0x3fb8aa3b, v131
	v_exp_f32_e32 v131, v131
	v_add_f32_e32 v132, 1.0, v132
	v_div_scale_f32 v133, s[18:19], v132, v132, 1.0
	v_rcp_f32_e32 v137, v133
	s_nop 0
	v_fma_f32 v157, -v133, v137, 1.0
	v_fmac_f32_e32 v137, v157, v137
	v_div_scale_f32 v157, vcc, 1.0, v132, 1.0
	v_mul_f32_e32 v162, v157, v137
	v_fma_f32 v163, -v133, v162, v157
	v_fmac_f32_e32 v162, v163, v137
	v_fma_f32 v133, -v133, v162, v157
	v_div_fmas_f32 v133, v133, v137, v162
	v_div_fixup_f32 v132, v133, v132, 1.0
	v_mul_f32_e32 v132, 0xbf1b4598, v132
	v_mul_f32_e32 v132, 0x3fb8aa3b, v132
	v_exp_f32_e32 v137, v132
	v_lshl_add_u64 v[132:133], v[160:161], 0, v[180:181]
	v_lshl_add_u64 v[132:133], v[132:133], 2, s[50:51]
	global_store_dwordx4 v[132:133], v[128:131], off offset:512
	global_store_dwordx4 v[132:133], v[134:137], off offset:528

; __device__ __forceinline__ float sigmoidf_(float x) { return 1.0f / (1.0f + __expf(-x)); }
;     __device__ __forceinline__ void operator()(const f32x4 (&acc)[2][2][4][2], const pg8::Unit& u, int wr, int wc, int fr, int fq) const {
;     ...
;                 if (grp == 0) { const f32x4 b0 = *(const f32x4*)(p0 + c), b1 = *(const f32x4*)(p0 + c + 4);
; #pragma unroll
;                     for (int e = 0; e < 4; ++e) { v0[e] = __expf(-0.6065306597126334f * sigmoidf_(v0[e] + b0[e])); v1[e] = __expf(-0.6065306597126334f * sigmoidf_(v1[e] + b1[e])); }
;                     *(f32x4*)(f0 + off) = v0; *(f32x4*)(f0 + off + 4) = v1;
.LBB0_1026:
	s_waitcnt lgkmcnt(0)
	s_nop 1
	v_mov_b32_e32 v130, v202
	v_mov_b32_e32 v131, v203
	v_mov_b32_e32 v132, v204
	v_mov_b32_e32 v133, v205
	v_mov_b32_e32 v134, v198
	v_mov_b32_e32 v135, v199
	v_mov_b32_e32 v136, v200
	v_mov_b32_e32 v137, v201
	v_add_f32_e32 v128, v68, v134
	v_mul_f32_e32 v128, 0xbfb8aa3b, v128
	v_exp_f32_e32 v128, v128
	s_nop 0
	v_add_f32_e32 v128, 1.0, v128
	v_div_scale_f32 v129, s[18:19], v128, v128, 1.0
	v_rcp_f32_e32 v134, v129
	s_nop 0
	v_fma_f32 v157, -v129, v134, 1.0
	v_fmac_f32_e32 v134, v157, v134
	v_div_scale_f32 v157, vcc, 1.0, v128, 1.0
	v_mul_f32_e32 v162, v157, v134
	v_fma_f32 v163, -v129, v162, v157
	v_fmac_f32_e32 v162, v163, v134
	v_fma_f32 v129, -v129, v162, v157
	v_div_fmas_f32 v129, v129, v134, v162
	v_div_fixup_f32 v128, v129, v128, 1.0
	v_add_f32_e32 v129, v64, v130
	v_mul_f32_e32 v129, 0xbfb8aa3b, v129
	v_exp_f32_e32 v129, v129
	v_mul_f32_e32 v128, 0xbf1b4598, v128
	v_mul_f32_e32 v128, 0x3fb8aa3b, v128
	v_exp_f32_e32 v128, v128
	v_add_f32_e32 v129, 1.0, v129
	v_div_scale_f32 v130, s[18:19], v129, v129, 1.0
	v_rcp_f32_e32 v134, v130
	s_nop 0
	v_fma_f32 v157, -v130, v134, 1.0
	v_fmac_f32_e32 v134, v157, v134
	v_div_scale_f32 v157, vcc, 1.0, v129, 1.0
	v_mul_f32_e32 v162, v157, v134
	v_fma_f32 v163, -v130, v162, v157
	v_fmac_f32_e32 v162, v163, v134
	v_fma_f32 v130, -v130, v162, v157
	v_div_fmas_f32 v130, v130, v134, v162
	v_div_fixup_f32 v129, v130, v129, 1.0
	v_mul_f32_e32 v129, 0xbf1b4598, v129
	v_mul_f32_e32 v129, 0x3fb8aa3b, v129
	v_exp_f32_e32 v134, v129
	v_add_f32_e32 v129, v69, v135
	v_mul_f32_e32 v129, 0xbfb8aa3b, v129
	v_exp_f32_e32 v129, v129
	s_nop 0
	v_add_f32_e32 v129, 1.0, v129
	v_div_scale_f32 v130, s[18:19], v129, v129, 1.0
	v_rcp_f32_e32 v135, v130
	s_nop 0
	v_fma_f32 v157, -v130, v135, 1.0
	v_fmac_f32_e32 v135, v157, v135
	v_div_scale_f32 v157, vcc, 1.0, v129, 1.0
	v_mul_f32_e32 v162, v157, v135
	v_fma_f32 v163, -v130, v162, v157
	v_fmac_f32_e32 v162, v163, v135
	v_fma_f32 v130, -v130, v162, v157
	v_div_fmas_f32 v130, v130, v135, v162
	v_div_fixup_f32 v129, v130, v129, 1.0
	v_add_f32_e32 v130, v65, v131
	v_mul_f32_e32 v130, 0xbfb8aa3b, v130
	v_exp_f32_e32 v130, v130
	v_mul_f32_e32 v129, 0xbf1b4598, v129
	v_mul_f32_e32 v129, 0x3fb8aa3b, v129
	v_exp_f32_e32 v129, v129
	v_add_f32_e32 v130, 1.0, v130
	v_div_scale_f32 v131, s[18:19], v130, v130, 1.0
	v_rcp_f32_e32 v135, v131
	s_nop 0
	v_fma_f32 v157, -v131, v135, 1.0
	v_fmac_f32_e32 v135, v157, v135
	v_div_scale_f32 v157, vcc, 1.0, v130, 1.0
	v_mul_f32_e32 v162, v157, v135
	v_fma_f32 v163, -v131, v162, v157
	v_fmac_f32_e32 v162, v163, v135
	v_fma_f32 v131, -v131, v162, v157
	v_div_fmas_f32 v131, v131, v135, v162
	v_div_fixup_f32 v130, v131, v130, 1.0
	v_mul_f32_e32 v130, 0xbf1b4598, v130
	v_mul_f32_e32 v130, 0x3fb8aa3b, v130
	v_exp_f32_e32 v135, v130
	v_add_f32_e32 v130, v70, v136
	v_mul_f32_e32 v130, 0xbfb8aa3b, v130
	v_exp_f32_e32 v130, v130
	s_nop 0
	v_add_f32_e32 v130, 1.0, v130
	v_div_scale_f32 v131, s[18:19], v130, v130, 1.0
	v_rcp_f32_e32 v136, v131
	s_nop 0
	v_fma_f32 v157, -v131, v136, 1.0
	v_fmac_f32_e32 v136, v157, v136
	v_div_scale_f32 v157, vcc, 1.0, v130, 1.0
	v_mul_f32_e32 v162, v157, v136
	v_fma_f32 v163, -v131, v162, v157
	v_fmac_f32_e32 v162, v163, v136
	v_fma_f32 v131, -v131, v162, v157
	v_div_fmas_f32 v131, v131, v136, v162
	v_div_fixup_f32 v130, v131, v130, 1.0
	v_add_f32_e32 v131, v66, v132
	v_mul_f32_e32 v131, 0xbfb8aa3b, v131
	v_exp_f32_e32 v131, v131
	v_mul_f32_e32 v130, 0xbf1b4598, v130
	v_mul_f32_e32 v130, 0x3fb8aa3b, v130
	v_exp_f32_e32 v130, v130
	v_add_f32_e32 v131, 1.0, v131
	v_div_scale_f32 v132, s[18:19], v131, v131, 1.0
	v_rcp_f32_e32 v136, v132
	s_nop 0
	v_fma_f32 v157, -v132, v136, 1.0
	v_fmac_f32_e32 v136, v157, v136
	v_div_scale_f32 v157, vcc, 1.0, v131, 1.0
	v_mul_f32_e32 v162, v157, v136
	v_fma_f32 v163, -v132, v162, v157
	v_fmac_f32_e32 v162, v163, v136
	v_fma_f32 v132, -v132, v162, v157
	v_div_fmas_f32 v132, v132, v136, v162
	v_div_fixup_f32 v131, v132, v131, 1.0
	v_mul_f32_e32 v131, 0xbf1b4598, v131
	v_mul_f32_e32 v131, 0x3fb8aa3b, v131
	v_exp_f32_e32 v136, v131
	v_add_f32_e32 v131, v71, v137
	v_mul_f32_e32 v131, 0xbfb8aa3b, v131
	v_exp_f32_e32 v131, v131
	s_nop 0
	v_add_f32_e32 v131, 1.0, v131
	v_div_scale_f32 v132, s[18:19], v131, v131, 1.0
	v_rcp_f32_e32 v137, v132
	s_nop 0
	v_fma_f32 v157, -v132, v137, 1.0
	v_fmac_f32_e32 v137, v157, v137
	v_div_scale_f32 v157, vcc, 1.0, v131, 1.0
	v_mul_f32_e32 v162, v157, v137
	v_fma_f32 v163, -v132, v162, v157
	v_fmac_f32_e32 v162, v163, v137
	v_fma_f32 v132, -v132, v162, v157
	v_div_fmas_f32 v132, v132, v137, v162
	v_div_fixup_f32 v131, v132, v131, 1.0
	v_add_f32_e32 v132, v67, v133
	v_mul_f32_e32 v132, 0xbfb8aa3b, v132
	v_exp_f32_e32 v132, v132
	v_mul_f32_e32 v131, 0xbf1b4598, v131
	v_mul_f32_e32 v131, 0x3fb8aa3b, v131
	v_exp_f32_e32 v131, v131
	v_add_f32_e32 v132, 1.0, v132
	v_div_scale_f32 v133, s[18:19], v132, v132, 1.0
	v_rcp_f32_e32 v137, v133
	s_nop 0
	v_fma_f32 v157, -v133, v137, 1.0
	v_fmac_f32_e32 v137, v157, v137
	v_div_scale_f32 v157, vcc, 1.0, v132, 1.0
	v_mul_f32_e32 v162, v157, v137
	v_fma_f32 v163, -v133, v162, v157
	v_fmac_f32_e32 v162, v163, v137
	v_fma_f32 v133, -v133, v162, v157
	v_div_fmas_f32 v133, v133, v137, v162
	v_div_fixup_f32 v132, v133, v132, 1.0
	v_mul_f32_e32 v132, 0xbf1b4598, v132
	v_mul_f32_e32 v132, 0x3fb8aa3b, v132
	v_exp_f32_e32 v137, v132
	v_lshl_add_u64 v[132:133], v[160:161], 0, v[180:181]
	v_lshl_add_u64 v[132:133], v[132:133], 2, s[50:51]
	global_store_dwordx4 v[132:133], v[128:131], off offset:512
	global_store_dwordx4 v[132:133], v[134:137], off offset:528

; __device__ __forceinline__ float sigmoidf_(float x) { return 1.0f / (1.0f + __expf(-x)); }
;     __device__ __forceinline__ void operator()(const f32x4 (&acc)[2][2][4][2], const pg8::Unit& u, int wr, int wc, int fr, int fq) const {
;     ...
;                 if (grp == 0) { const f32x4 b0 = *(const f32x4*)(p0 + c), b1 = *(const f32x4*)(p0 + c + 4);
; #pragma unroll
;                     for (int e = 0; e < 4; ++e) { v0[e] = __expf(-0.6065306597126334f * sigmoidf_(v0[e] + b0[e])); v1[e] = __expf(-0.6065306597126334f * sigmoidf_(v1[e] + b1[e])); }
;                     *(f32x4*)(f0 + off) = v0; *(f32x4*)(f0 + off + 4) = v1;
.LBB0_1031:
	s_waitcnt lgkmcnt(0)
	s_nop 1
	v_mov_b32_e32 v130, v202
	v_mov_b32_e32 v131, v203
	v_mov_b32_e32 v132, v204
	v_mov_b32_e32 v133, v205
	v_mov_b32_e32 v134, v198
	v_mov_b32_e32 v135, v199
	v_mov_b32_e32 v136, v200
	v_mov_b32_e32 v137, v201
	v_add_f32_e32 v128, v52, v134
	v_mul_f32_e32 v128, 0xbfb8aa3b, v128
	v_exp_f32_e32 v128, v128
	s_nop 0
	v_add_f32_e32 v128, 1.0, v128
	v_div_scale_f32 v129, s[18:19], v128, v128, 1.0
	v_rcp_f32_e32 v134, v129
	s_nop 0
	v_fma_f32 v157, -v129, v134, 1.0
	v_fmac_f32_e32 v134, v157, v134
	v_div_scale_f32 v157, vcc, 1.0, v128, 1.0
	v_mul_f32_e32 v162, v157, v134
	v_fma_f32 v163, -v129, v162, v157
	v_fmac_f32_e32 v162, v163, v134
	v_fma_f32 v129, -v129, v162, v157
	v_div_fmas_f32 v129, v129, v134, v162
	v_div_fixup_f32 v128, v129, v128, 1.0
	v_add_f32_e32 v129, v48, v130
	v_mul_f32_e32 v129, 0xbfb8aa3b, v129
	v_exp_f32_e32 v129, v129
	v_mul_f32_e32 v128, 0xbf1b4598, v128
	v_mul_f32_e32 v128, 0x3fb8aa3b, v128
	v_exp_f32_e32 v128, v128
	v_add_f32_e32 v129, 1.0, v129
	v_div_scale_f32 v130, s[18:19], v129, v129, 1.0
	v_rcp_f32_e32 v134, v130
	s_nop 0
	v_fma_f32 v157, -v130, v134, 1.0
	v_fmac_f32_e32 v134, v157, v134
	v_div_scale_f32 v157, vcc, 1.0, v129, 1.0
	v_mul_f32_e32 v162, v157, v134
	v_fma_f32 v163, -v130, v162, v157
	v_fmac_f32_e32 v162, v163, v134
	v_fma_f32 v130, -v130, v162, v157
	v_div_fmas_f32 v130, v130, v134, v162
	v_div_fixup_f32 v129, v130, v129, 1.0
	v_mul_f32_e32 v129, 0xbf1b4598, v129
	v_mul_f32_e32 v129, 0x3fb8aa3b, v129
	v_exp_f32_e32 v134, v129
	v_add_f32_e32 v129, v53, v135
	v_mul_f32_e32 v129, 0xbfb8aa3b, v129
	v_exp_f32_e32 v129, v129
	s_nop 0
	v_add_f32_e32 v129, 1.0, v129
	v_div_scale_f32 v130, s[18:19], v129, v129, 1.0
	v_rcp_f32_e32 v135, v130
	s_nop 0
	v_fma_f32 v157, -v130, v135, 1.0
	v_fmac_f32_e32 v135, v157, v135
	v_div_scale_f32 v157, vcc, 1.0, v129, 1.0
	v_mul_f32_e32 v162, v157, v135
	v_fma_f32 v163, -v130, v162, v157
	v_fmac_f32_e32 v162, v163, v135
	v_fma_f32 v130, -v130, v162, v157
	v_div_fmas_f32 v130, v130, v135, v162
	v_div_fixup_f32 v129, v130, v129, 1.0
	v_add_f32_e32 v130, v49, v131
	v_mul_f32_e32 v130, 0xbfb8aa3b, v130
	v_exp_f32_e32 v130, v130
	v_mul_f32_e32 v129, 0xbf1b4598, v129
	v_mul_f32_e32 v129, 0x3fb8aa3b, v129
	v_exp_f32_e32 v129, v129
	v_add_f32_e32 v130, 1.0, v130
	v_div_scale_f32 v131, s[18:19], v130, v130, 1.0
	v_rcp_f32_e32 v135, v131
	s_nop 0
	v_fma_f32 v157, -v131, v135, 1.0
	v_fmac_f32_e32 v135, v157, v135
	v_div_scale_f32 v157, vcc, 1.0, v130, 1.0
	v_mul_f32_e32 v162, v157, v135
	v_fma_f32 v163, -v131, v162, v157
	v_fmac_f32_e32 v162, v163, v135
	v_fma_f32 v131, -v131, v162, v157
	v_div_fmas_f32 v131, v131, v135, v162
	v_div_fixup_f32 v130, v131, v130, 1.0
	v_mul_f32_e32 v130, 0xbf1b4598, v130
	v_mul_f32_e32 v130, 0x3fb8aa3b, v130
	v_exp_f32_e32 v135, v130
	v_add_f32_e32 v130, v54, v136
	v_mul_f32_e32 v130, 0xbfb8aa3b, v130
	v_exp_f32_e32 v130, v130
	s_nop 0
	v_add_f32_e32 v130, 1.0, v130
	v_div_scale_f32 v131, s[18:19], v130, v130, 1.0
	v_rcp_f32_e32 v136, v131
	s_nop 0
	v_fma_f32 v157, -v131, v136, 1.0
	v_fmac_f32_e32 v136, v157, v136
	v_div_scale_f32 v157, vcc, 1.0, v130, 1.0
	v_mul_f32_e32 v162, v157, v136
	v_fma_f32 v163, -v131, v162, v157
	v_fmac_f32_e32 v162, v163, v136
	v_fma_f32 v131, -v131, v162, v157
	v_div_fmas_f32 v131, v131, v136, v162
	v_div_fixup_f32 v130, v131, v130, 1.0
	v_add_f32_e32 v131, v50, v132
	v_mul_f32_e32 v131, 0xbfb8aa3b, v131
	v_exp_f32_e32 v131, v131
	v_mul_f32_e32 v130, 0xbf1b4598, v130
	v_mul_f32_e32 v130, 0x3fb8aa3b, v130
	v_exp_f32_e32 v130, v130
	v_add_f32_e32 v131, 1.0, v131
	v_div_scale_f32 v132, s[18:19], v131, v131, 1.0
	v_rcp_f32_e32 v136, v132
	s_nop 0
	v_fma_f32 v157, -v132, v136, 1.0
	v_fmac_f32_e32 v136, v157, v136
	v_div_scale_f32 v157, vcc, 1.0, v131, 1.0
	v_mul_f32_e32 v162, v157, v136
	v_fma_f32 v163, -v132, v162, v157
	v_fmac_f32_e32 v162, v163, v136
	v_fma_f32 v132, -v132, v162, v157
	v_div_fmas_f32 v132, v132, v136, v162
	v_div_fixup_f32 v131, v132, v131, 1.0
	v_mul_f32_e32 v131, 0xbf1b4598, v131
	v_mul_f32_e32 v131, 0x3fb8aa3b, v131
	v_exp_f32_e32 v136, v131
	v_add_f32_e32 v131, v55, v137
	v_mul_f32_e32 v131, 0xbfb8aa3b, v131
	v_exp_f32_e32 v131, v131
	s_nop 0
	v_add_f32_e32 v131, 1.0, v131
	v_div_scale_f32 v132, s[18:19], v131, v131, 1.0
	v_rcp_f32_e32 v137, v132
	s_nop 0
	v_fma_f32 v157, -v132, v137, 1.0
	v_fmac_f32_e32 v137, v157, v137
	v_div_scale_f32 v157, vcc, 1.0, v131, 1.0
	v_mul_f32_e32 v162, v157, v137
	v_fma_f32 v163, -v132, v162, v157
	v_fmac_f32_e32 v162, v163, v137
	v_fma_f32 v132, -v132, v162, v157
	v_div_fmas_f32 v132, v132, v137, v162
	v_div_fixup_f32 v131, v132, v131, 1.0
	v_add_f32_e32 v132, v51, v133
	v_mul_f32_e32 v132, 0xbfb8aa3b, v132
	v_exp_f32_e32 v132, v132
	v_mul_f32_e32 v131, 0xbf1b4598, v131
	v_mul_f32_e32 v131, 0x3fb8aa3b, v131
	v_exp_f32_e32 v131, v131
	v_add_f32_e32 v132, 1.0, v132
	v_div_scale_f32 v133, s[18:19], v132, v132, 1.0
	v_rcp_f32_e32 v137, v133
	s_nop 0
	v_fma_f32 v157, -v133, v137, 1.0
	v_fmac_f32_e32 v137, v157, v137
	v_div_scale_f32 v157, vcc, 1.0, v132, 1.0
	v_mul_f32_e32 v162, v157, v137
	v_fma_f32 v163, -v133, v162, v157
	v_fmac_f32_e32 v162, v163, v137
	v_fma_f32 v133, -v133, v162, v157
	v_div_fmas_f32 v133, v133, v137, v162
	v_div_fixup_f32 v132, v133, v132, 1.0
	v_mul_f32_e32 v132, 0xbf1b4598, v132
	v_mul_f32_e32 v132, 0x3fb8aa3b, v132
	v_exp_f32_e32 v137, v132
	v_lshl_add_u64 v[132:133], v[160:161], 0, v[180:181]
	v_lshl_add_u64 v[132:133], v[132:133], 2, s[50:51]
	global_store_dwordx4 v[132:133], v[128:131], off offset:512
	global_store_dwordx4 v[132:133], v[134:137], off offset:528

; __device__ __forceinline__ float sigmoidf_(float x) { return 1.0f / (1.0f + __expf(-x)); }
;     __device__ __forceinline__ void operator()(const f32x4 (&acc)[2][2][4][2], const pg8::Unit& u, int wr, int wc, int fr, int fq) const {
;     ...
;                 if (grp == 0) { const f32x4 b0 = *(const f32x4*)(p0 + c), b1 = *(const f32x4*)(p0 + c + 4);
; #pragma unroll
;                     for (int e = 0; e < 4; ++e) { v0[e] = __expf(-0.6065306597126334f * sigmoidf_(v0[e] + b0[e])); v1[e] = __expf(-0.6065306597126334f * sigmoidf_(v1[e] + b1[e])); }
;                     *(f32x4*)(f0 + off) = v0; *(f32x4*)(f0 + off + 4) = v1;
.LBB0_1036:
	s_waitcnt lgkmcnt(0)
	s_nop 1
	v_mov_b32_e32 v130, v202
	v_mov_b32_e32 v131, v203
	v_mov_b32_e32 v132, v204
	v_mov_b32_e32 v133, v205
	v_mov_b32_e32 v134, v198
	v_mov_b32_e32 v135, v199
	v_mov_b32_e32 v136, v200
	v_mov_b32_e32 v137, v201
	v_add_f32_e32 v128, v36, v134
	v_mul_f32_e32 v128, 0xbfb8aa3b, v128
	v_exp_f32_e32 v128, v128
	s_nop 0
	v_add_f32_e32 v128, 1.0, v128
	v_div_scale_f32 v129, s[18:19], v128, v128, 1.0
	v_rcp_f32_e32 v134, v129
	s_nop 0
	v_fma_f32 v157, -v129, v134, 1.0
	v_fmac_f32_e32 v134, v157, v134
	v_div_scale_f32 v157, vcc, 1.0, v128, 1.0
	v_mul_f32_e32 v162, v157, v134
	v_fma_f32 v163, -v129, v162, v157
	v_fmac_f32_e32 v162, v163, v134
	v_fma_f32 v129, -v129, v162, v157
	v_div_fmas_f32 v129, v129, v134, v162
	v_div_fixup_f32 v128, v129, v128, 1.0
	v_add_f32_e32 v129, v32, v130
	v_mul_f32_e32 v129, 0xbfb8aa3b, v129
	v_exp_f32_e32 v129, v129
	v_mul_f32_e32 v128, 0xbf1b4598, v128
	v_mul_f32_e32 v128, 0x3fb8aa3b, v128
	v_exp_f32_e32 v128, v128
	v_add_f32_e32 v129, 1.0, v129
	v_div_scale_f32 v130, s[18:19], v129, v129, 1.0
	v_rcp_f32_e32 v134, v130
	s_nop 0
	v_fma_f32 v157, -v130, v134, 1.0
	v_fmac_f32_e32 v134, v157, v134
	v_div_scale_f32 v157, vcc, 1.0, v129, 1.0
	v_mul_f32_e32 v162, v157, v134
	v_fma_f32 v163, -v130, v162, v157
	v_fmac_f32_e32 v162, v163, v134
	v_fma_f32 v130, -v130, v162, v157
	v_div_fmas_f32 v130, v130, v134, v162
	v_div_fixup_f32 v129, v130, v129, 1.0
	v_mul_f32_e32 v129, 0xbf1b4598, v129
	v_mul_f32_e32 v129, 0x3fb8aa3b, v129
	v_exp_f32_e32 v134, v129
	v_add_f32_e32 v129, v37, v135
	v_mul_f32_e32 v129, 0xbfb8aa3b, v129
	v_exp_f32_e32 v129, v129
	s_nop 0
	v_add_f32_e32 v129, 1.0, v129
	v_div_scale_f32 v130, s[18:19], v129, v129, 1.0
	v_rcp_f32_e32 v135, v130
	s_nop 0
	v_fma_f32 v157, -v130, v135, 1.0
	v_fmac_f32_e32 v135, v157, v135
	v_div_scale_f32 v157, vcc, 1.0, v129, 1.0
	v_mul_f32_e32 v162, v157, v135
	v_fma_f32 v163, -v130, v162, v157
	v_fmac_f32_e32 v162, v163, v135
	v_fma_f32 v130, -v130, v162, v157
	v_div_fmas_f32 v130, v130, v135, v162
	v_div_fixup_f32 v129, v130, v129, 1.0
	v_add_f32_e32 v130, v33, v131
	v_mul_f32_e32 v130, 0xbfb8aa3b, v130
	v_exp_f32_e32 v130, v130
	v_mul_f32_e32 v129, 0xbf1b4598, v129
	v_mul_f32_e32 v129, 0x3fb8aa3b, v129
	v_exp_f32_e32 v129, v129
	v_add_f32_e32 v130, 1.0, v130
	v_div_scale_f32 v131, s[18:19], v130, v130, 1.0
	v_rcp_f32_e32 v135, v131
	s_nop 0
	v_fma_f32 v157, -v131, v135, 1.0
	v_fmac_f32_e32 v135, v157, v135
	v_div_scale_f32 v157, vcc, 1.0, v130, 1.0
	v_mul_f32_e32 v162, v157, v135
	v_fma_f32 v163, -v131, v162, v157
	v_fmac_f32_e32 v162, v163, v135
	v_fma_f32 v131, -v131, v162, v157
	v_div_fmas_f32 v131, v131, v135, v162
	v_div_fixup_f32 v130, v131, v130, 1.0
	v_mul_f32_e32 v130, 0xbf1b4598, v130
	v_mul_f32_e32 v130, 0x3fb8aa3b, v130
	v_exp_f32_e32 v135, v130
	v_add_f32_e32 v130, v38, v136
	v_mul_f32_e32 v130, 0xbfb8aa3b, v130
	v_exp_f32_e32 v130, v130
	s_nop 0
	v_add_f32_e32 v130, 1.0, v130
	v_div_scale_f32 v131, s[18:19], v130, v130, 1.0
	v_rcp_f32_e32 v136, v131
	s_nop 0
	v_fma_f32 v157, -v131, v136, 1.0
	v_fmac_f32_e32 v136, v157, v136
	v_div_scale_f32 v157, vcc, 1.0, v130, 1.0
	v_mul_f32_e32 v162, v157, v136
	v_fma_f32 v163, -v131, v162, v157
	v_fmac_f32_e32 v162, v163, v136
	v_fma_f32 v131, -v131, v162, v157
	v_div_fmas_f32 v131, v131, v136, v162
	v_div_fixup_f32 v130, v131, v130, 1.0
	v_add_f32_e32 v131, v34, v132
	v_mul_f32_e32 v131, 0xbfb8aa3b, v131
	v_exp_f32_e32 v131, v131
	v_mul_f32_e32 v130, 0xbf1b4598, v130
	v_mul_f32_e32 v130, 0x3fb8aa3b, v130
	v_exp_f32_e32 v130, v130
	v_add_f32_e32 v131, 1.0, v131
	v_div_scale_f32 v132, s[18:19], v131, v131, 1.0
	v_rcp_f32_e32 v136, v132
	s_nop 0
	v_fma_f32 v157, -v132, v136, 1.0
	v_fmac_f32_e32 v136, v157, v136
	v_div_scale_f32 v157, vcc, 1.0, v131, 1.0
	v_mul_f32_e32 v162, v157, v136
	v_fma_f32 v163, -v132, v162, v157
	v_fmac_f32_e32 v162, v163, v136
	v_fma_f32 v132, -v132, v162, v157
	v_div_fmas_f32 v132, v132, v136, v162
	v_div_fixup_f32 v131, v132, v131, 1.0
	v_mul_f32_e32 v131, 0xbf1b4598, v131
	v_mul_f32_e32 v131, 0x3fb8aa3b, v131
	v_exp_f32_e32 v136, v131
	v_add_f32_e32 v131, v39, v137
	v_mul_f32_e32 v131, 0xbfb8aa3b, v131
	v_exp_f32_e32 v131, v131
	s_nop 0
	v_add_f32_e32 v131, 1.0, v131
	v_div_scale_f32 v132, s[18:19], v131, v131, 1.0
	v_rcp_f32_e32 v137, v132
	s_nop 0
	v_fma_f32 v157, -v132, v137, 1.0
	v_fmac_f32_e32 v137, v157, v137
	v_div_scale_f32 v157, vcc, 1.0, v131, 1.0
	v_mul_f32_e32 v162, v157, v137
	v_fma_f32 v163, -v132, v162, v157
	v_fmac_f32_e32 v162, v163, v137
	v_fma_f32 v132, -v132, v162, v157
	v_div_fmas_f32 v132, v132, v137, v162
	v_div_fixup_f32 v131, v132, v131, 1.0
	v_add_f32_e32 v132, v35, v133
	v_mul_f32_e32 v132, 0xbfb8aa3b, v132
	v_exp_f32_e32 v132, v132
	v_mul_f32_e32 v131, 0xbf1b4598, v131
	v_mul_f32_e32 v131, 0x3fb8aa3b, v131
	v_exp_f32_e32 v131, v131
	v_add_f32_e32 v132, 1.0, v132
	v_div_scale_f32 v133, s[18:19], v132, v132, 1.0
	v_rcp_f32_e32 v137, v133
	s_nop 0
	v_fma_f32 v157, -v133, v137, 1.0
	v_fmac_f32_e32 v137, v157, v137
	v_div_scale_f32 v157, vcc, 1.0, v132, 1.0
	v_mul_f32_e32 v162, v157, v137
	v_fma_f32 v163, -v133, v162, v157
	v_fmac_f32_e32 v162, v163, v137
	v_fma_f32 v133, -v133, v162, v157
	v_div_fmas_f32 v133, v133, v137, v162
	v_div_fixup_f32 v132, v133, v132, 1.0
	v_mul_f32_e32 v132, 0xbf1b4598, v132
	v_mul_f32_e32 v132, 0x3fb8aa3b, v132
	v_exp_f32_e32 v137, v132
	v_lshl_add_u64 v[132:133], v[160:161], 0, v[180:181]
	v_lshl_add_u64 v[132:133], v[132:133], 2, s[50:51]
	global_store_dwordx4 v[132:133], v[128:131], off offset:512
	global_store_dwordx4 v[132:133], v[134:137], off offset:528

; __device__ __forceinline__ float sigmoidf_(float x) { return 1.0f / (1.0f + __expf(-x)); }
;     __device__ __forceinline__ void operator()(const f32x4 (&acc)[2][2][4][2], const pg8::Unit& u, int wr, int wc, int fr, int fq) const {
;     ...
;             EPI_BEGIN { const int c = col & 2047; const size_t off = (size_t)row * 2048 + c;
;                 if (grp == 0) { const f32x4 b0 = *(const f32x4*)(p0 + c), b1 = *(const f32x4*)(p0 + c + 4);
; #pragma unroll
;                     for (int e = 0; e < 4; ++e) { v0[e] = __expf(-0.6065306597126334f * sigmoidf_(v0[e] + b0[e])); v1[e] = __expf(-0.6065306597126334f * sigmoidf_(v1[e] + b1[e])); }
;                     *(f32x4*)(f0 + off) = v0; *(f32x4*)(f0 + off + 4) = v1;
.LBB0_1041:
	s_waitcnt lgkmcnt(0)
	s_nop 1
	v_mov_b32_e32 v130, v202
	v_mov_b32_e32 v131, v203
	v_mov_b32_e32 v132, v204
	v_mov_b32_e32 v133, v205
	v_mov_b32_e32 v134, v198
	v_mov_b32_e32 v135, v199
	v_mov_b32_e32 v136, v200
	v_mov_b32_e32 v137, v201
	v_add_f32_e32 v128, v20, v134
	v_mul_f32_e32 v128, 0xbfb8aa3b, v128
	v_exp_f32_e32 v128, v128
	s_nop 0
	v_add_f32_e32 v128, 1.0, v128
	v_div_scale_f32 v129, s[18:19], v128, v128, 1.0
	v_rcp_f32_e32 v134, v129
	s_nop 0
	v_fma_f32 v157, -v129, v134, 1.0
	v_fmac_f32_e32 v134, v157, v134
	v_div_scale_f32 v157, vcc, 1.0, v128, 1.0
	v_mul_f32_e32 v162, v157, v134
	v_fma_f32 v163, -v129, v162, v157
	v_fmac_f32_e32 v162, v163, v134
	v_fma_f32 v129, -v129, v162, v157
	v_div_fmas_f32 v129, v129, v134, v162
	v_div_fixup_f32 v128, v129, v128, 1.0
	v_add_f32_e32 v129, v16, v130
	v_mul_f32_e32 v129, 0xbfb8aa3b, v129
	v_exp_f32_e32 v129, v129
	v_mul_f32_e32 v128, 0xbf1b4598, v128
	v_mul_f32_e32 v128, 0x3fb8aa3b, v128
	v_exp_f32_e32 v128, v128
	v_add_f32_e32 v129, 1.0, v129
	v_div_scale_f32 v130, s[18:19], v129, v129, 1.0
	v_rcp_f32_e32 v134, v130
	s_nop 0
	v_fma_f32 v157, -v130, v134, 1.0
	v_fmac_f32_e32 v134, v157, v134
	v_div_scale_f32 v157, vcc, 1.0, v129, 1.0
	v_mul_f32_e32 v162, v157, v134
	v_fma_f32 v163, -v130, v162, v157
	v_fmac_f32_e32 v162, v163, v134
	v_fma_f32 v130, -v130, v162, v157
	v_div_fmas_f32 v130, v130, v134, v162
	v_div_fixup_f32 v129, v130, v129, 1.0
	v_mul_f32_e32 v129, 0xbf1b4598, v129
	v_mul_f32_e32 v129, 0x3fb8aa3b, v129
	v_exp_f32_e32 v134, v129
	v_add_f32_e32 v129, v21, v135
	v_mul_f32_e32 v129, 0xbfb8aa3b, v129
	v_exp_f32_e32 v129, v129
	s_nop 0
	v_add_f32_e32 v129, 1.0, v129
	v_div_scale_f32 v130, s[18:19], v129, v129, 1.0
	v_rcp_f32_e32 v135, v130
	s_nop 0
	v_fma_f32 v157, -v130, v135, 1.0
	v_fmac_f32_e32 v135, v157, v135
	v_div_scale_f32 v157, vcc, 1.0, v129, 1.0
	v_mul_f32_e32 v162, v157, v135
	v_fma_f32 v163, -v130, v162, v157
	v_fmac_f32_e32 v162, v163, v135
	v_fma_f32 v130, -v130, v162, v157
	v_div_fmas_f32 v130, v130, v135, v162
	v_div_fixup_f32 v129, v130, v129, 1.0
	v_add_f32_e32 v130, v17, v131
	v_mul_f32_e32 v130, 0xbfb8aa3b, v130
	v_exp_f32_e32 v130, v130
	v_mul_f32_e32 v129, 0xbf1b4598, v129
	v_mul_f32_e32 v129, 0x3fb8aa3b, v129
	v_exp_f32_e32 v129, v129
	v_add_f32_e32 v130, 1.0, v130
	v_div_scale_f32 v131, s[18:19], v130, v130, 1.0
	v_rcp_f32_e32 v135, v131
	s_nop 0
	v_fma_f32 v157, -v131, v135, 1.0
	v_fmac_f32_e32 v135, v157, v135
	v_div_scale_f32 v157, vcc, 1.0, v130, 1.0
	v_mul_f32_e32 v162, v157, v135
	v_fma_f32 v163, -v131, v162, v157
	v_fmac_f32_e32 v162, v163, v135
	v_fma_f32 v131, -v131, v162, v157
	v_div_fmas_f32 v131, v131, v135, v162
	v_div_fixup_f32 v130, v131, v130, 1.0
	v_mul_f32_e32 v130, 0xbf1b4598, v130
	v_mul_f32_e32 v130, 0x3fb8aa3b, v130
	v_exp_f32_e32 v135, v130
	v_add_f32_e32 v130, v22, v136
	v_mul_f32_e32 v130, 0xbfb8aa3b, v130
	v_exp_f32_e32 v130, v130
	s_nop 0
	v_add_f32_e32 v130, 1.0, v130
	v_div_scale_f32 v131, s[18:19], v130, v130, 1.0
	v_rcp_f32_e32 v136, v131
	s_nop 0
	v_fma_f32 v157, -v131, v136, 1.0
	v_fmac_f32_e32 v136, v157, v136
	v_div_scale_f32 v157, vcc, 1.0, v130, 1.0
	v_mul_f32_e32 v162, v157, v136
	v_fma_f32 v163, -v131, v162, v157
	v_fmac_f32_e32 v162, v163, v136
	v_fma_f32 v131, -v131, v162, v157
	v_div_fmas_f32 v131, v131, v136, v162
	v_div_fixup_f32 v130, v131, v130, 1.0
	v_add_f32_e32 v131, v18, v132
	v_mul_f32_e32 v131, 0xbfb8aa3b, v131
	v_exp_f32_e32 v131, v131
	v_mul_f32_e32 v130, 0xbf1b4598, v130
	v_mul_f32_e32 v130, 0x3fb8aa3b, v130
	v_exp_f32_e32 v130, v130
	v_add_f32_e32 v131, 1.0, v131
	v_div_scale_f32 v132, s[18:19], v131, v131, 1.0
	v_rcp_f32_e32 v136, v132
	s_nop 0
	v_fma_f32 v157, -v132, v136, 1.0
	v_fmac_f32_e32 v136, v157, v136
	v_div_scale_f32 v157, vcc, 1.0, v131, 1.0
	v_mul_f32_e32 v162, v157, v136
	v_fma_f32 v163, -v132, v162, v157
	v_fmac_f32_e32 v162, v163, v136
	v_fma_f32 v132, -v132, v162, v157
	v_div_fmas_f32 v132, v132, v136, v162
	v_div_fixup_f32 v131, v132, v131, 1.0
	v_mul_f32_e32 v131, 0xbf1b4598, v131
	v_mul_f32_e32 v131, 0x3fb8aa3b, v131
	v_exp_f32_e32 v136, v131
	v_add_f32_e32 v131, v23, v137
	v_mul_f32_e32 v131, 0xbfb8aa3b, v131
	v_exp_f32_e32 v131, v131
	s_nop 0
	v_add_f32_e32 v131, 1.0, v131
	v_div_scale_f32 v132, s[18:19], v131, v131, 1.0
	v_rcp_f32_e32 v137, v132
	s_nop 0
	v_fma_f32 v157, -v132, v137, 1.0
	v_fmac_f32_e32 v137, v157, v137
	v_div_scale_f32 v157, vcc, 1.0, v131, 1.0
	v_mul_f32_e32 v162, v157, v137
	v_fma_f32 v163, -v132, v162, v157
	v_fmac_f32_e32 v162, v163, v137
	v_fma_f32 v132, -v132, v162, v157
	v_div_fmas_f32 v132, v132, v137, v162
	v_div_fixup_f32 v131, v132, v131, 1.0
	v_add_f32_e32 v132, v19, v133
	v_mul_f32_e32 v132, 0xbfb8aa3b, v132
	v_exp_f32_e32 v132, v132
	v_mul_f32_e32 v131, 0xbf1b4598, v131
	v_mul_f32_e32 v131, 0x3fb8aa3b, v131
	v_exp_f32_e32 v131, v131
	v_add_f32_e32 v132, 1.0, v132
	v_div_scale_f32 v133, s[18:19], v132, v132, 1.0
	v_rcp_f32_e32 v137, v133
	s_nop 0
	v_fma_f32 v157, -v133, v137, 1.0
	v_fmac_f32_e32 v137, v157, v137
	v_div_scale_f32 v157, vcc, 1.0, v132, 1.0
	v_mul_f32_e32 v162, v157, v137
	v_fma_f32 v163, -v133, v162, v157
	v_fmac_f32_e32 v162, v163, v137
	v_fma_f32 v133, -v133, v162, v157
	v_div_fmas_f32 v133, v133, v137, v162
	v_div_fixup_f32 v132, v133, v132, 1.0
	v_mul_f32_e32 v132, 0xbf1b4598, v132
	v_mul_f32_e32 v132, 0x3fb8aa3b, v132
	v_exp_f32_e32 v137, v132
	v_lshl_add_u64 v[132:133], v[160:161], 0, v[180:181]
	v_lshl_add_u64 v[132:133], v[132:133], 2, s[50:51]
	global_store_dwordx4 v[132:133], v[128:131], off offset:512
	global_store_dwordx4 v[132:133], v[134:137], off offset:528

; __device__ __forceinline__ float sigmoidf_(float x) { return 1.0f / (1.0f + __expf(-x)); }
;     __device__ __forceinline__ void operator()(const f32x4 (&acc)[2][2][4][2], const pg8::Unit& u, int wr, int wc, int fr, int fq) const {
;     ...
;             EPI_BEGIN { const int c = col & 2047; const size_t off = (size_t)row * 2048 + c;
;                 if (grp == 0) { const f32x4 b0 = *(const f32x4*)(p0 + c), b1 = *(const f32x4*)(p0 + c + 4);
; #pragma unroll
;                     for (int e = 0; e < 4; ++e) { v0[e] = __expf(-0.6065306597126334f * sigmoidf_(v0[e] + b0[e])); v1[e] = __expf(-0.6065306597126334f * sigmoidf_(v1[e] + b1[e])); }
;                     *(f32x4*)(f0 + off) = v0; *(f32x4*)(f0 + off + 4) = v1;
.LBB0_1046:
	s_waitcnt lgkmcnt(0)
	s_nop 1
	v_mov_b32_e32 v130, v202
	v_mov_b32_e32 v131, v203
	v_mov_b32_e32 v132, v204
	v_mov_b32_e32 v133, v205
	v_mov_b32_e32 v134, v198
	v_mov_b32_e32 v135, v199
	v_mov_b32_e32 v136, v200
	v_mov_b32_e32 v137, v201
	v_add_f32_e32 v128, v4, v134
	v_mul_f32_e32 v128, 0xbfb8aa3b, v128
	v_exp_f32_e32 v128, v128
	s_nop 0
	v_add_f32_e32 v128, 1.0, v128
	v_div_scale_f32 v129, s[18:19], v128, v128, 1.0
	v_rcp_f32_e32 v134, v129
	s_nop 0
	v_fma_f32 v155, -v129, v134, 1.0
	v_fmac_f32_e32 v134, v155, v134
	v_div_scale_f32 v155, vcc, 1.0, v128, 1.0
	v_mul_f32_e32 v157, v155, v134
	v_fma_f32 v159, -v129, v157, v155
	v_fmac_f32_e32 v157, v159, v134
	v_fma_f32 v129, -v129, v157, v155
	v_div_fmas_f32 v129, v129, v134, v157
	v_div_fixup_f32 v128, v129, v128, 1.0
	v_add_f32_e32 v129, v0, v130
	v_mul_f32_e32 v129, 0xbfb8aa3b, v129
	v_exp_f32_e32 v129, v129
	v_mul_f32_e32 v128, 0xbf1b4598, v128
	v_mul_f32_e32 v128, 0x3fb8aa3b, v128
	v_exp_f32_e32 v128, v128
	v_add_f32_e32 v129, 1.0, v129
	v_div_scale_f32 v130, s[18:19], v129, v129, 1.0
	v_rcp_f32_e32 v134, v130
	s_nop 0
	v_fma_f32 v155, -v130, v134, 1.0
	v_fmac_f32_e32 v134, v155, v134
	v_div_scale_f32 v155, vcc, 1.0, v129, 1.0
	v_mul_f32_e32 v157, v155, v134
	v_fma_f32 v159, -v130, v157, v155
	v_fmac_f32_e32 v157, v159, v134
	v_fma_f32 v130, -v130, v157, v155
	v_div_fmas_f32 v130, v130, v134, v157
	v_div_fixup_f32 v129, v130, v129, 1.0
	v_mul_f32_e32 v129, 0xbf1b4598, v129
	v_mul_f32_e32 v129, 0x3fb8aa3b, v129
	v_exp_f32_e32 v134, v129
	v_add_f32_e32 v129, v5, v135
	v_mul_f32_e32 v129, 0xbfb8aa3b, v129
	v_exp_f32_e32 v129, v129
	s_nop 0
	v_add_f32_e32 v129, 1.0, v129
	v_div_scale_f32 v130, s[18:19], v129, v129, 1.0
	v_rcp_f32_e32 v135, v130
	s_nop 0
	v_fma_f32 v155, -v130, v135, 1.0
	v_fmac_f32_e32 v135, v155, v135
	v_div_scale_f32 v155, vcc, 1.0, v129, 1.0
	v_mul_f32_e32 v157, v155, v135
	v_fma_f32 v159, -v130, v157, v155
	v_fmac_f32_e32 v157, v159, v135
	v_fma_f32 v130, -v130, v157, v155
	v_div_fmas_f32 v130, v130, v135, v157
	v_div_fixup_f32 v129, v130, v129, 1.0
	v_add_f32_e32 v130, v1, v131
	v_mul_f32_e32 v130, 0xbfb8aa3b, v130
	v_exp_f32_e32 v130, v130
	v_mul_f32_e32 v129, 0xbf1b4598, v129
	v_mul_f32_e32 v129, 0x3fb8aa3b, v129
	v_exp_f32_e32 v129, v129
	v_add_f32_e32 v130, 1.0, v130
	v_div_scale_f32 v131, s[18:19], v130, v130, 1.0
	v_rcp_f32_e32 v135, v131
	s_nop 0
	v_fma_f32 v155, -v131, v135, 1.0
	v_fmac_f32_e32 v135, v155, v135
	v_div_scale_f32 v155, vcc, 1.0, v130, 1.0
	v_mul_f32_e32 v157, v155, v135
	v_fma_f32 v159, -v131, v157, v155
	v_fmac_f32_e32 v157, v159, v135
	v_fma_f32 v131, -v131, v157, v155
	v_div_fmas_f32 v131, v131, v135, v157
	v_div_fixup_f32 v130, v131, v130, 1.0
	v_mul_f32_e32 v130, 0xbf1b4598, v130
	v_mul_f32_e32 v130, 0x3fb8aa3b, v130
	v_exp_f32_e32 v135, v130
	v_add_f32_e32 v130, v6, v136
	v_mul_f32_e32 v130, 0xbfb8aa3b, v130
	v_exp_f32_e32 v130, v130
	s_nop 0
	v_add_f32_e32 v130, 1.0, v130
	v_div_scale_f32 v131, s[18:19], v130, v130, 1.0
	v_rcp_f32_e32 v136, v131
	s_nop 0
	v_fma_f32 v155, -v131, v136, 1.0
	v_fmac_f32_e32 v136, v155, v136
	v_div_scale_f32 v155, vcc, 1.0, v130, 1.0
	v_mul_f32_e32 v157, v155, v136
	v_fma_f32 v159, -v131, v157, v155
	v_fmac_f32_e32 v157, v159, v136
	v_fma_f32 v131, -v131, v157, v155
	v_div_fmas_f32 v131, v131, v136, v157
	v_div_fixup_f32 v130, v131, v130, 1.0
	v_add_f32_e32 v131, v2, v132
	v_mul_f32_e32 v131, 0xbfb8aa3b, v131
	v_exp_f32_e32 v131, v131
	v_mul_f32_e32 v130, 0xbf1b4598, v130
	v_mul_f32_e32 v130, 0x3fb8aa3b, v130
	v_exp_f32_e32 v130, v130
	v_add_f32_e32 v131, 1.0, v131
	v_div_scale_f32 v132, s[18:19], v131, v131, 1.0
	v_rcp_f32_e32 v136, v132
	s_nop 0
	v_fma_f32 v155, -v132, v136, 1.0
	v_fmac_f32_e32 v136, v155, v136
	v_div_scale_f32 v155, vcc, 1.0, v131, 1.0
	v_mul_f32_e32 v157, v155, v136
	v_fma_f32 v159, -v132, v157, v155
	v_fmac_f32_e32 v157, v159, v136
	v_fma_f32 v132, -v132, v157, v155
	v_div_fmas_f32 v132, v132, v136, v157
	v_div_fixup_f32 v131, v132, v131, 1.0
	v_mul_f32_e32 v131, 0xbf1b4598, v131
	v_mul_f32_e32 v131, 0x3fb8aa3b, v131
	v_exp_f32_e32 v136, v131
	v_add_f32_e32 v131, v7, v137
	v_mul_f32_e32 v131, 0xbfb8aa3b, v131
	v_exp_f32_e32 v131, v131
	s_nop 0
	v_add_f32_e32 v131, 1.0, v131
	v_div_scale_f32 v132, s[18:19], v131, v131, 1.0
	v_rcp_f32_e32 v137, v132
	s_nop 0
	v_fma_f32 v155, -v132, v137, 1.0
	v_fmac_f32_e32 v137, v155, v137
	v_div_scale_f32 v155, vcc, 1.0, v131, 1.0
	v_mul_f32_e32 v157, v155, v137
	v_fma_f32 v159, -v132, v157, v155
	v_fmac_f32_e32 v157, v159, v137
	v_fma_f32 v132, -v132, v157, v155
	v_div_fmas_f32 v132, v132, v137, v157
	v_div_fixup_f32 v131, v132, v131, 1.0
	v_add_f32_e32 v132, v3, v133
	v_mul_f32_e32 v132, 0xbfb8aa3b, v132
	v_exp_f32_e32 v132, v132
	v_mul_f32_e32 v131, 0xbf1b4598, v131
	v_mul_f32_e32 v131, 0x3fb8aa3b, v131
	v_exp_f32_e32 v131, v131
	v_add_f32_e32 v132, 1.0, v132
	v_div_scale_f32 v133, s[18:19], v132, v132, 1.0
	v_rcp_f32_e32 v137, v133
	s_nop 0
	v_fma_f32 v155, -v133, v137, 1.0
	v_fmac_f32_e32 v137, v155, v137
	v_div_scale_f32 v155, vcc, 1.0, v132, 1.0
	v_mul_f32_e32 v157, v155, v137
	v_fma_f32 v159, -v133, v157, v155
	v_fmac_f32_e32 v157, v159, v137
	v_fma_f32 v133, -v133, v157, v155
	v_div_fmas_f32 v133, v133, v137, v157
	v_div_fixup_f32 v132, v133, v132, 1.0
	v_mul_f32_e32 v132, 0xbf1b4598, v132
	v_mul_f32_e32 v132, 0x3fb8aa3b, v132
	v_exp_f32_e32 v137, v132
	v_lshl_add_u64 v[132:133], v[160:161], 0, v[180:181]
	v_lshl_add_u64 v[132:133], v[132:133], 2, s[50:51]
	global_store_dwordx4 v[132:133], v[128:131], off offset:512
	global_store_dwordx4 v[132:133], v[134:137], off offset:528

; __device__ __forceinline__ float sigmoidf_(float x) { return 1.0f / (1.0f + __expf(-x)); }
;     __device__ __forceinline__ void operator()(const f32x4 (&acc)[2][2][4][2], const pg8::Unit& u, int wr, int wc, int fr, int fq) const {
;     ...
;                 } else if (grp == 1) { const f32x4 b0 = *(const f32x4*)(p1 + c), b1 = *(const f32x4*)(p1 + c + 4);
; #pragma unroll
;                     for (int e = 0; e < 4; ++e) { v0[e] = sigmoidf_(v0[e] + b0[e]); v1[e] = sigmoidf_(v1[e] + b1[e]); }
;                     *(f32x4*)(f1 + off) = v0; *(f32x4*)(f1 + off + 4) = v1;
.LBB0_1242:
	s_andn2_b64 vcc, exec, s[18:19]
	s_cbranch_vccnz .LBB0_1244
	s_waitcnt lgkmcnt(0)
	s_nop 1
	v_mov_b32_e32 v130, v228
	v_mov_b32_e32 v131, v229
	v_mov_b32_e32 v132, v230
	v_mov_b32_e32 v133, v231
	v_mov_b32_e32 v134, v224
	v_mov_b32_e32 v135, v225
	v_mov_b32_e32 v136, v226
	v_mov_b32_e32 v137, v227
	v_add_f32_e32 v129, v104, v130
	v_add_f32_e32 v130, v105, v131
	v_add_f32_e32 v131, v106, v132
	v_mul_f32_e32 v129, 0xbfb8aa3b, v129
	v_mul_f32_e32 v130, 0xbfb8aa3b, v130
	v_mul_f32_e32 v131, 0xbfb8aa3b, v131
	v_add_f32_e32 v128, v108, v134
	v_exp_f32_e32 v134, v129
	v_add_f32_e32 v129, v109, v135
	v_exp_f32_e32 v135, v130
	v_add_f32_e32 v130, v110, v136
	v_exp_f32_e32 v136, v131
	v_add_f32_e32 v131, v111, v137
	v_mul_f32_e32 v130, 0xbfb8aa3b, v130
	v_mul_f32_e32 v131, 0xbfb8aa3b, v131
	v_exp_f32_e32 v130, v130
	v_exp_f32_e32 v131, v131
	v_mul_f32_e32 v128, 0xbfb8aa3b, v128
	v_mul_f32_e32 v129, 0xbfb8aa3b, v129
	v_exp_f32_e32 v128, v128
	v_pk_add_f32 v[130:131], v[130:131], 1.0 op_sel_hi:[1,0]
	v_exp_f32_e32 v129, v129
	v_div_scale_f32 v132, s[18:19], v131, v131, 1.0
	v_rcp_f32_e32 v137, v132
	v_pk_add_f32 v[128:129], v[128:129], 1.0 op_sel_hi:[1,0]
	v_fma_f32 v157, -v132, v137, 1.0
	v_fmac_f32_e32 v137, v157, v137
	v_div_scale_f32 v157, vcc, 1.0, v131, 1.0
	v_mul_f32_e32 v164, v157, v137
	v_fma_f32 v165, -v132, v164, v157
	v_fmac_f32_e32 v164, v165, v137
	v_fma_f32 v132, -v132, v164, v157
	v_div_fmas_f32 v132, v132, v137, v164
	v_div_fixup_f32 v131, v132, v131, 1.0
	v_div_scale_f32 v132, s[18:19], v130, v130, 1.0
	v_rcp_f32_e32 v137, v132
	s_nop 0
	v_fma_f32 v157, -v132, v137, 1.0
	v_fmac_f32_e32 v137, v157, v137
	v_div_scale_f32 v157, vcc, 1.0, v130, 1.0
	v_mul_f32_e32 v164, v157, v137
	v_fma_f32 v165, -v132, v164, v157
	v_fmac_f32_e32 v164, v165, v137
	v_fma_f32 v132, -v132, v164, v157
	v_div_fmas_f32 v132, v132, v137, v164
	v_div_fixup_f32 v130, v132, v130, 1.0
	v_div_scale_f32 v132, s[18:19], v129, v129, 1.0
	v_rcp_f32_e32 v137, v132
	s_nop 0
	v_fma_f32 v157, -v132, v137, 1.0
	v_fmac_f32_e32 v137, v157, v137
	v_div_scale_f32 v157, vcc, 1.0, v129, 1.0
	v_mul_f32_e32 v164, v157, v137
	v_fma_f32 v165, -v132, v164, v157
	v_fmac_f32_e32 v164, v165, v137
	v_fma_f32 v132, -v132, v164, v157
	v_div_fmas_f32 v132, v132, v137, v164
	v_div_fixup_f32 v129, v132, v129, 1.0
	v_div_scale_f32 v132, s[18:19], v128, v128, 1.0
	v_rcp_f32_e32 v137, v132
	s_nop 0
	v_fma_f32 v157, -v132, v137, 1.0
	v_fmac_f32_e32 v137, v157, v137
	v_div_scale_f32 v157, vcc, 1.0, v128, 1.0
	v_mul_f32_e32 v164, v157, v137
	v_fma_f32 v165, -v132, v164, v157
	v_fmac_f32_e32 v164, v165, v137
	v_fma_f32 v132, -v132, v164, v157
	v_div_fmas_f32 v132, v132, v137, v164
	v_div_fixup_f32 v128, v132, v128, 1.0
	v_add_f32_e32 v132, v107, v133
	v_mul_f32_e32 v132, 0xbfb8aa3b, v132
	v_exp_f32_e32 v137, v132
	v_pk_add_f32 v[132:133], v[134:135], 1.0 op_sel_hi:[1,0]
	v_pk_add_f32 v[134:135], v[136:137], 1.0 op_sel_hi:[1,0]
	s_nop 0
	v_div_scale_f32 v136, s[18:19], v135, v135, 1.0
	v_rcp_f32_e32 v137, v136
	s_nop 0
	v_fma_f32 v157, -v136, v137, 1.0
	v_fmac_f32_e32 v137, v157, v137
	v_div_scale_f32 v157, vcc, 1.0, v135, 1.0
	v_mul_f32_e32 v164, v157, v137
	v_fma_f32 v165, -v136, v164, v157
	v_fmac_f32_e32 v164, v165, v137
	v_fma_f32 v136, -v136, v164, v157
	v_div_fmas_f32 v136, v136, v137, v164
	v_div_fixup_f32 v135, v136, v135, 1.0
	v_div_scale_f32 v136, s[18:19], v134, v134, 1.0
	v_rcp_f32_e32 v137, v136
	s_nop 0
	v_fma_f32 v157, -v136, v137, 1.0
	v_fmac_f32_e32 v137, v157, v137
	v_div_scale_f32 v157, vcc, 1.0, v134, 1.0
	v_mul_f32_e32 v164, v157, v137
	v_fma_f32 v165, -v136, v164, v157
	v_fmac_f32_e32 v164, v165, v137
	v_fma_f32 v136, -v136, v164, v157
	v_div_fmas_f32 v136, v136, v137, v164
	v_div_fixup_f32 v134, v136, v134, 1.0
	v_div_scale_f32 v136, s[18:19], v133, v133, 1.0
	v_rcp_f32_e32 v137, v136
	s_nop 0
	v_fma_f32 v157, -v136, v137, 1.0
	v_fmac_f32_e32 v137, v157, v137
	v_div_scale_f32 v157, vcc, 1.0, v133, 1.0
	v_mul_f32_e32 v164, v157, v137
	v_fma_f32 v165, -v136, v164, v157
	v_fmac_f32_e32 v164, v165, v137
	v_fma_f32 v136, -v136, v164, v157
	v_div_fmas_f32 v136, v136, v137, v164
	v_div_fixup_f32 v133, v136, v133, 1.0
	v_div_scale_f32 v136, s[18:19], v132, v132, 1.0
	v_rcp_f32_e32 v137, v136
	s_nop 0
	v_fma_f32 v157, -v136, v137, 1.0
	v_fmac_f32_e32 v137, v157, v137
	v_div_scale_f32 v157, vcc, 1.0, v132, 1.0
	v_mul_f32_e32 v164, v157, v137
	v_fma_f32 v165, -v136, v164, v157
	v_fmac_f32_e32 v164, v165, v137
	v_fma_f32 v136, -v136, v164, v157
	v_div_fmas_f32 v136, v136, v137, v164
	v_div_fixup_f32 v132, v136, v132, 1.0
	v_lshl_add_u64 v[136:137], v[162:163], 2, s[20:21]
	global_store_dwordx4 v[136:137], v[128:131], off
	global_store_dwordx4 v[136:137], v[132:135], off offset:16

; __device__ __forceinline__ float sigmoidf_(float x) { return 1.0f / (1.0f + __expf(-x)); }
;     __device__ __forceinline__ void operator()(const f32x4 (&acc)[2][2][4][2], const pg8::Unit& u, int wr, int wc, int fr, int fq) const {
;     ...
;             EPI_BEGIN { const int c = col & 2047; const size_t off = (size_t)row * 2048 + c;
;                 if (grp == 0) { const f32x4 b0 = *(const f32x4*)(p0 + c), b1 = *(const f32x4*)(p0 + c + 4);
; #pragma unroll
;                     for (int e = 0; e < 4; ++e) { v0[e] = __expf(-0.6065306597126334f * sigmoidf_(v0[e] + b0[e])); v1[e] = __expf(-0.6065306597126334f * sigmoidf_(v1[e] + b1[e])); }
;                     *(f32x4*)(f0 + off) = v0; *(f32x4*)(f0 + off + 4) = v1;
.LBB0_1245:
	s_waitcnt lgkmcnt(0)
	s_nop 1
	v_mov_b32_e32 v130, v194
	v_mov_b32_e32 v131, v195
	v_mov_b32_e32 v132, v196
	v_mov_b32_e32 v133, v197
	v_mov_b32_e32 v134, v190
	v_mov_b32_e32 v135, v191
	v_mov_b32_e32 v136, v192
	v_mov_b32_e32 v137, v193
	v_add_f32_e32 v128, v108, v134
	v_mul_f32_e32 v128, 0xbfb8aa3b, v128
	v_exp_f32_e32 v128, v128
	s_nop 0
	v_add_f32_e32 v128, 1.0, v128
	v_div_scale_f32 v129, s[18:19], v128, v128, 1.0
	v_rcp_f32_e32 v134, v129
	s_nop 0
	v_fma_f32 v157, -v129, v134, 1.0
	v_fmac_f32_e32 v134, v157, v134
	v_div_scale_f32 v157, vcc, 1.0, v128, 1.0
	v_mul_f32_e32 v164, v157, v134
	v_fma_f32 v165, -v129, v164, v157
	v_fmac_f32_e32 v164, v165, v134
	v_fma_f32 v129, -v129, v164, v157
	v_div_fmas_f32 v129, v129, v134, v164
	v_div_fixup_f32 v128, v129, v128, 1.0
	v_add_f32_e32 v129, v104, v130
	v_mul_f32_e32 v129, 0xbfb8aa3b, v129
	v_exp_f32_e32 v129, v129
	v_mul_f32_e32 v128, 0xbf1b4598, v128
	v_mul_f32_e32 v128, 0x3fb8aa3b, v128
	v_exp_f32_e32 v128, v128
	v_add_f32_e32 v129, 1.0, v129
	v_div_scale_f32 v130, s[18:19], v129, v129, 1.0
	v_rcp_f32_e32 v134, v130
	s_nop 0
	v_fma_f32 v157, -v130, v134, 1.0
	v_fmac_f32_e32 v134, v157, v134
	v_div_scale_f32 v157, vcc, 1.0, v129, 1.0
	v_mul_f32_e32 v164, v157, v134
	v_fma_f32 v165, -v130, v164, v157
	v_fmac_f32_e32 v164, v165, v134
	v_fma_f32 v130, -v130, v164, v157
	v_div_fmas_f32 v130, v130, v134, v164
	v_div_fixup_f32 v129, v130, v129, 1.0
	v_mul_f32_e32 v129, 0xbf1b4598, v129
	v_mul_f32_e32 v129, 0x3fb8aa3b, v129
	v_exp_f32_e32 v134, v129
	v_add_f32_e32 v129, v109, v135
	v_mul_f32_e32 v129, 0xbfb8aa3b, v129
	v_exp_f32_e32 v129, v129
	s_nop 0
	v_add_f32_e32 v129, 1.0, v129
	v_div_scale_f32 v130, s[18:19], v129, v129, 1.0
	v_rcp_f32_e32 v135, v130
	s_nop 0
	v_fma_f32 v157, -v130, v135, 1.0
	v_fmac_f32_e32 v135, v157, v135
	v_div_scale_f32 v157, vcc, 1.0, v129, 1.0
	v_mul_f32_e32 v164, v157, v135
	v_fma_f32 v165, -v130, v164, v157
	v_fmac_f32_e32 v164, v165, v135
	v_fma_f32 v130, -v130, v164, v157
	v_div_fmas_f32 v130, v130, v135, v164
	v_div_fixup_f32 v129, v130, v129, 1.0
	v_add_f32_e32 v130, v105, v131
	v_mul_f32_e32 v130, 0xbfb8aa3b, v130
	v_exp_f32_e32 v130, v130
	v_mul_f32_e32 v129, 0xbf1b4598, v129
	v_mul_f32_e32 v129, 0x3fb8aa3b, v129
	v_exp_f32_e32 v129, v129
	v_add_f32_e32 v130, 1.0, v130
	v_div_scale_f32 v131, s[18:19], v130, v130, 1.0
	v_rcp_f32_e32 v135, v131
	s_nop 0
	v_fma_f32 v157, -v131, v135, 1.0
	v_fmac_f32_e32 v135, v157, v135
	v_div_scale_f32 v157, vcc, 1.0, v130, 1.0
	v_mul_f32_e32 v164, v157, v135
	v_fma_f32 v165, -v131, v164, v157
	v_fmac_f32_e32 v164, v165, v135
	v_fma_f32 v131, -v131, v164, v157
	v_div_fmas_f32 v131, v131, v135, v164
	v_div_fixup_f32 v130, v131, v130, 1.0
	v_mul_f32_e32 v130, 0xbf1b4598, v130
	v_mul_f32_e32 v130, 0x3fb8aa3b, v130
	v_exp_f32_e32 v135, v130
	v_add_f32_e32 v130, v110, v136
	v_mul_f32_e32 v130, 0xbfb8aa3b, v130
	v_exp_f32_e32 v130, v130
	s_nop 0
	v_add_f32_e32 v130, 1.0, v130
	v_div_scale_f32 v131, s[18:19], v130, v130, 1.0
	v_rcp_f32_e32 v136, v131
	s_nop 0
	v_fma_f32 v157, -v131, v136, 1.0
	v_fmac_f32_e32 v136, v157, v136
	v_div_scale_f32 v157, vcc, 1.0, v130, 1.0
	v_mul_f32_e32 v164, v157, v136
	v_fma_f32 v165, -v131, v164, v157
	v_fmac_f32_e32 v164, v165, v136
	v_fma_f32 v131, -v131, v164, v157
	v_div_fmas_f32 v131, v131, v136, v164
	v_div_fixup_f32 v130, v131, v130, 1.0
	v_add_f32_e32 v131, v106, v132
	v_mul_f32_e32 v131, 0xbfb8aa3b, v131
	v_exp_f32_e32 v131, v131
	v_mul_f32_e32 v130, 0xbf1b4598, v130
	v_mul_f32_e32 v130, 0x3fb8aa3b, v130
	v_exp_f32_e32 v130, v130
	v_add_f32_e32 v131, 1.0, v131
	v_div_scale_f32 v132, s[18:19], v131, v131, 1.0
	v_rcp_f32_e32 v136, v132
	s_nop 0
	v_fma_f32 v157, -v132, v136, 1.0
	v_fmac_f32_e32 v136, v157, v136
	v_div_scale_f32 v157, vcc, 1.0, v131, 1.0
	v_mul_f32_e32 v164, v157, v136
	v_fma_f32 v165, -v132, v164, v157
	v_fmac_f32_e32 v164, v165, v136
	v_fma_f32 v132, -v132, v164, v157
	v_div_fmas_f32 v132, v132, v136, v164
	v_div_fixup_f32 v131, v132, v131, 1.0
	v_mul_f32_e32 v131, 0xbf1b4598, v131
	v_mul_f32_e32 v131, 0x3fb8aa3b, v131
	v_exp_f32_e32 v136, v131
	v_add_f32_e32 v131, v111, v137
	v_mul_f32_e32 v131, 0xbfb8aa3b, v131
	v_exp_f32_e32 v131, v131
	s_nop 0
	v_add_f32_e32 v131, 1.0, v131
	v_div_scale_f32 v132, s[18:19], v131, v131, 1.0
	v_rcp_f32_e32 v137, v132
	s_nop 0
	v_fma_f32 v157, -v132, v137, 1.0
	v_fmac_f32_e32 v137, v157, v137
	v_div_scale_f32 v157, vcc, 1.0, v131, 1.0
	v_mul_f32_e32 v164, v157, v137
	v_fma_f32 v165, -v132, v164, v157
	v_fmac_f32_e32 v164, v165, v137
	v_fma_f32 v132, -v132, v164, v157
	v_div_fmas_f32 v132, v132, v137, v164
	v_div_fixup_f32 v131, v132, v131, 1.0
	v_add_f32_e32 v132, v107, v133
	v_mul_f32_e32 v132, 0xbfb8aa3b, v132
	v_exp_f32_e32 v132, v132
	v_mul_f32_e32 v131, 0xbf1b4598, v131
	v_mul_f32_e32 v131, 0x3fb8aa3b, v131
	v_exp_f32_e32 v131, v131
	v_add_f32_e32 v132, 1.0, v132
	v_div_scale_f32 v133, s[18:19], v132, v132, 1.0
	v_rcp_f32_e32 v137, v133
	s_nop 0
	v_fma_f32 v157, -v133, v137, 1.0
	v_fmac_f32_e32 v137, v157, v137
	v_div_scale_f32 v157, vcc, 1.0, v132, 1.0
	v_mul_f32_e32 v164, v157, v137
	v_fma_f32 v165, -v133, v164, v157
	v_fmac_f32_e32 v164, v165, v137
	v_fma_f32 v133, -v133, v164, v157
	v_div_fmas_f32 v133, v133, v137, v164
	v_div_fixup_f32 v132, v133, v132, 1.0
	v_mul_f32_e32 v132, 0xbf1b4598, v132
	v_mul_f32_e32 v132, 0x3fb8aa3b, v132
	v_exp_f32_e32 v137, v132
	v_lshl_add_u64 v[132:133], v[162:163], 2, s[50:51]
	global_store_dwordx4 v[132:133], v[128:131], off
	global_store_dwordx4 v[132:133], v[134:137], off offset:16
	s_and_b64 vcc, exec, s[46:47]
	s_mov_b64 s[18:19], -1
	s_cbranch_vccnz .LBB0_1015

; __device__ __forceinline__ float sigmoidf_(float x) { return 1.0f / (1.0f + __expf(-x)); }
;     __device__ __forceinline__ void operator()(const f32x4 (&acc)[2][2][4][2], const pg8::Unit& u, int wr, int wc, int fr, int fq) const {
;     ...
;                 } else if (grp == 1) { const f32x4 b0 = *(const f32x4*)(p1 + c), b1 = *(const f32x4*)(p1 + c + 4);
; #pragma unroll
;                     for (int e = 0; e < 4; ++e) { v0[e] = sigmoidf_(v0[e] + b0[e]); v1[e] = sigmoidf_(v1[e] + b1[e]); }
;                     *(f32x4*)(f1 + off) = v0; *(f32x4*)(f1 + off + 4) = v1;
.LBB0_1248:
	s_andn2_b64 vcc, exec, s[18:19]
	s_cbranch_vccnz .LBB0_1250
	s_waitcnt lgkmcnt(0)
	s_nop 1
	v_mov_b32_e32 v130, v236
	v_mov_b32_e32 v131, v237
	v_mov_b32_e32 v132, v238
	v_mov_b32_e32 v133, v239
	v_mov_b32_e32 v134, v232
	v_mov_b32_e32 v135, v233
	v_mov_b32_e32 v136, v234
	v_mov_b32_e32 v137, v235
	v_add_f32_e32 v129, v96, v130
	v_add_f32_e32 v130, v97, v131
	v_add_f32_e32 v131, v98, v132
	v_mul_f32_e32 v129, 0xbfb8aa3b, v129
	v_mul_f32_e32 v130, 0xbfb8aa3b, v130
	v_mul_f32_e32 v131, 0xbfb8aa3b, v131
	v_add_f32_e32 v128, v100, v134
	v_exp_f32_e32 v134, v129
	v_add_f32_e32 v129, v101, v135
	v_exp_f32_e32 v135, v130
	v_add_f32_e32 v130, v102, v136
	v_exp_f32_e32 v136, v131
	v_add_f32_e32 v131, v103, v137
	v_mul_f32_e32 v130, 0xbfb8aa3b, v130
	v_mul_f32_e32 v131, 0xbfb8aa3b, v131
	v_exp_f32_e32 v130, v130
	v_exp_f32_e32 v131, v131
	v_mul_f32_e32 v128, 0xbfb8aa3b, v128
	v_mul_f32_e32 v129, 0xbfb8aa3b, v129
	v_exp_f32_e32 v128, v128
	v_pk_add_f32 v[130:131], v[130:131], 1.0 op_sel_hi:[1,0]
	v_exp_f32_e32 v129, v129
	v_div_scale_f32 v132, s[18:19], v131, v131, 1.0
	v_rcp_f32_e32 v137, v132
	v_pk_add_f32 v[128:129], v[128:129], 1.0 op_sel_hi:[1,0]
	v_fma_f32 v157, -v132, v137, 1.0
	v_fmac_f32_e32 v137, v157, v137
	v_div_scale_f32 v157, vcc, 1.0, v131, 1.0
	v_mul_f32_e32 v162, v157, v137
	v_fma_f32 v163, -v132, v162, v157
	v_fmac_f32_e32 v162, v163, v137
	v_fma_f32 v132, -v132, v162, v157
	v_div_fmas_f32 v132, v132, v137, v162
	v_div_fixup_f32 v131, v132, v131, 1.0
	v_div_scale_f32 v132, s[18:19], v130, v130, 1.0
	v_rcp_f32_e32 v137, v132
	s_nop 0
	v_fma_f32 v157, -v132, v137, 1.0
	v_fmac_f32_e32 v137, v157, v137
	v_div_scale_f32 v157, vcc, 1.0, v130, 1.0
	v_mul_f32_e32 v162, v157, v137
	v_fma_f32 v163, -v132, v162, v157
	v_fmac_f32_e32 v162, v163, v137
	v_fma_f32 v132, -v132, v162, v157
	v_div_fmas_f32 v132, v132, v137, v162
	v_div_fixup_f32 v130, v132, v130, 1.0
	v_div_scale_f32 v132, s[18:19], v129, v129, 1.0
	v_rcp_f32_e32 v137, v132
	s_nop 0
	v_fma_f32 v157, -v132, v137, 1.0
	v_fmac_f32_e32 v137, v157, v137
	v_div_scale_f32 v157, vcc, 1.0, v129, 1.0
	v_mul_f32_e32 v162, v157, v137
	v_fma_f32 v163, -v132, v162, v157
	v_fmac_f32_e32 v162, v163, v137
	v_fma_f32 v132, -v132, v162, v157
	v_div_fmas_f32 v132, v132, v137, v162
	v_div_fixup_f32 v129, v132, v129, 1.0
	v_div_scale_f32 v132, s[18:19], v128, v128, 1.0
	v_rcp_f32_e32 v137, v132
	s_nop 0
	v_fma_f32 v157, -v132, v137, 1.0
	v_fmac_f32_e32 v137, v157, v137
	v_div_scale_f32 v157, vcc, 1.0, v128, 1.0
	v_mul_f32_e32 v162, v157, v137
	v_fma_f32 v163, -v132, v162, v157
	v_fmac_f32_e32 v162, v163, v137
	v_fma_f32 v132, -v132, v162, v157
	v_div_fmas_f32 v132, v132, v137, v162
	v_div_fixup_f32 v128, v132, v128, 1.0
	v_add_f32_e32 v132, v99, v133
	v_mul_f32_e32 v132, 0xbfb8aa3b, v132
	v_exp_f32_e32 v137, v132
	v_pk_add_f32 v[132:133], v[134:135], 1.0 op_sel_hi:[1,0]
	v_pk_add_f32 v[134:135], v[136:137], 1.0 op_sel_hi:[1,0]
	s_nop 0
	v_div_scale_f32 v136, s[18:19], v135, v135, 1.0
	v_rcp_f32_e32 v137, v136
	s_nop 0
	v_fma_f32 v157, -v136, v137, 1.0
	v_fmac_f32_e32 v137, v157, v137
	v_div_scale_f32 v157, vcc, 1.0, v135, 1.0
	v_mul_f32_e32 v162, v157, v137
	v_fma_f32 v163, -v136, v162, v157
	v_fmac_f32_e32 v162, v163, v137
	v_fma_f32 v136, -v136, v162, v157
	v_div_fmas_f32 v136, v136, v137, v162
	v_div_fixup_f32 v135, v136, v135, 1.0
	v_div_scale_f32 v136, s[18:19], v134, v134, 1.0
	v_rcp_f32_e32 v137, v136
	s_nop 0
	v_fma_f32 v157, -v136, v137, 1.0
	v_fmac_f32_e32 v137, v157, v137
	v_div_scale_f32 v157, vcc, 1.0, v134, 1.0
	v_mul_f32_e32 v162, v157, v137
	v_fma_f32 v163, -v136, v162, v157
	v_fmac_f32_e32 v162, v163, v137
	v_fma_f32 v136, -v136, v162, v157
	v_div_fmas_f32 v136, v136, v137, v162
	v_div_fixup_f32 v134, v136, v134, 1.0
	v_div_scale_f32 v136, s[18:19], v133, v133, 1.0
	v_rcp_f32_e32 v137, v136
	s_nop 0
	v_fma_f32 v157, -v136, v137, 1.0
	v_fmac_f32_e32 v137, v157, v137
	v_div_scale_f32 v157, vcc, 1.0, v133, 1.0
	v_mul_f32_e32 v162, v157, v137
	v_fma_f32 v163, -v136, v162, v157
	v_fmac_f32_e32 v162, v163, v137
	v_fma_f32 v136, -v136, v162, v157
	v_div_fmas_f32 v136, v136, v137, v162
	v_div_fixup_f32 v133, v136, v133, 1.0
	v_div_scale_f32 v136, s[18:19], v132, v132, 1.0
	v_rcp_f32_e32 v137, v136
	s_nop 0
	v_fma_f32 v157, -v136, v137, 1.0
	v_fmac_f32_e32 v137, v157, v137
	v_div_scale_f32 v157, vcc, 1.0, v132, 1.0
	v_mul_f32_e32 v162, v157, v137
	v_fma_f32 v163, -v136, v162, v157
	v_fmac_f32_e32 v162, v163, v137
	v_fma_f32 v136, -v136, v162, v157
	v_div_fmas_f32 v136, v136, v137, v162
	v_div_fixup_f32 v132, v136, v132, 1.0
	v_lshl_add_u64 v[136:137], v[160:161], 0, v[180:181]
	v_lshl_add_u64 v[136:137], v[136:137], 2, s[20:21]
	global_store_dwordx4 v[136:137], v[128:131], off offset:512
	global_store_dwordx4 v[136:137], v[132:135], off offset:528

; __device__ __forceinline__ float sigmoidf_(float x) { return 1.0f / (1.0f + __expf(-x)); }
;     __device__ __forceinline__ void operator()(const f32x4 (&acc)[2][2][4][2], const pg8::Unit& u, int wr, int wc, int fr, int fq) const {
;     ...
;                 } else if (grp == 1) { const f32x4 b0 = *(const f32x4*)(p1 + c), b1 = *(const f32x4*)(p1 + c + 4);
; #pragma unroll
;                     for (int e = 0; e < 4; ++e) { v0[e] = sigmoidf_(v0[e] + b0[e]); v1[e] = sigmoidf_(v1[e] + b1[e]); }
;                     *(f32x4*)(f1 + off) = v0; *(f32x4*)(f1 + off + 4) = v1;
.LBB0_1253:
	s_andn2_b64 vcc, exec, s[18:19]
	s_cbranch_vccnz .LBB0_1255
	s_waitcnt lgkmcnt(0)
	s_nop 1
	v_mov_b32_e32 v130, v228
	v_mov_b32_e32 v131, v229
	v_mov_b32_e32 v132, v230
	v_mov_b32_e32 v133, v231
	v_mov_b32_e32 v134, v224
	v_mov_b32_e32 v135, v225
	v_mov_b32_e32 v136, v226
	v_mov_b32_e32 v137, v227
	v_add_f32_e32 v129, v88, v130
	v_add_f32_e32 v130, v89, v131
	v_add_f32_e32 v131, v90, v132
	v_mul_f32_e32 v129, 0xbfb8aa3b, v129
	v_mul_f32_e32 v130, 0xbfb8aa3b, v130
	v_mul_f32_e32 v131, 0xbfb8aa3b, v131
	v_add_f32_e32 v128, v92, v134
	v_exp_f32_e32 v134, v129
	v_add_f32_e32 v129, v93, v135
	v_exp_f32_e32 v135, v130
	v_add_f32_e32 v130, v94, v136
	v_exp_f32_e32 v136, v131
	v_add_f32_e32 v131, v95, v137
	v_mul_f32_e32 v130, 0xbfb8aa3b, v130
	v_mul_f32_e32 v131, 0xbfb8aa3b, v131
	v_exp_f32_e32 v130, v130
	v_exp_f32_e32 v131, v131
	v_mul_f32_e32 v128, 0xbfb8aa3b, v128
	v_mul_f32_e32 v129, 0xbfb8aa3b, v129
	v_exp_f32_e32 v128, v128
	v_pk_add_f32 v[130:131], v[130:131], 1.0 op_sel_hi:[1,0]
	v_exp_f32_e32 v129, v129
	v_div_scale_f32 v132, s[18:19], v131, v131, 1.0
	v_rcp_f32_e32 v137, v132
	v_pk_add_f32 v[128:129], v[128:129], 1.0 op_sel_hi:[1,0]
	v_fma_f32 v157, -v132, v137, 1.0
	v_fmac_f32_e32 v137, v157, v137
	v_div_scale_f32 v157, vcc, 1.0, v131, 1.0
	v_mul_f32_e32 v164, v157, v137
	v_fma_f32 v165, -v132, v164, v157
	v_fmac_f32_e32 v164, v165, v137
	v_fma_f32 v132, -v132, v164, v157
	v_div_fmas_f32 v132, v132, v137, v164
	v_div_fixup_f32 v131, v132, v131, 1.0
	v_div_scale_f32 v132, s[18:19], v130, v130, 1.0
	v_rcp_f32_e32 v137, v132
	s_nop 0
	v_fma_f32 v157, -v132, v137, 1.0
	v_fmac_f32_e32 v137, v157, v137
	v_div_scale_f32 v157, vcc, 1.0, v130, 1.0
	v_mul_f32_e32 v164, v157, v137
	v_fma_f32 v165, -v132, v164, v157
	v_fmac_f32_e32 v164, v165, v137
	v_fma_f32 v132, -v132, v164, v157
	v_div_fmas_f32 v132, v132, v137, v164
	v_div_fixup_f32 v130, v132, v130, 1.0
	v_div_scale_f32 v132, s[18:19], v129, v129, 1.0
	v_rcp_f32_e32 v137, v132
	s_nop 0
	v_fma_f32 v157, -v132, v137, 1.0
	v_fmac_f32_e32 v137, v157, v137
	v_div_scale_f32 v157, vcc, 1.0, v129, 1.0
	v_mul_f32_e32 v164, v157, v137
	v_fma_f32 v165, -v132, v164, v157
	v_fmac_f32_e32 v164, v165, v137
	v_fma_f32 v132, -v132, v164, v157
	v_div_fmas_f32 v132, v132, v137, v164
	v_div_fixup_f32 v129, v132, v129, 1.0
	v_div_scale_f32 v132, s[18:19], v128, v128, 1.0
	v_rcp_f32_e32 v137, v132
	s_nop 0
	v_fma_f32 v157, -v132, v137, 1.0
	v_fmac_f32_e32 v137, v157, v137
	v_div_scale_f32 v157, vcc, 1.0, v128, 1.0
	v_mul_f32_e32 v164, v157, v137
	v_fma_f32 v165, -v132, v164, v157
	v_fmac_f32_e32 v164, v165, v137
	v_fma_f32 v132, -v132, v164, v157
	v_div_fmas_f32 v132, v132, v137, v164
	v_div_fixup_f32 v128, v132, v128, 1.0
	v_add_f32_e32 v132, v91, v133
	v_mul_f32_e32 v132, 0xbfb8aa3b, v132
	v_exp_f32_e32 v137, v132
	v_pk_add_f32 v[132:133], v[134:135], 1.0 op_sel_hi:[1,0]
	v_pk_add_f32 v[134:135], v[136:137], 1.0 op_sel_hi:[1,0]
	s_nop 0
	v_div_scale_f32 v136, s[18:19], v135, v135, 1.0
	v_rcp_f32_e32 v137, v136
	s_nop 0
	v_fma_f32 v157, -v136, v137, 1.0
	v_fmac_f32_e32 v137, v157, v137
	v_div_scale_f32 v157, vcc, 1.0, v135, 1.0
	v_mul_f32_e32 v164, v157, v137
	v_fma_f32 v165, -v136, v164, v157
	v_fmac_f32_e32 v164, v165, v137
	v_fma_f32 v136, -v136, v164, v157
	v_div_fmas_f32 v136, v136, v137, v164
	v_div_fixup_f32 v135, v136, v135, 1.0
	v_div_scale_f32 v136, s[18:19], v134, v134, 1.0
	v_rcp_f32_e32 v137, v136
	s_nop 0
	v_fma_f32 v157, -v136, v137, 1.0
	v_fmac_f32_e32 v137, v157, v137
	v_div_scale_f32 v157, vcc, 1.0, v134, 1.0
	v_mul_f32_e32 v164, v157, v137
	v_fma_f32 v165, -v136, v164, v157
	v_fmac_f32_e32 v164, v165, v137
	v_fma_f32 v136, -v136, v164, v157
	v_div_fmas_f32 v136, v136, v137, v164
	v_div_fixup_f32 v134, v136, v134, 1.0
	v_div_scale_f32 v136, s[18:19], v133, v133, 1.0
	v_rcp_f32_e32 v137, v136
	s_nop 0
	v_fma_f32 v157, -v136, v137, 1.0
	v_fmac_f32_e32 v137, v157, v137
	v_div_scale_f32 v157, vcc, 1.0, v133, 1.0
	v_mul_f32_e32 v164, v157, v137
	v_fma_f32 v165, -v136, v164, v157
	v_fmac_f32_e32 v164, v165, v137
	v_fma_f32 v136, -v136, v164, v157
	v_div_fmas_f32 v136, v136, v137, v164
	v_div_fixup_f32 v133, v136, v133, 1.0
	v_div_scale_f32 v136, s[18:19], v132, v132, 1.0
	v_rcp_f32_e32 v137, v136
	s_nop 0
	v_fma_f32 v157, -v136, v137, 1.0
	v_fmac_f32_e32 v137, v157, v137
	v_div_scale_f32 v157, vcc, 1.0, v132, 1.0
	v_mul_f32_e32 v164, v157, v137
	v_fma_f32 v165, -v136, v164, v157
	v_fmac_f32_e32 v164, v165, v137
	v_fma_f32 v136, -v136, v164, v157
	v_div_fmas_f32 v136, v136, v137, v164
	v_div_fixup_f32 v132, v136, v132, 1.0
	v_lshl_add_u64 v[136:137], v[162:163], 2, s[20:21]
	global_store_dwordx4 v[136:137], v[128:131], off
	global_store_dwordx4 v[136:137], v[132:135], off offset:16

; __device__ __forceinline__ float sigmoidf_(float x) { return 1.0f / (1.0f + __expf(-x)); }
;     __device__ __forceinline__ void operator()(const f32x4 (&acc)[2][2][4][2], const pg8::Unit& u, int wr, int wc, int fr, int fq) const {
;     ...
;             EPI_BEGIN { const int c = col & 2047; const size_t off = (size_t)row * 2048 + c;
;                 if (grp == 0) { const f32x4 b0 = *(const f32x4*)(p0 + c), b1 = *(const f32x4*)(p0 + c + 4);
; #pragma unroll
;                     for (int e = 0; e < 4; ++e) { v0[e] = __expf(-0.6065306597126334f * sigmoidf_(v0[e] + b0[e])); v1[e] = __expf(-0.6065306597126334f * sigmoidf_(v1[e] + b1[e])); }
;                     *(f32x4*)(f0 + off) = v0; *(f32x4*)(f0 + off + 4) = v1;
.LBB0_1256:
	s_waitcnt lgkmcnt(0)
	s_nop 1
	v_mov_b32_e32 v130, v194
	v_mov_b32_e32 v131, v195
	v_mov_b32_e32 v132, v196
	v_mov_b32_e32 v133, v197
	v_mov_b32_e32 v134, v190
	v_mov_b32_e32 v135, v191
	v_mov_b32_e32 v136, v192
	v_mov_b32_e32 v137, v193
	v_add_f32_e32 v128, v92, v134
	v_mul_f32_e32 v128, 0xbfb8aa3b, v128
	v_exp_f32_e32 v128, v128
	s_nop 0
	v_add_f32_e32 v128, 1.0, v128
	v_div_scale_f32 v129, s[18:19], v128, v128, 1.0
	v_rcp_f32_e32 v134, v129
	s_nop 0
	v_fma_f32 v157, -v129, v134, 1.0
	v_fmac_f32_e32 v134, v157, v134
	v_div_scale_f32 v157, vcc, 1.0, v128, 1.0
	v_mul_f32_e32 v164, v157, v134
	v_fma_f32 v165, -v129, v164, v157
	v_fmac_f32_e32 v164, v165, v134
	v_fma_f32 v129, -v129, v164, v157
	v_div_fmas_f32 v129, v129, v134, v164
	v_div_fixup_f32 v128, v129, v128, 1.0
	v_add_f32_e32 v129, v88, v130
	v_mul_f32_e32 v129, 0xbfb8aa3b, v129
	v_exp_f32_e32 v129, v129
	v_mul_f32_e32 v128, 0xbf1b4598, v128
	v_mul_f32_e32 v128, 0x3fb8aa3b, v128
	v_exp_f32_e32 v128, v128
	v_add_f32_e32 v129, 1.0, v129
	v_div_scale_f32 v130, s[18:19], v129, v129, 1.0
	v_rcp_f32_e32 v134, v130
	s_nop 0
	v_fma_f32 v157, -v130, v134, 1.0
	v_fmac_f32_e32 v134, v157, v134
	v_div_scale_f32 v157, vcc, 1.0, v129, 1.0
	v_mul_f32_e32 v164, v157, v134
	v_fma_f32 v165, -v130, v164, v157
	v_fmac_f32_e32 v164, v165, v134
	v_fma_f32 v130, -v130, v164, v157
	v_div_fmas_f32 v130, v130, v134, v164
	v_div_fixup_f32 v129, v130, v129, 1.0
	v_mul_f32_e32 v129, 0xbf1b4598, v129
	v_mul_f32_e32 v129, 0x3fb8aa3b, v129
	v_exp_f32_e32 v134, v129
	v_add_f32_e32 v129, v93, v135
	v_mul_f32_e32 v129, 0xbfb8aa3b, v129
	v_exp_f32_e32 v129, v129
	s_nop 0
	v_add_f32_e32 v129, 1.0, v129
	v_div_scale_f32 v130, s[18:19], v129, v129, 1.0
	v_rcp_f32_e32 v135, v130
	s_nop 0
	v_fma_f32 v157, -v130, v135, 1.0
	v_fmac_f32_e32 v135, v157, v135
	v_div_scale_f32 v157, vcc, 1.0, v129, 1.0
	v_mul_f32_e32 v164, v157, v135
	v_fma_f32 v165, -v130, v164, v157
	v_fmac_f32_e32 v164, v165, v135
	v_fma_f32 v130, -v130, v164, v157
	v_div_fmas_f32 v130, v130, v135, v164
	v_div_fixup_f32 v129, v130, v129, 1.0
	v_add_f32_e32 v130, v89, v131
	v_mul_f32_e32 v130, 0xbfb8aa3b, v130
	v_exp_f32_e32 v130, v130
	v_mul_f32_e32 v129, 0xbf1b4598, v129
	v_mul_f32_e32 v129, 0x3fb8aa3b, v129
	v_exp_f32_e32 v129, v129
	v_add_f32_e32 v130, 1.0, v130
	v_div_scale_f32 v131, s[18:19], v130, v130, 1.0
	v_rcp_f32_e32 v135, v131
	s_nop 0
	v_fma_f32 v157, -v131, v135, 1.0
	v_fmac_f32_e32 v135, v157, v135
	v_div_scale_f32 v157, vcc, 1.0, v130, 1.0
	v_mul_f32_e32 v164, v157, v135
	v_fma_f32 v165, -v131, v164, v157
	v_fmac_f32_e32 v164, v165, v135
	v_fma_f32 v131, -v131, v164, v157
	v_div_fmas_f32 v131, v131, v135, v164
	v_div_fixup_f32 v130, v131, v130, 1.0
	v_mul_f32_e32 v130, 0xbf1b4598, v130
	v_mul_f32_e32 v130, 0x3fb8aa3b, v130
	v_exp_f32_e32 v135, v130
	v_add_f32_e32 v130, v94, v136
	v_mul_f32_e32 v130, 0xbfb8aa3b, v130
	v_exp_f32_e32 v130, v130
	s_nop 0
	v_add_f32_e32 v130, 1.0, v130
	v_div_scale_f32 v131, s[18:19], v130, v130, 1.0
	v_rcp_f32_e32 v136, v131
	s_nop 0
	v_fma_f32 v157, -v131, v136, 1.0
	v_fmac_f32_e32 v136, v157, v136
	v_div_scale_f32 v157, vcc, 1.0, v130, 1.0
	v_mul_f32_e32 v164, v157, v136
	v_fma_f32 v165, -v131, v164, v157
	v_fmac_f32_e32 v164, v165, v136
	v_fma_f32 v131, -v131, v164, v157
	v_div_fmas_f32 v131, v131, v136, v164
	v_div_fixup_f32 v130, v131, v130, 1.0
	v_add_f32_e32 v131, v90, v132
	v_mul_f32_e32 v131, 0xbfb8aa3b, v131
	v_exp_f32_e32 v131, v131
	v_mul_f32_e32 v130, 0xbf1b4598, v130
	v_mul_f32_e32 v130, 0x3fb8aa3b, v130
	v_exp_f32_e32 v130, v130
	v_add_f32_e32 v131, 1.0, v131
	v_div_scale_f32 v132, s[18:19], v131, v131, 1.0
	v_rcp_f32_e32 v136, v132
	s_nop 0
	v_fma_f32 v157, -v132, v136, 1.0
	v_fmac_f32_e32 v136, v157, v136
	v_div_scale_f32 v157, vcc, 1.0, v131, 1.0
	v_mul_f32_e32 v164, v157, v136
	v_fma_f32 v165, -v132, v164, v157
	v_fmac_f32_e32 v164, v165, v136
	v_fma_f32 v132, -v132, v164, v157
	v_div_fmas_f32 v132, v132, v136, v164
	v_div_fixup_f32 v131, v132, v131, 1.0
	v_mul_f32_e32 v131, 0xbf1b4598, v131
	v_mul_f32_e32 v131, 0x3fb8aa3b, v131
	v_exp_f32_e32 v136, v131
	v_add_f32_e32 v131, v95, v137
	v_mul_f32_e32 v131, 0xbfb8aa3b, v131
	v_exp_f32_e32 v131, v131
	s_nop 0
	v_add_f32_e32 v131, 1.0, v131
	v_div_scale_f32 v132, s[18:19], v131, v131, 1.0
	v_rcp_f32_e32 v137, v132
	s_nop 0
	v_fma_f32 v157, -v132, v137, 1.0
	v_fmac_f32_e32 v137, v157, v137
	v_div_scale_f32 v157, vcc, 1.0, v131, 1.0
	v_mul_f32_e32 v164, v157, v137
	v_fma_f32 v165, -v132, v164, v157
	v_fmac_f32_e32 v164, v165, v137
	v_fma_f32 v132, -v132, v164, v157
	v_div_fmas_f32 v132, v132, v137, v164
	v_div_fixup_f32 v131, v132, v131, 1.0
	v_add_f32_e32 v132, v91, v133
	v_mul_f32_e32 v132, 0xbfb8aa3b, v132
	v_exp_f32_e32 v132, v132
	v_mul_f32_e32 v131, 0xbf1b4598, v131
	v_mul_f32_e32 v131, 0x3fb8aa3b, v131
	v_exp_f32_e32 v131, v131
	v_add_f32_e32 v132, 1.0, v132
	v_div_scale_f32 v133, s[18:19], v132, v132, 1.0
	v_rcp_f32_e32 v137, v133
	s_nop 0
	v_fma_f32 v157, -v133, v137, 1.0
	v_fmac_f32_e32 v137, v157, v137
	v_div_scale_f32 v157, vcc, 1.0, v132, 1.0
	v_mul_f32_e32 v164, v157, v137
	v_fma_f32 v165, -v133, v164, v157
	v_fmac_f32_e32 v164, v165, v137
	v_fma_f32 v133, -v133, v164, v157
	v_div_fmas_f32 v133, v133, v137, v164
	v_div_fixup_f32 v132, v133, v132, 1.0
	v_mul_f32_e32 v132, 0xbf1b4598, v132
	v_mul_f32_e32 v132, 0x3fb8aa3b, v132
	v_exp_f32_e32 v137, v132
	v_lshl_add_u64 v[132:133], v[162:163], 2, s[50:51]
	global_store_dwordx4 v[132:133], v[128:131], off
	global_store_dwordx4 v[132:133], v[134:137], off offset:16
	s_and_b64 vcc, exec, s[46:47]
	s_mov_b64 s[18:19], -1
	s_cbranch_vccnz .LBB0_1020

; __device__ __forceinline__ float sigmoidf_(float x) { return 1.0f / (1.0f + __expf(-x)); }
;     __device__ __forceinline__ void operator()(const f32x4 (&acc)[2][2][4][2], const pg8::Unit& u, int wr, int wc, int fr, int fq) const {
;     ...
;                 } else if (grp == 1) { const f32x4 b0 = *(const f32x4*)(p1 + c), b1 = *(const f32x4*)(p1 + c + 4);
; #pragma unroll
;                     for (int e = 0; e < 4; ++e) { v0[e] = sigmoidf_(v0[e] + b0[e]); v1[e] = sigmoidf_(v1[e] + b1[e]); }
;                     *(f32x4*)(f1 + off) = v0; *(f32x4*)(f1 + off + 4) = v1;
.LBB0_1259:
	s_andn2_b64 vcc, exec, s[18:19]
	s_cbranch_vccnz .LBB0_1261
	s_waitcnt lgkmcnt(0)
	s_nop 1
	v_mov_b32_e32 v130, v236
	v_mov_b32_e32 v131, v237
	v_mov_b32_e32 v132, v238
	v_mov_b32_e32 v133, v239
	v_mov_b32_e32 v134, v232
	v_mov_b32_e32 v135, v233
	v_mov_b32_e32 v136, v234
	v_mov_b32_e32 v137, v235
	v_add_f32_e32 v129, v80, v130
	v_add_f32_e32 v130, v81, v131
	v_add_f32_e32 v131, v82, v132
	v_mul_f32_e32 v129, 0xbfb8aa3b, v129
	v_mul_f32_e32 v130, 0xbfb8aa3b, v130
	v_mul_f32_e32 v131, 0xbfb8aa3b, v131
	v_add_f32_e32 v128, v84, v134
	v_exp_f32_e32 v134, v129
	v_add_f32_e32 v129, v85, v135
	v_exp_f32_e32 v135, v130
	v_add_f32_e32 v130, v86, v136
	v_exp_f32_e32 v136, v131
	v_add_f32_e32 v131, v87, v137
	v_mul_f32_e32 v130, 0xbfb8aa3b, v130
	v_mul_f32_e32 v131, 0xbfb8aa3b, v131
	v_exp_f32_e32 v130, v130
	v_exp_f32_e32 v131, v131
	v_mul_f32_e32 v128, 0xbfb8aa3b, v128
	v_mul_f32_e32 v129, 0xbfb8aa3b, v129
	v_exp_f32_e32 v128, v128
	v_pk_add_f32 v[130:131], v[130:131], 1.0 op_sel_hi:[1,0]
	v_exp_f32_e32 v129, v129
	v_div_scale_f32 v132, s[18:19], v131, v131, 1.0
	v_rcp_f32_e32 v137, v132
	v_pk_add_f32 v[128:129], v[128:129], 1.0 op_sel_hi:[1,0]
	v_fma_f32 v157, -v132, v137, 1.0
	v_fmac_f32_e32 v137, v157, v137
	v_div_scale_f32 v157, vcc, 1.0, v131, 1.0
	v_mul_f32_e32 v162, v157, v137
	v_fma_f32 v163, -v132, v162, v157
	v_fmac_f32_e32 v162, v163, v137
	v_fma_f32 v132, -v132, v162, v157
	v_div_fmas_f32 v132, v132, v137, v162
	v_div_fixup_f32 v131, v132, v131, 1.0
	v_div_scale_f32 v132, s[18:19], v130, v130, 1.0
	v_rcp_f32_e32 v137, v132
	s_nop 0
	v_fma_f32 v157, -v132, v137, 1.0
	v_fmac_f32_e32 v137, v157, v137
	v_div_scale_f32 v157, vcc, 1.0, v130, 1.0
	v_mul_f32_e32 v162, v157, v137
	v_fma_f32 v163, -v132, v162, v157
	v_fmac_f32_e32 v162, v163, v137
	v_fma_f32 v132, -v132, v162, v157
	v_div_fmas_f32 v132, v132, v137, v162
	v_div_fixup_f32 v130, v132, v130, 1.0
	v_div_scale_f32 v132, s[18:19], v129, v129, 1.0
	v_rcp_f32_e32 v137, v132
	s_nop 0
	v_fma_f32 v157, -v132, v137, 1.0
	v_fmac_f32_e32 v137, v157, v137
	v_div_scale_f32 v157, vcc, 1.0, v129, 1.0
	v_mul_f32_e32 v162, v157, v137
	v_fma_f32 v163, -v132, v162, v157
	v_fmac_f32_e32 v162, v163, v137
	v_fma_f32 v132, -v132, v162, v157
	v_div_fmas_f32 v132, v132, v137, v162
	v_div_fixup_f32 v129, v132, v129, 1.0
	v_div_scale_f32 v132, s[18:19], v128, v128, 1.0
	v_rcp_f32_e32 v137, v132
	s_nop 0
	v_fma_f32 v157, -v132, v137, 1.0
	v_fmac_f32_e32 v137, v157, v137
	v_div_scale_f32 v157, vcc, 1.0, v128, 1.0
	v_mul_f32_e32 v162, v157, v137
	v_fma_f32 v163, -v132, v162, v157
	v_fmac_f32_e32 v162, v163, v137
	v_fma_f32 v132, -v132, v162, v157
	v_div_fmas_f32 v132, v132, v137, v162
	v_div_fixup_f32 v128, v132, v128, 1.0
	v_add_f32_e32 v132, v83, v133
	v_mul_f32_e32 v132, 0xbfb8aa3b, v132
	v_exp_f32_e32 v137, v132
	v_pk_add_f32 v[132:133], v[134:135], 1.0 op_sel_hi:[1,0]
	v_pk_add_f32 v[134:135], v[136:137], 1.0 op_sel_hi:[1,0]
	s_nop 0
	v_div_scale_f32 v136, s[18:19], v135, v135, 1.0
	v_rcp_f32_e32 v137, v136
	s_nop 0
	v_fma_f32 v157, -v136, v137, 1.0
	v_fmac_f32_e32 v137, v157, v137
	v_div_scale_f32 v157, vcc, 1.0, v135, 1.0
	v_mul_f32_e32 v162, v157, v137
	v_fma_f32 v163, -v136, v162, v157
	v_fmac_f32_e32 v162, v163, v137
	v_fma_f32 v136, -v136, v162, v157
	v_div_fmas_f32 v136, v136, v137, v162
	v_div_fixup_f32 v135, v136, v135, 1.0
	v_div_scale_f32 v136, s[18:19], v134, v134, 1.0
	v_rcp_f32_e32 v137, v136
	s_nop 0
	v_fma_f32 v157, -v136, v137, 1.0
	v_fmac_f32_e32 v137, v157, v137
	v_div_scale_f32 v157, vcc, 1.0, v134, 1.0
	v_mul_f32_e32 v162, v157, v137
	v_fma_f32 v163, -v136, v162, v157
	v_fmac_f32_e32 v162, v163, v137
	v_fma_f32 v136, -v136, v162, v157
	v_div_fmas_f32 v136, v136, v137, v162
	v_div_fixup_f32 v134, v136, v134, 1.0
	v_div_scale_f32 v136, s[18:19], v133, v133, 1.0
	v_rcp_f32_e32 v137, v136
	s_nop 0
	v_fma_f32 v157, -v136, v137, 1.0
	v_fmac_f32_e32 v137, v157, v137
	v_div_scale_f32 v157, vcc, 1.0, v133, 1.0
	v_mul_f32_e32 v162, v157, v137
	v_fma_f32 v163, -v136, v162, v157
	v_fmac_f32_e32 v162, v163, v137
	v_fma_f32 v136, -v136, v162, v157
	v_div_fmas_f32 v136, v136, v137, v162
	v_div_fixup_f32 v133, v136, v133, 1.0
	v_div_scale_f32 v136, s[18:19], v132, v132, 1.0
	v_rcp_f32_e32 v137, v136
	s_nop 0
	v_fma_f32 v157, -v136, v137, 1.0
	v_fmac_f32_e32 v137, v157, v137
	v_div_scale_f32 v157, vcc, 1.0, v132, 1.0
	v_mul_f32_e32 v162, v157, v137
	v_fma_f32 v163, -v136, v162, v157
	v_fmac_f32_e32 v162, v163, v137
	v_fma_f32 v136, -v136, v162, v157
	v_div_fmas_f32 v136, v136, v137, v162
	v_div_fixup_f32 v132, v136, v132, 1.0
	v_lshl_add_u64 v[136:137], v[160:161], 0, v[180:181]
	v_lshl_add_u64 v[136:137], v[136:137], 2, s[20:21]
	global_store_dwordx4 v[136:137], v[128:131], off offset:512
	global_store_dwordx4 v[136:137], v[132:135], off offset:528

; __device__ __forceinline__ float sigmoidf_(float x) { return 1.0f / (1.0f + __expf(-x)); }
;     __device__ __forceinline__ void operator()(const f32x4 (&acc)[2][2][4][2], const pg8::Unit& u, int wr, int wc, int fr, int fq) const {
;     ...
;                 } else if (grp == 1) { const f32x4 b0 = *(const f32x4*)(p1 + c), b1 = *(const f32x4*)(p1 + c + 4);
; #pragma unroll
;                     for (int e = 0; e < 4; ++e) { v0[e] = sigmoidf_(v0[e] + b0[e]); v1[e] = sigmoidf_(v1[e] + b1[e]); }
;                     *(f32x4*)(f1 + off) = v0; *(f32x4*)(f1 + off + 4) = v1;
.LBB0_1264:
	s_andn2_b64 vcc, exec, s[18:19]
	s_cbranch_vccnz .LBB0_1266
	s_waitcnt lgkmcnt(0)
	s_nop 1
	v_mov_b32_e32 v130, v228
	v_mov_b32_e32 v131, v229
	v_mov_b32_e32 v132, v230
	v_mov_b32_e32 v133, v231
	v_mov_b32_e32 v134, v224
	v_mov_b32_e32 v135, v225
	v_mov_b32_e32 v136, v226
	v_mov_b32_e32 v137, v227
	v_add_f32_e32 v129, v72, v130
	v_add_f32_e32 v130, v73, v131
	v_add_f32_e32 v131, v74, v132
	v_mul_f32_e32 v129, 0xbfb8aa3b, v129
	v_mul_f32_e32 v130, 0xbfb8aa3b, v130
	v_mul_f32_e32 v131, 0xbfb8aa3b, v131
	v_add_f32_e32 v128, v76, v134
	v_exp_f32_e32 v134, v129
	v_add_f32_e32 v129, v77, v135
	v_exp_f32_e32 v135, v130
	v_add_f32_e32 v130, v78, v136
	v_exp_f32_e32 v136, v131
	v_add_f32_e32 v131, v79, v137
	v_mul_f32_e32 v130, 0xbfb8aa3b, v130
	v_mul_f32_e32 v131, 0xbfb8aa3b, v131
	v_exp_f32_e32 v130, v130
	v_exp_f32_e32 v131, v131
	v_mul_f32_e32 v128, 0xbfb8aa3b, v128
	v_mul_f32_e32 v129, 0xbfb8aa3b, v129
	v_exp_f32_e32 v128, v128
	v_pk_add_f32 v[130:131], v[130:131], 1.0 op_sel_hi:[1,0]
	v_exp_f32_e32 v129, v129
	v_div_scale_f32 v132, s[18:19], v131, v131, 1.0
	v_rcp_f32_e32 v137, v132
	v_pk_add_f32 v[128:129], v[128:129], 1.0 op_sel_hi:[1,0]
	v_fma_f32 v157, -v132, v137, 1.0
	v_fmac_f32_e32 v137, v157, v137
	v_div_scale_f32 v157, vcc, 1.0, v131, 1.0
	v_mul_f32_e32 v164, v157, v137
	v_fma_f32 v165, -v132, v164, v157
	v_fmac_f32_e32 v164, v165, v137
	v_fma_f32 v132, -v132, v164, v157
	v_div_fmas_f32 v132, v132, v137, v164
	v_div_fixup_f32 v131, v132, v131, 1.0
	v_div_scale_f32 v132, s[18:19], v130, v130, 1.0
	v_rcp_f32_e32 v137, v132
	s_nop 0
	v_fma_f32 v157, -v132, v137, 1.0
	v_fmac_f32_e32 v137, v157, v137
	v_div_scale_f32 v157, vcc, 1.0, v130, 1.0
	v_mul_f32_e32 v164, v157, v137
	v_fma_f32 v165, -v132, v164, v157
	v_fmac_f32_e32 v164, v165, v137
	v_fma_f32 v132, -v132, v164, v157
	v_div_fmas_f32 v132, v132, v137, v164
	v_div_fixup_f32 v130, v132, v130, 1.0
	v_div_scale_f32 v132, s[18:19], v129, v129, 1.0
	v_rcp_f32_e32 v137, v132
	s_nop 0
	v_fma_f32 v157, -v132, v137, 1.0
	v_fmac_f32_e32 v137, v157, v137
	v_div_scale_f32 v157, vcc, 1.0, v129, 1.0
	v_mul_f32_e32 v164, v157, v137
	v_fma_f32 v165, -v132, v164, v157
	v_fmac_f32_e32 v164, v165, v137
	v_fma_f32 v132, -v132, v164, v157
	v_div_fmas_f32 v132, v132, v137, v164
	v_div_fixup_f32 v129, v132, v129, 1.0
	v_div_scale_f32 v132, s[18:19], v128, v128, 1.0
	v_rcp_f32_e32 v137, v132
	s_nop 0
	v_fma_f32 v157, -v132, v137, 1.0
	v_fmac_f32_e32 v137, v157, v137
	v_div_scale_f32 v157, vcc, 1.0, v128, 1.0
	v_mul_f32_e32 v164, v157, v137
	v_fma_f32 v165, -v132, v164, v157
	v_fmac_f32_e32 v164, v165, v137
	v_fma_f32 v132, -v132, v164, v157
	v_div_fmas_f32 v132, v132, v137, v164
	v_div_fixup_f32 v128, v132, v128, 1.0
	v_add_f32_e32 v132, v75, v133
	v_mul_f32_e32 v132, 0xbfb8aa3b, v132
	v_exp_f32_e32 v137, v132
	v_pk_add_f32 v[132:133], v[134:135], 1.0 op_sel_hi:[1,0]
	v_pk_add_f32 v[134:135], v[136:137], 1.0 op_sel_hi:[1,0]
	s_nop 0
	v_div_scale_f32 v136, s[18:19], v135, v135, 1.0
	v_rcp_f32_e32 v137, v136
	s_nop 0
	v_fma_f32 v157, -v136, v137, 1.0
	v_fmac_f32_e32 v137, v157, v137
	v_div_scale_f32 v157, vcc, 1.0, v135, 1.0
	v_mul_f32_e32 v164, v157, v137
	v_fma_f32 v165, -v136, v164, v157
	v_fmac_f32_e32 v164, v165, v137
	v_fma_f32 v136, -v136, v164, v157
	v_div_fmas_f32 v136, v136, v137, v164
	v_div_fixup_f32 v135, v136, v135, 1.0
	v_div_scale_f32 v136, s[18:19], v134, v134, 1.0
	v_rcp_f32_e32 v137, v136
	s_nop 0
	v_fma_f32 v157, -v136, v137, 1.0
	v_fmac_f32_e32 v137, v157, v137
	v_div_scale_f32 v157, vcc, 1.0, v134, 1.0
	v_mul_f32_e32 v164, v157, v137
	v_fma_f32 v165, -v136, v164, v157
	v_fmac_f32_e32 v164, v165, v137
	v_fma_f32 v136, -v136, v164, v157
	v_div_fmas_f32 v136, v136, v137, v164
	v_div_fixup_f32 v134, v136, v134, 1.0
	v_div_scale_f32 v136, s[18:19], v133, v133, 1.0
	v_rcp_f32_e32 v137, v136
	s_nop 0
	v_fma_f32 v157, -v136, v137, 1.0
	v_fmac_f32_e32 v137, v157, v137
	v_div_scale_f32 v157, vcc, 1.0, v133, 1.0
	v_mul_f32_e32 v164, v157, v137
	v_fma_f32 v165, -v136, v164, v157
	v_fmac_f32_e32 v164, v165, v137
	v_fma_f32 v136, -v136, v164, v157
	v_div_fmas_f32 v136, v136, v137, v164
	v_div_fixup_f32 v133, v136, v133, 1.0
	v_div_scale_f32 v136, s[18:19], v132, v132, 1.0
	v_rcp_f32_e32 v137, v136
	s_nop 0
	v_fma_f32 v157, -v136, v137, 1.0
	v_fmac_f32_e32 v137, v157, v137
	v_div_scale_f32 v157, vcc, 1.0, v132, 1.0
	v_mul_f32_e32 v164, v157, v137
	v_fma_f32 v165, -v136, v164, v157
	v_fmac_f32_e32 v164, v165, v137
	v_fma_f32 v136, -v136, v164, v157
	v_div_fmas_f32 v136, v136, v137, v164
	v_div_fixup_f32 v132, v136, v132, 1.0
	v_lshl_add_u64 v[136:137], v[162:163], 2, s[20:21]
	global_store_dwordx4 v[136:137], v[128:131], off
	global_store_dwordx4 v[136:137], v[132:135], off offset:16

; __device__ __forceinline__ float sigmoidf_(float x) { return 1.0f / (1.0f + __expf(-x)); }
;     __device__ __forceinline__ void operator()(const f32x4 (&acc)[2][2][4][2], const pg8::Unit& u, int wr, int wc, int fr, int fq) const {
;     ...
;             EPI_BEGIN { const int c = col & 2047; const size_t off = (size_t)row * 2048 + c;
;                 if (grp == 0) { const f32x4 b0 = *(const f32x4*)(p0 + c), b1 = *(const f32x4*)(p0 + c + 4);
; #pragma unroll
;                     for (int e = 0; e < 4; ++e) { v0[e] = __expf(-0.6065306597126334f * sigmoidf_(v0[e] + b0[e])); v1[e] = __expf(-0.6065306597126334f * sigmoidf_(v1[e] + b1[e])); }
;                     *(f32x4*)(f0 + off) = v0; *(f32x4*)(f0 + off + 4) = v1;
.LBB0_1267:
	s_waitcnt lgkmcnt(0)
	s_nop 1
	v_mov_b32_e32 v130, v194
	v_mov_b32_e32 v131, v195
	v_mov_b32_e32 v132, v196
	v_mov_b32_e32 v133, v197
	v_mov_b32_e32 v134, v190
	v_mov_b32_e32 v135, v191
	v_mov_b32_e32 v136, v192
	v_mov_b32_e32 v137, v193
	v_add_f32_e32 v128, v76, v134
	v_mul_f32_e32 v128, 0xbfb8aa3b, v128
	v_exp_f32_e32 v128, v128
	s_nop 0
	v_add_f32_e32 v128, 1.0, v128
	v_div_scale_f32 v129, s[18:19], v128, v128, 1.0
	v_rcp_f32_e32 v134, v129
	s_nop 0
	v_fma_f32 v157, -v129, v134, 1.0
	v_fmac_f32_e32 v134, v157, v134
	v_div_scale_f32 v157, vcc, 1.0, v128, 1.0
	v_mul_f32_e32 v164, v157, v134
	v_fma_f32 v165, -v129, v164, v157
	v_fmac_f32_e32 v164, v165, v134
	v_fma_f32 v129, -v129, v164, v157
	v_div_fmas_f32 v129, v129, v134, v164
	v_div_fixup_f32 v128, v129, v128, 1.0
	v_add_f32_e32 v129, v72, v130
	v_mul_f32_e32 v129, 0xbfb8aa3b, v129
	v_exp_f32_e32 v129, v129
	v_mul_f32_e32 v128, 0xbf1b4598, v128
	v_mul_f32_e32 v128, 0x3fb8aa3b, v128
	v_exp_f32_e32 v128, v128
	v_add_f32_e32 v129, 1.0, v129
	v_div_scale_f32 v130, s[18:19], v129, v129, 1.0
	v_rcp_f32_e32 v134, v130
	s_nop 0
	v_fma_f32 v157, -v130, v134, 1.0
	v_fmac_f32_e32 v134, v157, v134
	v_div_scale_f32 v157, vcc, 1.0, v129, 1.0
	v_mul_f32_e32 v164, v157, v134
	v_fma_f32 v165, -v130, v164, v157
	v_fmac_f32_e32 v164, v165, v134
	v_fma_f32 v130, -v130, v164, v157
	v_div_fmas_f32 v130, v130, v134, v164
	v_div_fixup_f32 v129, v130, v129, 1.0
	v_mul_f32_e32 v129, 0xbf1b4598, v129
	v_mul_f32_e32 v129, 0x3fb8aa3b, v129
	v_exp_f32_e32 v134, v129
	v_add_f32_e32 v129, v77, v135
	v_mul_f32_e32 v129, 0xbfb8aa3b, v129
	v_exp_f32_e32 v129, v129
	s_nop 0
	v_add_f32_e32 v129, 1.0, v129
	v_div_scale_f32 v130, s[18:19], v129, v129, 1.0
	v_rcp_f32_e32 v135, v130
	s_nop 0
	v_fma_f32 v157, -v130, v135, 1.0
	v_fmac_f32_e32 v135, v157, v135
	v_div_scale_f32 v157, vcc, 1.0, v129, 1.0
	v_mul_f32_e32 v164, v157, v135
	v_fma_f32 v165, -v130, v164, v157
	v_fmac_f32_e32 v164, v165, v135
	v_fma_f32 v130, -v130, v164, v157
	v_div_fmas_f32 v130, v130, v135, v164
	v_div_fixup_f32 v129, v130, v129, 1.0
	v_add_f32_e32 v130, v73, v131
	v_mul_f32_e32 v130, 0xbfb8aa3b, v130
	v_exp_f32_e32 v130, v130
	v_mul_f32_e32 v129, 0xbf1b4598, v129
	v_mul_f32_e32 v129, 0x3fb8aa3b, v129
	v_exp_f32_e32 v129, v129
	v_add_f32_e32 v130, 1.0, v130
	v_div_scale_f32 v131, s[18:19], v130, v130, 1.0
	v_rcp_f32_e32 v135, v131
	s_nop 0
	v_fma_f32 v157, -v131, v135, 1.0
	v_fmac_f32_e32 v135, v157, v135
	v_div_scale_f32 v157, vcc, 1.0, v130, 1.0
	v_mul_f32_e32 v164, v157, v135
	v_fma_f32 v165, -v131, v164, v157
	v_fmac_f32_e32 v164, v165, v135
	v_fma_f32 v131, -v131, v164, v157
	v_div_fmas_f32 v131, v131, v135, v164
	v_div_fixup_f32 v130, v131, v130, 1.0
	v_mul_f32_e32 v130, 0xbf1b4598, v130
	v_mul_f32_e32 v130, 0x3fb8aa3b, v130
	v_exp_f32_e32 v135, v130
	v_add_f32_e32 v130, v78, v136
	v_mul_f32_e32 v130, 0xbfb8aa3b, v130
	v_exp_f32_e32 v130, v130
	s_nop 0
	v_add_f32_e32 v130, 1.0, v130
	v_div_scale_f32 v131, s[18:19], v130, v130, 1.0
	v_rcp_f32_e32 v136, v131
	s_nop 0
	v_fma_f32 v157, -v131, v136, 1.0
	v_fmac_f32_e32 v136, v157, v136
	v_div_scale_f32 v157, vcc, 1.0, v130, 1.0
	v_mul_f32_e32 v164, v157, v136
	v_fma_f32 v165, -v131, v164, v157
	v_fmac_f32_e32 v164, v165, v136
	v_fma_f32 v131, -v131, v164, v157
	v_div_fmas_f32 v131, v131, v136, v164
	v_div_fixup_f32 v130, v131, v130, 1.0
	v_add_f32_e32 v131, v74, v132
	v_mul_f32_e32 v131, 0xbfb8aa3b, v131
	v_exp_f32_e32 v131, v131
	v_mul_f32_e32 v130, 0xbf1b4598, v130
	v_mul_f32_e32 v130, 0x3fb8aa3b, v130
	v_exp_f32_e32 v130, v130
	v_add_f32_e32 v131, 1.0, v131
	v_div_scale_f32 v132, s[18:19], v131, v131, 1.0
	v_rcp_f32_e32 v136, v132
	s_nop 0
	v_fma_f32 v157, -v132, v136, 1.0
	v_fmac_f32_e32 v136, v157, v136
	v_div_scale_f32 v157, vcc, 1.0, v131, 1.0
	v_mul_f32_e32 v164, v157, v136
	v_fma_f32 v165, -v132, v164, v157
	v_fmac_f32_e32 v164, v165, v136
	v_fma_f32 v132, -v132, v164, v157
	v_div_fmas_f32 v132, v132, v136, v164
	v_div_fixup_f32 v131, v132, v131, 1.0
	v_mul_f32_e32 v131, 0xbf1b4598, v131
	v_mul_f32_e32 v131, 0x3fb8aa3b, v131
	v_exp_f32_e32 v136, v131
	v_add_f32_e32 v131, v79, v137
	v_mul_f32_e32 v131, 0xbfb8aa3b, v131
	v_exp_f32_e32 v131, v131
	s_nop 0
	v_add_f32_e32 v131, 1.0, v131
	v_div_scale_f32 v132, s[18:19], v131, v131, 1.0
	v_rcp_f32_e32 v137, v132
	s_nop 0
	v_fma_f32 v157, -v132, v137, 1.0
	v_fmac_f32_e32 v137, v157, v137
	v_div_scale_f32 v157, vcc, 1.0, v131, 1.0
	v_mul_f32_e32 v164, v157, v137
	v_fma_f32 v165, -v132, v164, v157
	v_fmac_f32_e32 v164, v165, v137
	v_fma_f32 v132, -v132, v164, v157
	v_div_fmas_f32 v132, v132, v137, v164
	v_div_fixup_f32 v131, v132, v131, 1.0
	v_add_f32_e32 v132, v75, v133
	v_mul_f32_e32 v132, 0xbfb8aa3b, v132
	v_exp_f32_e32 v132, v132
	v_mul_f32_e32 v131, 0xbf1b4598, v131
	v_mul_f32_e32 v131, 0x3fb8aa3b, v131
	v_exp_f32_e32 v131, v131
	v_add_f32_e32 v132, 1.0, v132
	v_div_scale_f32 v133, s[18:19], v132, v132, 1.0
	v_rcp_f32_e32 v137, v133
	s_nop 0
	v_fma_f32 v157, -v133, v137, 1.0
	v_fmac_f32_e32 v137, v157, v137
	v_div_scale_f32 v157, vcc, 1.0, v132, 1.0
	v_mul_f32_e32 v164, v157, v137
	v_fma_f32 v165, -v133, v164, v157
	v_fmac_f32_e32 v164, v165, v137
	v_fma_f32 v133, -v133, v164, v157
	v_div_fmas_f32 v133, v133, v137, v164
	v_div_fixup_f32 v132, v133, v132, 1.0
	v_mul_f32_e32 v132, 0xbf1b4598, v132
	v_mul_f32_e32 v132, 0x3fb8aa3b, v132
	v_exp_f32_e32 v137, v132
	v_lshl_add_u64 v[132:133], v[162:163], 2, s[50:51]
	global_store_dwordx4 v[132:133], v[128:131], off
	global_store_dwordx4 v[132:133], v[134:137], off offset:16
	s_and_b64 vcc, exec, s[46:47]
	s_mov_b64 s[18:19], -1
	s_cbranch_vccnz .LBB0_1025

; __device__ __forceinline__ float sigmoidf_(float x) { return 1.0f / (1.0f + __expf(-x)); }
;     __device__ __forceinline__ void operator()(const f32x4 (&acc)[2][2][4][2], const pg8::Unit& u, int wr, int wc, int fr, int fq) const {
;     ...
;                 } else if (grp == 1) { const f32x4 b0 = *(const f32x4*)(p1 + c), b1 = *(const f32x4*)(p1 + c + 4);
; #pragma unroll
;                     for (int e = 0; e < 4; ++e) { v0[e] = sigmoidf_(v0[e] + b0[e]); v1[e] = sigmoidf_(v1[e] + b1[e]); }
;                     *(f32x4*)(f1 + off) = v0; *(f32x4*)(f1 + off + 4) = v1;
.LBB0_1270:
	s_andn2_b64 vcc, exec, s[18:19]
	s_cbranch_vccnz .LBB0_1272
	s_waitcnt lgkmcnt(0)
	s_nop 1
	v_mov_b32_e32 v130, v236
	v_mov_b32_e32 v131, v237
	v_mov_b32_e32 v132, v238
	v_mov_b32_e32 v133, v239
	v_mov_b32_e32 v134, v232
	v_mov_b32_e32 v135, v233
	v_mov_b32_e32 v136, v234
	v_mov_b32_e32 v137, v235
	v_add_f32_e32 v129, v64, v130
	v_add_f32_e32 v130, v65, v131
	v_add_f32_e32 v131, v66, v132
	v_mul_f32_e32 v129, 0xbfb8aa3b, v129
	v_mul_f32_e32 v130, 0xbfb8aa3b, v130
	v_mul_f32_e32 v131, 0xbfb8aa3b, v131
	v_add_f32_e32 v128, v68, v134
	v_exp_f32_e32 v134, v129
	v_add_f32_e32 v129, v69, v135
	v_exp_f32_e32 v135, v130
	v_add_f32_e32 v130, v70, v136
	v_exp_f32_e32 v136, v131
	v_add_f32_e32 v131, v71, v137
	v_mul_f32_e32 v130, 0xbfb8aa3b, v130
	v_mul_f32_e32 v131, 0xbfb8aa3b, v131
	v_exp_f32_e32 v130, v130
	v_exp_f32_e32 v131, v131
	v_mul_f32_e32 v128, 0xbfb8aa3b, v128
	v_mul_f32_e32 v129, 0xbfb8aa3b, v129
	v_exp_f32_e32 v128, v128
	v_pk_add_f32 v[130:131], v[130:131], 1.0 op_sel_hi:[1,0]
	v_exp_f32_e32 v129, v129
	v_div_scale_f32 v132, s[18:19], v131, v131, 1.0
	v_rcp_f32_e32 v137, v132
	v_pk_add_f32 v[128:129], v[128:129], 1.0 op_sel_hi:[1,0]
	v_fma_f32 v157, -v132, v137, 1.0
	v_fmac_f32_e32 v137, v157, v137
	v_div_scale_f32 v157, vcc, 1.0, v131, 1.0
	v_mul_f32_e32 v162, v157, v137
	v_fma_f32 v163, -v132, v162, v157
	v_fmac_f32_e32 v162, v163, v137
	v_fma_f32 v132, -v132, v162, v157
	v_div_fmas_f32 v132, v132, v137, v162
	v_div_fixup_f32 v131, v132, v131, 1.0
	v_div_scale_f32 v132, s[18:19], v130, v130, 1.0
	v_rcp_f32_e32 v137, v132
	s_nop 0
	v_fma_f32 v157, -v132, v137, 1.0
	v_fmac_f32_e32 v137, v157, v137
	v_div_scale_f32 v157, vcc, 1.0, v130, 1.0
	v_mul_f32_e32 v162, v157, v137
	v_fma_f32 v163, -v132, v162, v157
	v_fmac_f32_e32 v162, v163, v137
	v_fma_f32 v132, -v132, v162, v157
	v_div_fmas_f32 v132, v132, v137, v162
	v_div_fixup_f32 v130, v132, v130, 1.0
	v_div_scale_f32 v132, s[18:19], v129, v129, 1.0
	v_rcp_f32_e32 v137, v132
	s_nop 0
	v_fma_f32 v157, -v132, v137, 1.0
	v_fmac_f32_e32 v137, v157, v137
	v_div_scale_f32 v157, vcc, 1.0, v129, 1.0
	v_mul_f32_e32 v162, v157, v137
	v_fma_f32 v163, -v132, v162, v157
	v_fmac_f32_e32 v162, v163, v137
	v_fma_f32 v132, -v132, v162, v157
	v_div_fmas_f32 v132, v132, v137, v162
	v_div_fixup_f32 v129, v132, v129, 1.0
	v_div_scale_f32 v132, s[18:19], v128, v128, 1.0
	v_rcp_f32_e32 v137, v132
	s_nop 0
	v_fma_f32 v157, -v132, v137, 1.0
	v_fmac_f32_e32 v137, v157, v137
	v_div_scale_f32 v157, vcc, 1.0, v128, 1.0
	v_mul_f32_e32 v162, v157, v137
	v_fma_f32 v163, -v132, v162, v157
	v_fmac_f32_e32 v162, v163, v137
	v_fma_f32 v132, -v132, v162, v157
	v_div_fmas_f32 v132, v132, v137, v162
	v_div_fixup_f32 v128, v132, v128, 1.0
	v_add_f32_e32 v132, v67, v133
	v_mul_f32_e32 v132, 0xbfb8aa3b, v132
	v_exp_f32_e32 v137, v132
	v_pk_add_f32 v[132:133], v[134:135], 1.0 op_sel_hi:[1,0]
	v_pk_add_f32 v[134:135], v[136:137], 1.0 op_sel_hi:[1,0]
	s_nop 0
	v_div_scale_f32 v136, s[18:19], v135, v135, 1.0
	v_rcp_f32_e32 v137, v136
	s_nop 0
	v_fma_f32 v157, -v136, v137, 1.0
	v_fmac_f32_e32 v137, v157, v137
	v_div_scale_f32 v157, vcc, 1.0, v135, 1.0
	v_mul_f32_e32 v162, v157, v137
	v_fma_f32 v163, -v136, v162, v157
	v_fmac_f32_e32 v162, v163, v137
	v_fma_f32 v136, -v136, v162, v157
	v_div_fmas_f32 v136, v136, v137, v162
	v_div_fixup_f32 v135, v136, v135, 1.0
	v_div_scale_f32 v136, s[18:19], v134, v134, 1.0
	v_rcp_f32_e32 v137, v136
	s_nop 0
	v_fma_f32 v157, -v136, v137, 1.0
	v_fmac_f32_e32 v137, v157, v137
	v_div_scale_f32 v157, vcc, 1.0, v134, 1.0
	v_mul_f32_e32 v162, v157, v137
	v_fma_f32 v163, -v136, v162, v157
	v_fmac_f32_e32 v162, v163, v137
	v_fma_f32 v136, -v136, v162, v157
	v_div_fmas_f32 v136, v136, v137, v162
	v_div_fixup_f32 v134, v136, v134, 1.0
	v_div_scale_f32 v136, s[18:19], v133, v133, 1.0
	v_rcp_f32_e32 v137, v136
	s_nop 0
	v_fma_f32 v157, -v136, v137, 1.0
	v_fmac_f32_e32 v137, v157, v137
	v_div_scale_f32 v157, vcc, 1.0, v133, 1.0
	v_mul_f32_e32 v162, v157, v137
	v_fma_f32 v163, -v136, v162, v157
	v_fmac_f32_e32 v162, v163, v137
	v_fma_f32 v136, -v136, v162, v157
	v_div_fmas_f32 v136, v136, v137, v162
	v_div_fixup_f32 v133, v136, v133, 1.0
	v_div_scale_f32 v136, s[18:19], v132, v132, 1.0
	v_rcp_f32_e32 v137, v136
	s_nop 0
	v_fma_f32 v157, -v136, v137, 1.0
	v_fmac_f32_e32 v137, v157, v137
	v_div_scale_f32 v157, vcc, 1.0, v132, 1.0
	v_mul_f32_e32 v162, v157, v137
	v_fma_f32 v163, -v136, v162, v157
	v_fmac_f32_e32 v162, v163, v137
	v_fma_f32 v136, -v136, v162, v157
	v_div_fmas_f32 v136, v136, v137, v162
	v_div_fixup_f32 v132, v136, v132, 1.0
	v_lshl_add_u64 v[136:137], v[160:161], 0, v[180:181]
	v_lshl_add_u64 v[136:137], v[136:137], 2, s[20:21]
	global_store_dwordx4 v[136:137], v[128:131], off offset:512
	global_store_dwordx4 v[136:137], v[132:135], off offset:528

; __device__ __forceinline__ float sigmoidf_(float x) { return 1.0f / (1.0f + __expf(-x)); }
;     __device__ __forceinline__ void operator()(const f32x4 (&acc)[2][2][4][2], const pg8::Unit& u, int wr, int wc, int fr, int fq) const {
;     ...
;                 } else if (grp == 1) { const f32x4 b0 = *(const f32x4*)(p1 + c), b1 = *(const f32x4*)(p1 + c + 4);
; #pragma unroll
;                     for (int e = 0; e < 4; ++e) { v0[e] = sigmoidf_(v0[e] + b0[e]); v1[e] = sigmoidf_(v1[e] + b1[e]); }
;                     *(f32x4*)(f1 + off) = v0; *(f32x4*)(f1 + off + 4) = v1;
.LBB0_1275:
	s_andn2_b64 vcc, exec, s[18:19]
	s_cbranch_vccnz .LBB0_1277
	s_waitcnt lgkmcnt(0)
	s_nop 1
	v_mov_b32_e32 v130, v228
	v_mov_b32_e32 v131, v229
	v_mov_b32_e32 v132, v230
	v_mov_b32_e32 v133, v231
	v_mov_b32_e32 v134, v224
	v_mov_b32_e32 v135, v225
	v_mov_b32_e32 v136, v226
	v_mov_b32_e32 v137, v227
	v_add_f32_e32 v129, v56, v130
	v_add_f32_e32 v130, v57, v131
	v_add_f32_e32 v131, v58, v132
	v_mul_f32_e32 v129, 0xbfb8aa3b, v129
	v_mul_f32_e32 v130, 0xbfb8aa3b, v130
	v_mul_f32_e32 v131, 0xbfb8aa3b, v131
	v_add_f32_e32 v128, v60, v134
	v_exp_f32_e32 v134, v129
	v_add_f32_e32 v129, v61, v135
	v_exp_f32_e32 v135, v130
	v_add_f32_e32 v130, v62, v136
	v_exp_f32_e32 v136, v131
	v_add_f32_e32 v131, v63, v137
	v_mul_f32_e32 v130, 0xbfb8aa3b, v130
	v_mul_f32_e32 v131, 0xbfb8aa3b, v131
	v_exp_f32_e32 v130, v130
	v_exp_f32_e32 v131, v131
	v_mul_f32_e32 v128, 0xbfb8aa3b, v128
	v_mul_f32_e32 v129, 0xbfb8aa3b, v129
	v_exp_f32_e32 v128, v128
	v_pk_add_f32 v[130:131], v[130:131], 1.0 op_sel_hi:[1,0]
	v_exp_f32_e32 v129, v129
	v_div_scale_f32 v132, s[18:19], v131, v131, 1.0
	v_rcp_f32_e32 v137, v132
	v_pk_add_f32 v[128:129], v[128:129], 1.0 op_sel_hi:[1,0]
	v_fma_f32 v157, -v132, v137, 1.0
	v_fmac_f32_e32 v137, v157, v137
	v_div_scale_f32 v157, vcc, 1.0, v131, 1.0
	v_mul_f32_e32 v164, v157, v137
	v_fma_f32 v165, -v132, v164, v157
	v_fmac_f32_e32 v164, v165, v137
	v_fma_f32 v132, -v132, v164, v157
	v_div_fmas_f32 v132, v132, v137, v164
	v_div_fixup_f32 v131, v132, v131, 1.0
	v_div_scale_f32 v132, s[18:19], v130, v130, 1.0
	v_rcp_f32_e32 v137, v132
	s_nop 0
	v_fma_f32 v157, -v132, v137, 1.0
	v_fmac_f32_e32 v137, v157, v137
	v_div_scale_f32 v157, vcc, 1.0, v130, 1.0
	v_mul_f32_e32 v164, v157, v137
	v_fma_f32 v165, -v132, v164, v157
	v_fmac_f32_e32 v164, v165, v137
	v_fma_f32 v132, -v132, v164, v157
	v_div_fmas_f32 v132, v132, v137, v164
	v_div_fixup_f32 v130, v132, v130, 1.0
	v_div_scale_f32 v132, s[18:19], v129, v129, 1.0
	v_rcp_f32_e32 v137, v132
	s_nop 0
	v_fma_f32 v157, -v132, v137, 1.0
	v_fmac_f32_e32 v137, v157, v137
	v_div_scale_f32 v157, vcc, 1.0, v129, 1.0
	v_mul_f32_e32 v164, v157, v137
	v_fma_f32 v165, -v132, v164, v157
	v_fmac_f32_e32 v164, v165, v137
	v_fma_f32 v132, -v132, v164, v157
	v_div_fmas_f32 v132, v132, v137, v164
	v_div_fixup_f32 v129, v132, v129, 1.0
	v_div_scale_f32 v132, s[18:19], v128, v128, 1.0
	v_rcp_f32_e32 v137, v132
	s_nop 0
	v_fma_f32 v157, -v132, v137, 1.0
	v_fmac_f32_e32 v137, v157, v137
	v_div_scale_f32 v157, vcc, 1.0, v128, 1.0
	v_mul_f32_e32 v164, v157, v137
	v_fma_f32 v165, -v132, v164, v157
	v_fmac_f32_e32 v164, v165, v137
	v_fma_f32 v132, -v132, v164, v157
	v_div_fmas_f32 v132, v132, v137, v164
	v_div_fixup_f32 v128, v132, v128, 1.0
	v_add_f32_e32 v132, v59, v133
	v_mul_f32_e32 v132, 0xbfb8aa3b, v132
	v_exp_f32_e32 v137, v132
	v_pk_add_f32 v[132:133], v[134:135], 1.0 op_sel_hi:[1,0]
	v_pk_add_f32 v[134:135], v[136:137], 1.0 op_sel_hi:[1,0]
	s_nop 0
	v_div_scale_f32 v136, s[18:19], v135, v135, 1.0
	v_rcp_f32_e32 v137, v136
	s_nop 0
	v_fma_f32 v157, -v136, v137, 1.0
	v_fmac_f32_e32 v137, v157, v137
	v_div_scale_f32 v157, vcc, 1.0, v135, 1.0
	v_mul_f32_e32 v164, v157, v137
	v_fma_f32 v165, -v136, v164, v157
	v_fmac_f32_e32 v164, v165, v137
	v_fma_f32 v136, -v136, v164, v157
	v_div_fmas_f32 v136, v136, v137, v164
	v_div_fixup_f32 v135, v136, v135, 1.0
	v_div_scale_f32 v136, s[18:19], v134, v134, 1.0
	v_rcp_f32_e32 v137, v136
	s_nop 0
	v_fma_f32 v157, -v136, v137, 1.0
	v_fmac_f32_e32 v137, v157, v137
	v_div_scale_f32 v157, vcc, 1.0, v134, 1.0
	v_mul_f32_e32 v164, v157, v137
	v_fma_f32 v165, -v136, v164, v157
	v_fmac_f32_e32 v164, v165, v137
	v_fma_f32 v136, -v136, v164, v157
	v_div_fmas_f32 v136, v136, v137, v164
	v_div_fixup_f32 v134, v136, v134, 1.0
	v_div_scale_f32 v136, s[18:19], v133, v133, 1.0
	v_rcp_f32_e32 v137, v136
	s_nop 0
	v_fma_f32 v157, -v136, v137, 1.0
	v_fmac_f32_e32 v137, v157, v137
	v_div_scale_f32 v157, vcc, 1.0, v133, 1.0
	v_mul_f32_e32 v164, v157, v137
	v_fma_f32 v165, -v136, v164, v157
	v_fmac_f32_e32 v164, v165, v137
	v_fma_f32 v136, -v136, v164, v157
	v_div_fmas_f32 v136, v136, v137, v164
	v_div_fixup_f32 v133, v136, v133, 1.0
	v_div_scale_f32 v136, s[18:19], v132, v132, 1.0
	v_rcp_f32_e32 v137, v136
	s_nop 0
	v_fma_f32 v157, -v136, v137, 1.0
	v_fmac_f32_e32 v137, v157, v137
	v_div_scale_f32 v157, vcc, 1.0, v132, 1.0
	v_mul_f32_e32 v164, v157, v137
	v_fma_f32 v165, -v136, v164, v157
	v_fmac_f32_e32 v164, v165, v137
	v_fma_f32 v136, -v136, v164, v157
	v_div_fmas_f32 v136, v136, v137, v164
	v_div_fixup_f32 v132, v136, v132, 1.0
	v_lshl_add_u64 v[136:137], v[162:163], 2, s[20:21]
	global_store_dwordx4 v[136:137], v[128:131], off
	global_store_dwordx4 v[136:137], v[132:135], off offset:16

; __device__ __forceinline__ float sigmoidf_(float x) { return 1.0f / (1.0f + __expf(-x)); }
;     __device__ __forceinline__ void operator()(const f32x4 (&acc)[2][2][4][2], const pg8::Unit& u, int wr, int wc, int fr, int fq) const {
;     ...
;             EPI_BEGIN { const int c = col & 2047; const size_t off = (size_t)row * 2048 + c;
;                 if (grp == 0) { const f32x4 b0 = *(const f32x4*)(p0 + c), b1 = *(const f32x4*)(p0 + c + 4);
; #pragma unroll
;                     for (int e = 0; e < 4; ++e) { v0[e] = __expf(-0.6065306597126334f * sigmoidf_(v0[e] + b0[e])); v1[e] = __expf(-0.6065306597126334f * sigmoidf_(v1[e] + b1[e])); }
;                     *(f32x4*)(f0 + off) = v0; *(f32x4*)(f0 + off + 4) = v1;
.LBB0_1278:
	s_waitcnt lgkmcnt(0)
	s_nop 1
	v_mov_b32_e32 v130, v194
	v_mov_b32_e32 v131, v195
	v_mov_b32_e32 v132, v196
	v_mov_b32_e32 v133, v197
	v_mov_b32_e32 v134, v190
	v_mov_b32_e32 v135, v191
	v_mov_b32_e32 v136, v192
	v_mov_b32_e32 v137, v193
	v_add_f32_e32 v128, v60, v134
	v_mul_f32_e32 v128, 0xbfb8aa3b, v128
	v_exp_f32_e32 v128, v128
	s_nop 0
	v_add_f32_e32 v128, 1.0, v128
	v_div_scale_f32 v129, s[18:19], v128, v128, 1.0
	v_rcp_f32_e32 v134, v129
	s_nop 0
	v_fma_f32 v157, -v129, v134, 1.0
	v_fmac_f32_e32 v134, v157, v134
	v_div_scale_f32 v157, vcc, 1.0, v128, 1.0
	v_mul_f32_e32 v164, v157, v134
	v_fma_f32 v165, -v129, v164, v157
	v_fmac_f32_e32 v164, v165, v134
	v_fma_f32 v129, -v129, v164, v157
	v_div_fmas_f32 v129, v129, v134, v164
	v_div_fixup_f32 v128, v129, v128, 1.0
	v_add_f32_e32 v129, v56, v130
	v_mul_f32_e32 v129, 0xbfb8aa3b, v129
	v_exp_f32_e32 v129, v129
	v_mul_f32_e32 v128, 0xbf1b4598, v128
	v_mul_f32_e32 v128, 0x3fb8aa3b, v128
	v_exp_f32_e32 v128, v128
	v_add_f32_e32 v129, 1.0, v129
	v_div_scale_f32 v130, s[18:19], v129, v129, 1.0
	v_rcp_f32_e32 v134, v130
	s_nop 0
	v_fma_f32 v157, -v130, v134, 1.0
	v_fmac_f32_e32 v134, v157, v134
	v_div_scale_f32 v157, vcc, 1.0, v129, 1.0
	v_mul_f32_e32 v164, v157, v134
	v_fma_f32 v165, -v130, v164, v157
	v_fmac_f32_e32 v164, v165, v134
	v_fma_f32 v130, -v130, v164, v157
	v_div_fmas_f32 v130, v130, v134, v164
	v_div_fixup_f32 v129, v130, v129, 1.0
	v_mul_f32_e32 v129, 0xbf1b4598, v129
	v_mul_f32_e32 v129, 0x3fb8aa3b, v129
	v_exp_f32_e32 v134, v129
	v_add_f32_e32 v129, v61, v135
	v_mul_f32_e32 v129, 0xbfb8aa3b, v129
	v_exp_f32_e32 v129, v129
	s_nop 0
	v_add_f32_e32 v129, 1.0, v129
	v_div_scale_f32 v130, s[18:19], v129, v129, 1.0
	v_rcp_f32_e32 v135, v130
	s_nop 0
	v_fma_f32 v157, -v130, v135, 1.0
	v_fmac_f32_e32 v135, v157, v135
	v_div_scale_f32 v157, vcc, 1.0, v129, 1.0
	v_mul_f32_e32 v164, v157, v135
	v_fma_f32 v165, -v130, v164, v157
	v_fmac_f32_e32 v164, v165, v135
	v_fma_f32 v130, -v130, v164, v157
	v_div_fmas_f32 v130, v130, v135, v164
	v_div_fixup_f32 v129, v130, v129, 1.0
	v_add_f32_e32 v130, v57, v131
	v_mul_f32_e32 v130, 0xbfb8aa3b, v130
	v_exp_f32_e32 v130, v130
	v_mul_f32_e32 v129, 0xbf1b4598, v129
	v_mul_f32_e32 v129, 0x3fb8aa3b, v129
	v_exp_f32_e32 v129, v129
	v_add_f32_e32 v130, 1.0, v130
	v_div_scale_f32 v131, s[18:19], v130, v130, 1.0
	v_rcp_f32_e32 v135, v131
	s_nop 0
	v_fma_f32 v157, -v131, v135, 1.0
	v_fmac_f32_e32 v135, v157, v135
	v_div_scale_f32 v157, vcc, 1.0, v130, 1.0
	v_mul_f32_e32 v164, v157, v135
	v_fma_f32 v165, -v131, v164, v157
	v_fmac_f32_e32 v164, v165, v135
	v_fma_f32 v131, -v131, v164, v157
	v_div_fmas_f32 v131, v131, v135, v164
	v_div_fixup_f32 v130, v131, v130, 1.0
	v_mul_f32_e32 v130, 0xbf1b4598, v130
	v_mul_f32_e32 v130, 0x3fb8aa3b, v130
	v_exp_f32_e32 v135, v130
	v_add_f32_e32 v130, v62, v136
	v_mul_f32_e32 v130, 0xbfb8aa3b, v130
	v_exp_f32_e32 v130, v130
	s_nop 0
	v_add_f32_e32 v130, 1.0, v130
	v_div_scale_f32 v131, s[18:19], v130, v130, 1.0
	v_rcp_f32_e32 v136, v131
	s_nop 0
	v_fma_f32 v157, -v131, v136, 1.0
	v_fmac_f32_e32 v136, v157, v136
	v_div_scale_f32 v157, vcc, 1.0, v130, 1.0
	v_mul_f32_e32 v164, v157, v136
	v_fma_f32 v165, -v131, v164, v157
	v_fmac_f32_e32 v164, v165, v136
	v_fma_f32 v131, -v131, v164, v157
	v_div_fmas_f32 v131, v131, v136, v164
	v_div_fixup_f32 v130, v131, v130, 1.0
	v_add_f32_e32 v131, v58, v132
	v_mul_f32_e32 v131, 0xbfb8aa3b, v131
	v_exp_f32_e32 v131, v131
	v_mul_f32_e32 v130, 0xbf1b4598, v130
	v_mul_f32_e32 v130, 0x3fb8aa3b, v130
	v_exp_f32_e32 v130, v130
	v_add_f32_e32 v131, 1.0, v131
	v_div_scale_f32 v132, s[18:19], v131, v131, 1.0
	v_rcp_f32_e32 v136, v132
	s_nop 0
	v_fma_f32 v157, -v132, v136, 1.0
	v_fmac_f32_e32 v136, v157, v136
	v_div_scale_f32 v157, vcc, 1.0, v131, 1.0
	v_mul_f32_e32 v164, v157, v136
	v_fma_f32 v165, -v132, v164, v157
	v_fmac_f32_e32 v164, v165, v136
	v_fma_f32 v132, -v132, v164, v157
	v_div_fmas_f32 v132, v132, v136, v164
	v_div_fixup_f32 v131, v132, v131, 1.0
	v_mul_f32_e32 v131, 0xbf1b4598, v131
	v_mul_f32_e32 v131, 0x3fb8aa3b, v131
	v_exp_f32_e32 v136, v131
	v_add_f32_e32 v131, v63, v137
	v_mul_f32_e32 v131, 0xbfb8aa3b, v131
	v_exp_f32_e32 v131, v131
	s_nop 0
	v_add_f32_e32 v131, 1.0, v131
	v_div_scale_f32 v132, s[18:19], v131, v131, 1.0
	v_rcp_f32_e32 v137, v132
	s_nop 0
	v_fma_f32 v157, -v132, v137, 1.0
	v_fmac_f32_e32 v137, v157, v137
	v_div_scale_f32 v157, vcc, 1.0, v131, 1.0
	v_mul_f32_e32 v164, v157, v137
	v_fma_f32 v165, -v132, v164, v157
	v_fmac_f32_e32 v164, v165, v137
	v_fma_f32 v132, -v132, v164, v157
	v_div_fmas_f32 v132, v132, v137, v164
	v_div_fixup_f32 v131, v132, v131, 1.0
	v_add_f32_e32 v132, v59, v133
	v_mul_f32_e32 v132, 0xbfb8aa3b, v132
	v_exp_f32_e32 v132, v132
	v_mul_f32_e32 v131, 0xbf1b4598, v131
	v_mul_f32_e32 v131, 0x3fb8aa3b, v131
	v_exp_f32_e32 v131, v131
	v_add_f32_e32 v132, 1.0, v132
	v_div_scale_f32 v133, s[18:19], v132, v132, 1.0
	v_rcp_f32_e32 v137, v133
	s_nop 0
	v_fma_f32 v157, -v133, v137, 1.0
	v_fmac_f32_e32 v137, v157, v137
	v_div_scale_f32 v157, vcc, 1.0, v132, 1.0
	v_mul_f32_e32 v164, v157, v137
	v_fma_f32 v165, -v133, v164, v157
	v_fmac_f32_e32 v164, v165, v137
	v_fma_f32 v133, -v133, v164, v157
	v_div_fmas_f32 v133, v133, v137, v164
	v_div_fixup_f32 v132, v133, v132, 1.0
	v_mul_f32_e32 v132, 0xbf1b4598, v132
	v_mul_f32_e32 v132, 0x3fb8aa3b, v132
	v_exp_f32_e32 v137, v132
	v_lshl_add_u64 v[132:133], v[162:163], 2, s[50:51]
	global_store_dwordx4 v[132:133], v[128:131], off
	global_store_dwordx4 v[132:133], v[134:137], off offset:16
	s_and_b64 vcc, exec, s[46:47]
	s_mov_b64 s[18:19], -1
	s_cbranch_vccnz .LBB0_1030

; __device__ __forceinline__ float sigmoidf_(float x) { return 1.0f / (1.0f + __expf(-x)); }
;     __device__ __forceinline__ void operator()(const f32x4 (&acc)[2][2][4][2], const pg8::Unit& u, int wr, int wc, int fr, int fq) const {
;     ...
;                 } else if (grp == 1) { const f32x4 b0 = *(const f32x4*)(p1 + c), b1 = *(const f32x4*)(p1 + c + 4);
; #pragma unroll
;                     for (int e = 0; e < 4; ++e) { v0[e] = sigmoidf_(v0[e] + b0[e]); v1[e] = sigmoidf_(v1[e] + b1[e]); }
;                     *(f32x4*)(f1 + off) = v0; *(f32x4*)(f1 + off + 4) = v1;
.LBB0_1281:
	s_andn2_b64 vcc, exec, s[18:19]
	s_cbranch_vccnz .LBB0_1283
	s_waitcnt lgkmcnt(0)
	s_nop 1
	v_mov_b32_e32 v130, v236
	v_mov_b32_e32 v131, v237
	v_mov_b32_e32 v132, v238
	v_mov_b32_e32 v133, v239
	v_mov_b32_e32 v134, v232
	v_mov_b32_e32 v135, v233
	v_mov_b32_e32 v136, v234
	v_mov_b32_e32 v137, v235
	v_add_f32_e32 v129, v48, v130
	v_add_f32_e32 v130, v49, v131
	v_add_f32_e32 v131, v50, v132
	v_mul_f32_e32 v129, 0xbfb8aa3b, v129
	v_mul_f32_e32 v130, 0xbfb8aa3b, v130
	v_mul_f32_e32 v131, 0xbfb8aa3b, v131
	v_add_f32_e32 v128, v52, v134
	v_exp_f32_e32 v134, v129
	v_add_f32_e32 v129, v53, v135
	v_exp_f32_e32 v135, v130
	v_add_f32_e32 v130, v54, v136
	v_exp_f32_e32 v136, v131
	v_add_f32_e32 v131, v55, v137
	v_mul_f32_e32 v130, 0xbfb8aa3b, v130
	v_mul_f32_e32 v131, 0xbfb8aa3b, v131
	v_exp_f32_e32 v130, v130
	v_exp_f32_e32 v131, v131
	v_mul_f32_e32 v128, 0xbfb8aa3b, v128
	v_mul_f32_e32 v129, 0xbfb8aa3b, v129
	v_exp_f32_e32 v128, v128
	v_pk_add_f32 v[130:131], v[130:131], 1.0 op_sel_hi:[1,0]
	v_exp_f32_e32 v129, v129
	v_div_scale_f32 v132, s[18:19], v131, v131, 1.0
	v_rcp_f32_e32 v137, v132
	v_pk_add_f32 v[128:129], v[128:129], 1.0 op_sel_hi:[1,0]
	v_fma_f32 v157, -v132, v137, 1.0
	v_fmac_f32_e32 v137, v157, v137
	v_div_scale_f32 v157, vcc, 1.0, v131, 1.0
	v_mul_f32_e32 v162, v157, v137
	v_fma_f32 v163, -v132, v162, v157
	v_fmac_f32_e32 v162, v163, v137
	v_fma_f32 v132, -v132, v162, v157
	v_div_fmas_f32 v132, v132, v137, v162
	v_div_fixup_f32 v131, v132, v131, 1.0
	v_div_scale_f32 v132, s[18:19], v130, v130, 1.0
	v_rcp_f32_e32 v137, v132
	s_nop 0
	v_fma_f32 v157, -v132, v137, 1.0
	v_fmac_f32_e32 v137, v157, v137
	v_div_scale_f32 v157, vcc, 1.0, v130, 1.0
	v_mul_f32_e32 v162, v157, v137
	v_fma_f32 v163, -v132, v162, v157
	v_fmac_f32_e32 v162, v163, v137
	v_fma_f32 v132, -v132, v162, v157
	v_div_fmas_f32 v132, v132, v137, v162
	v_div_fixup_f32 v130, v132, v130, 1.0
	v_div_scale_f32 v132, s[18:19], v129, v129, 1.0
	v_rcp_f32_e32 v137, v132
	s_nop 0
	v_fma_f32 v157, -v132, v137, 1.0
	v_fmac_f32_e32 v137, v157, v137
	v_div_scale_f32 v157, vcc, 1.0, v129, 1.0
	v_mul_f32_e32 v162, v157, v137
	v_fma_f32 v163, -v132, v162, v157
	v_fmac_f32_e32 v162, v163, v137
	v_fma_f32 v132, -v132, v162, v157
	v_div_fmas_f32 v132, v132, v137, v162
	v_div_fixup_f32 v129, v132, v129, 1.0
	v_div_scale_f32 v132, s[18:19], v128, v128, 1.0
	v_rcp_f32_e32 v137, v132
	s_nop 0
	v_fma_f32 v157, -v132, v137, 1.0
	v_fmac_f32_e32 v137, v157, v137
	v_div_scale_f32 v157, vcc, 1.0, v128, 1.0
	v_mul_f32_e32 v162, v157, v137
	v_fma_f32 v163, -v132, v162, v157
	v_fmac_f32_e32 v162, v163, v137
	v_fma_f32 v132, -v132, v162, v157
	v_div_fmas_f32 v132, v132, v137, v162
	v_div_fixup_f32 v128, v132, v128, 1.0
	v_add_f32_e32 v132, v51, v133
	v_mul_f32_e32 v132, 0xbfb8aa3b, v132
	v_exp_f32_e32 v137, v132
	v_pk_add_f32 v[132:133], v[134:135], 1.0 op_sel_hi:[1,0]
	v_pk_add_f32 v[134:135], v[136:137], 1.0 op_sel_hi:[1,0]
	s_nop 0
	v_div_scale_f32 v136, s[18:19], v135, v135, 1.0
	v_rcp_f32_e32 v137, v136
	s_nop 0
	v_fma_f32 v157, -v136, v137, 1.0
	v_fmac_f32_e32 v137, v157, v137
	v_div_scale_f32 v157, vcc, 1.0, v135, 1.0
	v_mul_f32_e32 v162, v157, v137
	v_fma_f32 v163, -v136, v162, v157
	v_fmac_f32_e32 v162, v163, v137
	v_fma_f32 v136, -v136, v162, v157
	v_div_fmas_f32 v136, v136, v137, v162
	v_div_fixup_f32 v135, v136, v135, 1.0
	v_div_scale_f32 v136, s[18:19], v134, v134, 1.0
	v_rcp_f32_e32 v137, v136
	s_nop 0
	v_fma_f32 v157, -v136, v137, 1.0
	v_fmac_f32_e32 v137, v157, v137
	v_div_scale_f32 v157, vcc, 1.0, v134, 1.0
	v_mul_f32_e32 v162, v157, v137
	v_fma_f32 v163, -v136, v162, v157
	v_fmac_f32_e32 v162, v163, v137
	v_fma_f32 v136, -v136, v162, v157
	v_div_fmas_f32 v136, v136, v137, v162
	v_div_fixup_f32 v134, v136, v134, 1.0
	v_div_scale_f32 v136, s[18:19], v133, v133, 1.0
	v_rcp_f32_e32 v137, v136
	s_nop 0
	v_fma_f32 v157, -v136, v137, 1.0
	v_fmac_f32_e32 v137, v157, v137
	v_div_scale_f32 v157, vcc, 1.0, v133, 1.0
	v_mul_f32_e32 v162, v157, v137
	v_fma_f32 v163, -v136, v162, v157
	v_fmac_f32_e32 v162, v163, v137
	v_fma_f32 v136, -v136, v162, v157
	v_div_fmas_f32 v136, v136, v137, v162
	v_div_fixup_f32 v133, v136, v133, 1.0
	v_div_scale_f32 v136, s[18:19], v132, v132, 1.0
	v_rcp_f32_e32 v137, v136
	s_nop 0
	v_fma_f32 v157, -v136, v137, 1.0
	v_fmac_f32_e32 v137, v157, v137
	v_div_scale_f32 v157, vcc, 1.0, v132, 1.0
	v_mul_f32_e32 v162, v157, v137
	v_fma_f32 v163, -v136, v162, v157
	v_fmac_f32_e32 v162, v163, v137
	v_fma_f32 v136, -v136, v162, v157
	v_div_fmas_f32 v136, v136, v137, v162
	v_div_fixup_f32 v132, v136, v132, 1.0
	v_lshl_add_u64 v[136:137], v[160:161], 0, v[180:181]
	v_lshl_add_u64 v[136:137], v[136:137], 2, s[20:21]
	global_store_dwordx4 v[136:137], v[128:131], off offset:512
	global_store_dwordx4 v[136:137], v[132:135], off offset:528

; __device__ __forceinline__ float sigmoidf_(float x) { return 1.0f / (1.0f + __expf(-x)); }
;     __device__ __forceinline__ void operator()(const f32x4 (&acc)[2][2][4][2], const pg8::Unit& u, int wr, int wc, int fr, int fq) const {
;     ...
;                 } else if (grp == 1) { const f32x4 b0 = *(const f32x4*)(p1 + c), b1 = *(const f32x4*)(p1 + c + 4);
; #pragma unroll
;                     for (int e = 0; e < 4; ++e) { v0[e] = sigmoidf_(v0[e] + b0[e]); v1[e] = sigmoidf_(v1[e] + b1[e]); }
;                     *(f32x4*)(f1 + off) = v0; *(f32x4*)(f1 + off + 4) = v1;
.LBB0_1286:
	s_andn2_b64 vcc, exec, s[18:19]
	s_cbranch_vccnz .LBB0_1288
	s_waitcnt lgkmcnt(0)
	s_nop 1
	v_mov_b32_e32 v130, v228
	v_mov_b32_e32 v131, v229
	v_mov_b32_e32 v132, v230
	v_mov_b32_e32 v133, v231
	v_mov_b32_e32 v134, v224
	v_mov_b32_e32 v135, v225
	v_mov_b32_e32 v136, v226
	v_mov_b32_e32 v137, v227
	v_add_f32_e32 v129, v40, v130
	v_add_f32_e32 v130, v41, v131
	v_add_f32_e32 v131, v42, v132
	v_mul_f32_e32 v129, 0xbfb8aa3b, v129
	v_mul_f32_e32 v130, 0xbfb8aa3b, v130
	v_mul_f32_e32 v131, 0xbfb8aa3b, v131
	v_add_f32_e32 v128, v44, v134
	v_exp_f32_e32 v134, v129
	v_add_f32_e32 v129, v45, v135
	v_exp_f32_e32 v135, v130
	v_add_f32_e32 v130, v46, v136
	v_exp_f32_e32 v136, v131
	v_add_f32_e32 v131, v47, v137
	v_mul_f32_e32 v130, 0xbfb8aa3b, v130
	v_mul_f32_e32 v131, 0xbfb8aa3b, v131
	v_exp_f32_e32 v130, v130
	v_exp_f32_e32 v131, v131
	v_mul_f32_e32 v128, 0xbfb8aa3b, v128
	v_mul_f32_e32 v129, 0xbfb8aa3b, v129
	v_exp_f32_e32 v128, v128
	v_pk_add_f32 v[130:131], v[130:131], 1.0 op_sel_hi:[1,0]
	v_exp_f32_e32 v129, v129
	v_div_scale_f32 v132, s[18:19], v131, v131, 1.0
	v_rcp_f32_e32 v137, v132
	v_pk_add_f32 v[128:129], v[128:129], 1.0 op_sel_hi:[1,0]
	v_fma_f32 v157, -v132, v137, 1.0
	v_fmac_f32_e32 v137, v157, v137
	v_div_scale_f32 v157, vcc, 1.0, v131, 1.0
	v_mul_f32_e32 v164, v157, v137
	v_fma_f32 v165, -v132, v164, v157
	v_fmac_f32_e32 v164, v165, v137
	v_fma_f32 v132, -v132, v164, v157
	v_div_fmas_f32 v132, v132, v137, v164
	v_div_fixup_f32 v131, v132, v131, 1.0
	v_div_scale_f32 v132, s[18:19], v130, v130, 1.0
	v_rcp_f32_e32 v137, v132
	s_nop 0
	v_fma_f32 v157, -v132, v137, 1.0
	v_fmac_f32_e32 v137, v157, v137
	v_div_scale_f32 v157, vcc, 1.0, v130, 1.0
	v_mul_f32_e32 v164, v157, v137
	v_fma_f32 v165, -v132, v164, v157
	v_fmac_f32_e32 v164, v165, v137
	v_fma_f32 v132, -v132, v164, v157
	v_div_fmas_f32 v132, v132, v137, v164
	v_div_fixup_f32 v130, v132, v130, 1.0
	v_div_scale_f32 v132, s[18:19], v129, v129, 1.0
	v_rcp_f32_e32 v137, v132
	s_nop 0
	v_fma_f32 v157, -v132, v137, 1.0
	v_fmac_f32_e32 v137, v157, v137
	v_div_scale_f32 v157, vcc, 1.0, v129, 1.0
	v_mul_f32_e32 v164, v157, v137
	v_fma_f32 v165, -v132, v164, v157
	v_fmac_f32_e32 v164, v165, v137
	v_fma_f32 v132, -v132, v164, v157
	v_div_fmas_f32 v132, v132, v137, v164
	v_div_fixup_f32 v129, v132, v129, 1.0
	v_div_scale_f32 v132, s[18:19], v128, v128, 1.0
	v_rcp_f32_e32 v137, v132
	s_nop 0
	v_fma_f32 v157, -v132, v137, 1.0
	v_fmac_f32_e32 v137, v157, v137
	v_div_scale_f32 v157, vcc, 1.0, v128, 1.0
	v_mul_f32_e32 v164, v157, v137
	v_fma_f32 v165, -v132, v164, v157
	v_fmac_f32_e32 v164, v165, v137
	v_fma_f32 v132, -v132, v164, v157
	v_div_fmas_f32 v132, v132, v137, v164
	v_div_fixup_f32 v128, v132, v128, 1.0
	v_add_f32_e32 v132, v43, v133
	v_mul_f32_e32 v132, 0xbfb8aa3b, v132
	v_exp_f32_e32 v137, v132
	v_pk_add_f32 v[132:133], v[134:135], 1.0 op_sel_hi:[1,0]
	v_pk_add_f32 v[134:135], v[136:137], 1.0 op_sel_hi:[1,0]
	s_nop 0
	v_div_scale_f32 v136, s[18:19], v135, v135, 1.0
	v_rcp_f32_e32 v137, v136
	s_nop 0
	v_fma_f32 v157, -v136, v137, 1.0
	v_fmac_f32_e32 v137, v157, v137
	v_div_scale_f32 v157, vcc, 1.0, v135, 1.0
	v_mul_f32_e32 v164, v157, v137
	v_fma_f32 v165, -v136, v164, v157
	v_fmac_f32_e32 v164, v165, v137
	v_fma_f32 v136, -v136, v164, v157
	v_div_fmas_f32 v136, v136, v137, v164
	v_div_fixup_f32 v135, v136, v135, 1.0
	v_div_scale_f32 v136, s[18:19], v134, v134, 1.0
	v_rcp_f32_e32 v137, v136
	s_nop 0
	v_fma_f32 v157, -v136, v137, 1.0
	v_fmac_f32_e32 v137, v157, v137
	v_div_scale_f32 v157, vcc, 1.0, v134, 1.0
	v_mul_f32_e32 v164, v157, v137
	v_fma_f32 v165, -v136, v164, v157
	v_fmac_f32_e32 v164, v165, v137
	v_fma_f32 v136, -v136, v164, v157
	v_div_fmas_f32 v136, v136, v137, v164
	v_div_fixup_f32 v134, v136, v134, 1.0
	v_div_scale_f32 v136, s[18:19], v133, v133, 1.0
	v_rcp_f32_e32 v137, v136
	s_nop 0
	v_fma_f32 v157, -v136, v137, 1.0
	v_fmac_f32_e32 v137, v157, v137
	v_div_scale_f32 v157, vcc, 1.0, v133, 1.0
	v_mul_f32_e32 v164, v157, v137
	v_fma_f32 v165, -v136, v164, v157
	v_fmac_f32_e32 v164, v165, v137
	v_fma_f32 v136, -v136, v164, v157
	v_div_fmas_f32 v136, v136, v137, v164
	v_div_fixup_f32 v133, v136, v133, 1.0
	v_div_scale_f32 v136, s[18:19], v132, v132, 1.0
	v_rcp_f32_e32 v137, v136
	s_nop 0
	v_fma_f32 v157, -v136, v137, 1.0
	v_fmac_f32_e32 v137, v157, v137
	v_div_scale_f32 v157, vcc, 1.0, v132, 1.0
	v_mul_f32_e32 v164, v157, v137
	v_fma_f32 v165, -v136, v164, v157
	v_fmac_f32_e32 v164, v165, v137
	v_fma_f32 v136, -v136, v164, v157
	v_div_fmas_f32 v136, v136, v137, v164
	v_div_fixup_f32 v132, v136, v132, 1.0
	v_lshl_add_u64 v[136:137], v[162:163], 2, s[20:21]
	global_store_dwordx4 v[136:137], v[128:131], off
	global_store_dwordx4 v[136:137], v[132:135], off offset:16

; __device__ __forceinline__ float sigmoidf_(float x) { return 1.0f / (1.0f + __expf(-x)); }
;     __device__ __forceinline__ void operator()(const f32x4 (&acc)[2][2][4][2], const pg8::Unit& u, int wr, int wc, int fr, int fq) const {
;     ...
;             EPI_BEGIN { const int c = col & 2047; const size_t off = (size_t)row * 2048 + c;
;                 if (grp == 0) { const f32x4 b0 = *(const f32x4*)(p0 + c), b1 = *(const f32x4*)(p0 + c + 4);
; #pragma unroll
;                     for (int e = 0; e < 4; ++e) { v0[e] = __expf(-0.6065306597126334f * sigmoidf_(v0[e] + b0[e])); v1[e] = __expf(-0.6065306597126334f * sigmoidf_(v1[e] + b1[e])); }
;                     *(f32x4*)(f0 + off) = v0; *(f32x4*)(f0 + off + 4) = v1;
.LBB0_1289:
	s_waitcnt lgkmcnt(0)
	s_nop 1
	v_mov_b32_e32 v130, v194
	v_mov_b32_e32 v131, v195
	v_mov_b32_e32 v132, v196
	v_mov_b32_e32 v133, v197
	v_mov_b32_e32 v134, v190
	v_mov_b32_e32 v135, v191
	v_mov_b32_e32 v136, v192
	v_mov_b32_e32 v137, v193
	v_add_f32_e32 v128, v44, v134
	v_mul_f32_e32 v128, 0xbfb8aa3b, v128
	v_exp_f32_e32 v128, v128
	s_nop 0
	v_add_f32_e32 v128, 1.0, v128
	v_div_scale_f32 v129, s[18:19], v128, v128, 1.0
	v_rcp_f32_e32 v134, v129
	s_nop 0
	v_fma_f32 v157, -v129, v134, 1.0
	v_fmac_f32_e32 v134, v157, v134
	v_div_scale_f32 v157, vcc, 1.0, v128, 1.0
	v_mul_f32_e32 v164, v157, v134
	v_fma_f32 v165, -v129, v164, v157
	v_fmac_f32_e32 v164, v165, v134
	v_fma_f32 v129, -v129, v164, v157
	v_div_fmas_f32 v129, v129, v134, v164
	v_div_fixup_f32 v128, v129, v128, 1.0
	v_add_f32_e32 v129, v40, v130
	v_mul_f32_e32 v129, 0xbfb8aa3b, v129
	v_exp_f32_e32 v129, v129
	v_mul_f32_e32 v128, 0xbf1b4598, v128
	v_mul_f32_e32 v128, 0x3fb8aa3b, v128
	v_exp_f32_e32 v128, v128
	v_add_f32_e32 v129, 1.0, v129
	v_div_scale_f32 v130, s[18:19], v129, v129, 1.0
	v_rcp_f32_e32 v134, v130
	s_nop 0
	v_fma_f32 v157, -v130, v134, 1.0
	v_fmac_f32_e32 v134, v157, v134
	v_div_scale_f32 v157, vcc, 1.0, v129, 1.0
	v_mul_f32_e32 v164, v157, v134
	v_fma_f32 v165, -v130, v164, v157
	v_fmac_f32_e32 v164, v165, v134
	v_fma_f32 v130, -v130, v164, v157
	v_div_fmas_f32 v130, v130, v134, v164
	v_div_fixup_f32 v129, v130, v129, 1.0
	v_mul_f32_e32 v129, 0xbf1b4598, v129
	v_mul_f32_e32 v129, 0x3fb8aa3b, v129
	v_exp_f32_e32 v134, v129
	v_add_f32_e32 v129, v45, v135
	v_mul_f32_e32 v129, 0xbfb8aa3b, v129
	v_exp_f32_e32 v129, v129
	s_nop 0
	v_add_f32_e32 v129, 1.0, v129
	v_div_scale_f32 v130, s[18:19], v129, v129, 1.0
	v_rcp_f32_e32 v135, v130
	s_nop 0
	v_fma_f32 v157, -v130, v135, 1.0
	v_fmac_f32_e32 v135, v157, v135
	v_div_scale_f32 v157, vcc, 1.0, v129, 1.0
	v_mul_f32_e32 v164, v157, v135
	v_fma_f32 v165, -v130, v164, v157
	v_fmac_f32_e32 v164, v165, v135
	v_fma_f32 v130, -v130, v164, v157
	v_div_fmas_f32 v130, v130, v135, v164
	v_div_fixup_f32 v129, v130, v129, 1.0
	v_add_f32_e32 v130, v41, v131
	v_mul_f32_e32 v130, 0xbfb8aa3b, v130
	v_exp_f32_e32 v130, v130
	v_mul_f32_e32 v129, 0xbf1b4598, v129
	v_mul_f32_e32 v129, 0x3fb8aa3b, v129
	v_exp_f32_e32 v129, v129
	v_add_f32_e32 v130, 1.0, v130
	v_div_scale_f32 v131, s[18:19], v130, v130, 1.0
	v_rcp_f32_e32 v135, v131
	s_nop 0
	v_fma_f32 v157, -v131, v135, 1.0
	v_fmac_f32_e32 v135, v157, v135
	v_div_scale_f32 v157, vcc, 1.0, v130, 1.0
	v_mul_f32_e32 v164, v157, v135
	v_fma_f32 v165, -v131, v164, v157
	v_fmac_f32_e32 v164, v165, v135
	v_fma_f32 v131, -v131, v164, v157
	v_div_fmas_f32 v131, v131, v135, v164
	v_div_fixup_f32 v130, v131, v130, 1.0
	v_mul_f32_e32 v130, 0xbf1b4598, v130
	v_mul_f32_e32 v130, 0x3fb8aa3b, v130
	v_exp_f32_e32 v135, v130
	v_add_f32_e32 v130, v46, v136
	v_mul_f32_e32 v130, 0xbfb8aa3b, v130
	v_exp_f32_e32 v130, v130
	s_nop 0
	v_add_f32_e32 v130, 1.0, v130
	v_div_scale_f32 v131, s[18:19], v130, v130, 1.0
	v_rcp_f32_e32 v136, v131
	s_nop 0
	v_fma_f32 v157, -v131, v136, 1.0
	v_fmac_f32_e32 v136, v157, v136
	v_div_scale_f32 v157, vcc, 1.0, v130, 1.0
	v_mul_f32_e32 v164, v157, v136
	v_fma_f32 v165, -v131, v164, v157
	v_fmac_f32_e32 v164, v165, v136
	v_fma_f32 v131, -v131, v164, v157
	v_div_fmas_f32 v131, v131, v136, v164
	v_div_fixup_f32 v130, v131, v130, 1.0
	v_add_f32_e32 v131, v42, v132
	v_mul_f32_e32 v131, 0xbfb8aa3b, v131
	v_exp_f32_e32 v131, v131
	v_mul_f32_e32 v130, 0xbf1b4598, v130
	v_mul_f32_e32 v130, 0x3fb8aa3b, v130
	v_exp_f32_e32 v130, v130
	v_add_f32_e32 v131, 1.0, v131
	v_div_scale_f32 v132, s[18:19], v131, v131, 1.0
	v_rcp_f32_e32 v136, v132
	s_nop 0
	v_fma_f32 v157, -v132, v136, 1.0
	v_fmac_f32_e32 v136, v157, v136
	v_div_scale_f32 v157, vcc, 1.0, v131, 1.0
	v_mul_f32_e32 v164, v157, v136
	v_fma_f32 v165, -v132, v164, v157
	v_fmac_f32_e32 v164, v165, v136
	v_fma_f32 v132, -v132, v164, v157
	v_div_fmas_f32 v132, v132, v136, v164
	v_div_fixup_f32 v131, v132, v131, 1.0
	v_mul_f32_e32 v131, 0xbf1b4598, v131
	v_mul_f32_e32 v131, 0x3fb8aa3b, v131
	v_exp_f32_e32 v136, v131
	v_add_f32_e32 v131, v47, v137
	v_mul_f32_e32 v131, 0xbfb8aa3b, v131
	v_exp_f32_e32 v131, v131
	s_nop 0
	v_add_f32_e32 v131, 1.0, v131
	v_div_scale_f32 v132, s[18:19], v131, v131, 1.0
	v_rcp_f32_e32 v137, v132
	s_nop 0
	v_fma_f32 v157, -v132, v137, 1.0
	v_fmac_f32_e32 v137, v157, v137
	v_div_scale_f32 v157, vcc, 1.0, v131, 1.0
	v_mul_f32_e32 v164, v157, v137
	v_fma_f32 v165, -v132, v164, v157
	v_fmac_f32_e32 v164, v165, v137
	v_fma_f32 v132, -v132, v164, v157
	v_div_fmas_f32 v132, v132, v137, v164
	v_div_fixup_f32 v131, v132, v131, 1.0
	v_add_f32_e32 v132, v43, v133
	v_mul_f32_e32 v132, 0xbfb8aa3b, v132
	v_exp_f32_e32 v132, v132
	v_mul_f32_e32 v131, 0xbf1b4598, v131
	v_mul_f32_e32 v131, 0x3fb8aa3b, v131
	v_exp_f32_e32 v131, v131
	v_add_f32_e32 v132, 1.0, v132
	v_div_scale_f32 v133, s[18:19], v132, v132, 1.0
	v_rcp_f32_e32 v137, v133
	s_nop 0
	v_fma_f32 v157, -v133, v137, 1.0
	v_fmac_f32_e32 v137, v157, v137
	v_div_scale_f32 v157, vcc, 1.0, v132, 1.0
	v_mul_f32_e32 v164, v157, v137
	v_fma_f32 v165, -v133, v164, v157
	v_fmac_f32_e32 v164, v165, v137
	v_fma_f32 v133, -v133, v164, v157
	v_div_fmas_f32 v133, v133, v137, v164
	v_div_fixup_f32 v132, v133, v132, 1.0
	v_mul_f32_e32 v132, 0xbf1b4598, v132
	v_mul_f32_e32 v132, 0x3fb8aa3b, v132
	v_exp_f32_e32 v137, v132
	v_lshl_add_u64 v[132:133], v[162:163], 2, s[50:51]
	global_store_dwordx4 v[132:133], v[128:131], off
	global_store_dwordx4 v[132:133], v[134:137], off offset:16
	s_and_b64 vcc, exec, s[46:47]
	s_mov_b64 s[18:19], -1
	s_cbranch_vccnz .LBB0_1035

; __device__ __forceinline__ float sigmoidf_(float x) { return 1.0f / (1.0f + __expf(-x)); }
;     __device__ __forceinline__ void operator()(const f32x4 (&acc)[2][2][4][2], const pg8::Unit& u, int wr, int wc, int fr, int fq) const {
;     ...
;                 } else if (grp == 1) { const f32x4 b0 = *(const f32x4*)(p1 + c), b1 = *(const f32x4*)(p1 + c + 4);
; #pragma unroll
;                     for (int e = 0; e < 4; ++e) { v0[e] = sigmoidf_(v0[e] + b0[e]); v1[e] = sigmoidf_(v1[e] + b1[e]); }
;                     *(f32x4*)(f1 + off) = v0; *(f32x4*)(f1 + off + 4) = v1;
.LBB0_1292:
	s_andn2_b64 vcc, exec, s[18:19]
	s_cbranch_vccnz .LBB0_1294
	s_waitcnt lgkmcnt(0)
	s_nop 1
	v_mov_b32_e32 v130, v236
	v_mov_b32_e32 v131, v237
	v_mov_b32_e32 v132, v238
	v_mov_b32_e32 v133, v239
	v_mov_b32_e32 v134, v232
	v_mov_b32_e32 v135, v233
	v_mov_b32_e32 v136, v234
	v_mov_b32_e32 v137, v235
	v_add_f32_e32 v129, v32, v130
	v_add_f32_e32 v130, v33, v131
	v_add_f32_e32 v131, v34, v132
	v_mul_f32_e32 v129, 0xbfb8aa3b, v129
	v_mul_f32_e32 v130, 0xbfb8aa3b, v130
	v_mul_f32_e32 v131, 0xbfb8aa3b, v131
	v_add_f32_e32 v128, v36, v134
	v_exp_f32_e32 v134, v129
	v_add_f32_e32 v129, v37, v135
	v_exp_f32_e32 v135, v130
	v_add_f32_e32 v130, v38, v136
	v_exp_f32_e32 v136, v131
	v_add_f32_e32 v131, v39, v137
	v_mul_f32_e32 v130, 0xbfb8aa3b, v130
	v_mul_f32_e32 v131, 0xbfb8aa3b, v131
	v_exp_f32_e32 v130, v130
	v_exp_f32_e32 v131, v131
	v_mul_f32_e32 v128, 0xbfb8aa3b, v128
	v_mul_f32_e32 v129, 0xbfb8aa3b, v129
	v_exp_f32_e32 v128, v128
	v_pk_add_f32 v[130:131], v[130:131], 1.0 op_sel_hi:[1,0]
	v_exp_f32_e32 v129, v129
	v_div_scale_f32 v132, s[18:19], v131, v131, 1.0
	v_rcp_f32_e32 v137, v132
	v_pk_add_f32 v[128:129], v[128:129], 1.0 op_sel_hi:[1,0]
	v_fma_f32 v157, -v132, v137, 1.0
	v_fmac_f32_e32 v137, v157, v137
	v_div_scale_f32 v157, vcc, 1.0, v131, 1.0
	v_mul_f32_e32 v162, v157, v137
	v_fma_f32 v163, -v132, v162, v157
	v_fmac_f32_e32 v162, v163, v137
	v_fma_f32 v132, -v132, v162, v157
	v_div_fmas_f32 v132, v132, v137, v162
	v_div_fixup_f32 v131, v132, v131, 1.0
	v_div_scale_f32 v132, s[18:19], v130, v130, 1.0
	v_rcp_f32_e32 v137, v132
	s_nop 0
	v_fma_f32 v157, -v132, v137, 1.0
	v_fmac_f32_e32 v137, v157, v137
	v_div_scale_f32 v157, vcc, 1.0, v130, 1.0
	v_mul_f32_e32 v162, v157, v137
	v_fma_f32 v163, -v132, v162, v157
	v_fmac_f32_e32 v162, v163, v137
	v_fma_f32 v132, -v132, v162, v157
	v_div_fmas_f32 v132, v132, v137, v162
	v_div_fixup_f32 v130, v132, v130, 1.0
	v_div_scale_f32 v132, s[18:19], v129, v129, 1.0
	v_rcp_f32_e32 v137, v132
	s_nop 0
	v_fma_f32 v157, -v132, v137, 1.0
	v_fmac_f32_e32 v137, v157, v137
	v_div_scale_f32 v157, vcc, 1.0, v129, 1.0
	v_mul_f32_e32 v162, v157, v137
	v_fma_f32 v163, -v132, v162, v157
	v_fmac_f32_e32 v162, v163, v137
	v_fma_f32 v132, -v132, v162, v157
	v_div_fmas_f32 v132, v132, v137, v162
	v_div_fixup_f32 v129, v132, v129, 1.0
	v_div_scale_f32 v132, s[18:19], v128, v128, 1.0
	v_rcp_f32_e32 v137, v132
	s_nop 0
	v_fma_f32 v157, -v132, v137, 1.0
	v_fmac_f32_e32 v137, v157, v137
	v_div_scale_f32 v157, vcc, 1.0, v128, 1.0
	v_mul_f32_e32 v162, v157, v137
	v_fma_f32 v163, -v132, v162, v157
	v_fmac_f32_e32 v162, v163, v137
	v_fma_f32 v132, -v132, v162, v157
	v_div_fmas_f32 v132, v132, v137, v162
	v_div_fixup_f32 v128, v132, v128, 1.0
	v_add_f32_e32 v132, v35, v133
	v_mul_f32_e32 v132, 0xbfb8aa3b, v132
	v_exp_f32_e32 v137, v132
	v_pk_add_f32 v[132:133], v[134:135], 1.0 op_sel_hi:[1,0]
	v_pk_add_f32 v[134:135], v[136:137], 1.0 op_sel_hi:[1,0]
	s_nop 0
	v_div_scale_f32 v136, s[18:19], v135, v135, 1.0
	v_rcp_f32_e32 v137, v136
	s_nop 0
	v_fma_f32 v157, -v136, v137, 1.0
	v_fmac_f32_e32 v137, v157, v137
	v_div_scale_f32 v157, vcc, 1.0, v135, 1.0
	v_mul_f32_e32 v162, v157, v137
	v_fma_f32 v163, -v136, v162, v157
	v_fmac_f32_e32 v162, v163, v137
	v_fma_f32 v136, -v136, v162, v157
	v_div_fmas_f32 v136, v136, v137, v162
	v_div_fixup_f32 v135, v136, v135, 1.0
	v_div_scale_f32 v136, s[18:19], v134, v134, 1.0
	v_rcp_f32_e32 v137, v136
	s_nop 0
	v_fma_f32 v157, -v136, v137, 1.0
	v_fmac_f32_e32 v137, v157, v137
	v_div_scale_f32 v157, vcc, 1.0, v134, 1.0
	v_mul_f32_e32 v162, v157, v137
	v_fma_f32 v163, -v136, v162, v157
	v_fmac_f32_e32 v162, v163, v137
	v_fma_f32 v136, -v136, v162, v157
	v_div_fmas_f32 v136, v136, v137, v162
	v_div_fixup_f32 v134, v136, v134, 1.0
	v_div_scale_f32 v136, s[18:19], v133, v133, 1.0
	v_rcp_f32_e32 v137, v136
	s_nop 0
	v_fma_f32 v157, -v136, v137, 1.0
	v_fmac_f32_e32 v137, v157, v137
	v_div_scale_f32 v157, vcc, 1.0, v133, 1.0
	v_mul_f32_e32 v162, v157, v137
	v_fma_f32 v163, -v136, v162, v157
	v_fmac_f32_e32 v162, v163, v137
	v_fma_f32 v136, -v136, v162, v157
	v_div_fmas_f32 v136, v136, v137, v162
	v_div_fixup_f32 v133, v136, v133, 1.0
	v_div_scale_f32 v136, s[18:19], v132, v132, 1.0
	v_rcp_f32_e32 v137, v136
	s_nop 0
	v_fma_f32 v157, -v136, v137, 1.0
	v_fmac_f32_e32 v137, v157, v137
	v_div_scale_f32 v157, vcc, 1.0, v132, 1.0
	v_mul_f32_e32 v162, v157, v137
	v_fma_f32 v163, -v136, v162, v157
	v_fmac_f32_e32 v162, v163, v137
	v_fma_f32 v136, -v136, v162, v157
	v_div_fmas_f32 v136, v136, v137, v162
	v_div_fixup_f32 v132, v136, v132, 1.0
	v_lshl_add_u64 v[136:137], v[160:161], 0, v[180:181]
	v_lshl_add_u64 v[136:137], v[136:137], 2, s[20:21]
	global_store_dwordx4 v[136:137], v[128:131], off offset:512
	global_store_dwordx4 v[136:137], v[132:135], off offset:528

; __device__ __forceinline__ float sigmoidf_(float x) { return 1.0f / (1.0f + __expf(-x)); }
;     __device__ __forceinline__ void operator()(const f32x4 (&acc)[2][2][4][2], const pg8::Unit& u, int wr, int wc, int fr, int fq) const {
;     ...
;                 } else if (grp == 1) { const f32x4 b0 = *(const f32x4*)(p1 + c), b1 = *(const f32x4*)(p1 + c + 4);
; #pragma unroll
;                     for (int e = 0; e < 4; ++e) { v0[e] = sigmoidf_(v0[e] + b0[e]); v1[e] = sigmoidf_(v1[e] + b1[e]); }
;                     *(f32x4*)(f1 + off) = v0; *(f32x4*)(f1 + off + 4) = v1;
.LBB0_1297:
	s_andn2_b64 vcc, exec, s[18:19]
	s_cbranch_vccnz .LBB0_1299
	s_waitcnt lgkmcnt(0)
	s_nop 1
	v_mov_b32_e32 v130, v228
	v_mov_b32_e32 v131, v229
	v_mov_b32_e32 v132, v230
	v_mov_b32_e32 v133, v231
	v_mov_b32_e32 v134, v224
	v_mov_b32_e32 v135, v225
	v_mov_b32_e32 v136, v226
	v_mov_b32_e32 v137, v227
	v_add_f32_e32 v129, v24, v130
	v_add_f32_e32 v130, v25, v131
	v_add_f32_e32 v131, v26, v132
	v_mul_f32_e32 v129, 0xbfb8aa3b, v129
	v_mul_f32_e32 v130, 0xbfb8aa3b, v130
	v_mul_f32_e32 v131, 0xbfb8aa3b, v131
	v_add_f32_e32 v128, v28, v134
	v_exp_f32_e32 v134, v129
	v_add_f32_e32 v129, v29, v135
	v_exp_f32_e32 v135, v130
	v_add_f32_e32 v130, v30, v136
	v_exp_f32_e32 v136, v131
	v_add_f32_e32 v131, v31, v137
	v_mul_f32_e32 v130, 0xbfb8aa3b, v130
	v_mul_f32_e32 v131, 0xbfb8aa3b, v131
	v_exp_f32_e32 v130, v130
	v_exp_f32_e32 v131, v131
	v_mul_f32_e32 v128, 0xbfb8aa3b, v128
	v_mul_f32_e32 v129, 0xbfb8aa3b, v129
	v_exp_f32_e32 v128, v128
	v_pk_add_f32 v[130:131], v[130:131], 1.0 op_sel_hi:[1,0]
	v_exp_f32_e32 v129, v129
	v_div_scale_f32 v132, s[18:19], v131, v131, 1.0
	v_rcp_f32_e32 v137, v132
	v_pk_add_f32 v[128:129], v[128:129], 1.0 op_sel_hi:[1,0]
	v_fma_f32 v157, -v132, v137, 1.0
	v_fmac_f32_e32 v137, v157, v137
	v_div_scale_f32 v157, vcc, 1.0, v131, 1.0
	v_mul_f32_e32 v164, v157, v137
	v_fma_f32 v165, -v132, v164, v157
	v_fmac_f32_e32 v164, v165, v137
	v_fma_f32 v132, -v132, v164, v157
	v_div_fmas_f32 v132, v132, v137, v164
	v_div_fixup_f32 v131, v132, v131, 1.0
	v_div_scale_f32 v132, s[18:19], v130, v130, 1.0
	v_rcp_f32_e32 v137, v132
	s_nop 0
	v_fma_f32 v157, -v132, v137, 1.0
	v_fmac_f32_e32 v137, v157, v137
	v_div_scale_f32 v157, vcc, 1.0, v130, 1.0
	v_mul_f32_e32 v164, v157, v137
	v_fma_f32 v165, -v132, v164, v157
	v_fmac_f32_e32 v164, v165, v137
	v_fma_f32 v132, -v132, v164, v157
	v_div_fmas_f32 v132, v132, v137, v164
	v_div_fixup_f32 v130, v132, v130, 1.0
	v_div_scale_f32 v132, s[18:19], v129, v129, 1.0
	v_rcp_f32_e32 v137, v132
	s_nop 0
	v_fma_f32 v157, -v132, v137, 1.0
	v_fmac_f32_e32 v137, v157, v137
	v_div_scale_f32 v157, vcc, 1.0, v129, 1.0
	v_mul_f32_e32 v164, v157, v137
	v_fma_f32 v165, -v132, v164, v157
	v_fmac_f32_e32 v164, v165, v137
	v_fma_f32 v132, -v132, v164, v157
	v_div_fmas_f32 v132, v132, v137, v164
	v_div_fixup_f32 v129, v132, v129, 1.0
	v_div_scale_f32 v132, s[18:19], v128, v128, 1.0
	v_rcp_f32_e32 v137, v132
	s_nop 0
	v_fma_f32 v157, -v132, v137, 1.0
	v_fmac_f32_e32 v137, v157, v137
	v_div_scale_f32 v157, vcc, 1.0, v128, 1.0
	v_mul_f32_e32 v164, v157, v137
	v_fma_f32 v165, -v132, v164, v157
	v_fmac_f32_e32 v164, v165, v137
	v_fma_f32 v132, -v132, v164, v157
	v_div_fmas_f32 v132, v132, v137, v164
	v_div_fixup_f32 v128, v132, v128, 1.0
	v_add_f32_e32 v132, v27, v133
	v_mul_f32_e32 v132, 0xbfb8aa3b, v132
	v_exp_f32_e32 v137, v132
	v_pk_add_f32 v[132:133], v[134:135], 1.0 op_sel_hi:[1,0]
	v_pk_add_f32 v[134:135], v[136:137], 1.0 op_sel_hi:[1,0]
	s_nop 0
	v_div_scale_f32 v136, s[18:19], v135, v135, 1.0
	v_rcp_f32_e32 v137, v136
	s_nop 0
	v_fma_f32 v157, -v136, v137, 1.0
	v_fmac_f32_e32 v137, v157, v137
	v_div_scale_f32 v157, vcc, 1.0, v135, 1.0
	v_mul_f32_e32 v164, v157, v137
	v_fma_f32 v165, -v136, v164, v157
	v_fmac_f32_e32 v164, v165, v137
	v_fma_f32 v136, -v136, v164, v157
	v_div_fmas_f32 v136, v136, v137, v164
	v_div_fixup_f32 v135, v136, v135, 1.0
	v_div_scale_f32 v136, s[18:19], v134, v134, 1.0
	v_rcp_f32_e32 v137, v136
	s_nop 0
	v_fma_f32 v157, -v136, v137, 1.0
	v_fmac_f32_e32 v137, v157, v137
	v_div_scale_f32 v157, vcc, 1.0, v134, 1.0
	v_mul_f32_e32 v164, v157, v137
	v_fma_f32 v165, -v136, v164, v157
	v_fmac_f32_e32 v164, v165, v137
	v_fma_f32 v136, -v136, v164, v157
	v_div_fmas_f32 v136, v136, v137, v164
	v_div_fixup_f32 v134, v136, v134, 1.0
	v_div_scale_f32 v136, s[18:19], v133, v133, 1.0
	v_rcp_f32_e32 v137, v136
	s_nop 0
	v_fma_f32 v157, -v136, v137, 1.0
	v_fmac_f32_e32 v137, v157, v137
	v_div_scale_f32 v157, vcc, 1.0, v133, 1.0
	v_mul_f32_e32 v164, v157, v137
	v_fma_f32 v165, -v136, v164, v157
	v_fmac_f32_e32 v164, v165, v137
	v_fma_f32 v136, -v136, v164, v157
	v_div_fmas_f32 v136, v136, v137, v164
	v_div_fixup_f32 v133, v136, v133, 1.0
	v_div_scale_f32 v136, s[18:19], v132, v132, 1.0
	v_rcp_f32_e32 v137, v136
	s_nop 0
	v_fma_f32 v157, -v136, v137, 1.0
	v_fmac_f32_e32 v137, v157, v137
	v_div_scale_f32 v157, vcc, 1.0, v132, 1.0
	v_mul_f32_e32 v164, v157, v137
	v_fma_f32 v165, -v136, v164, v157
	v_fmac_f32_e32 v164, v165, v137
	v_fma_f32 v136, -v136, v164, v157
	v_div_fmas_f32 v136, v136, v137, v164
	v_div_fixup_f32 v132, v136, v132, 1.0
	v_lshl_add_u64 v[136:137], v[162:163], 2, s[20:21]
	global_store_dwordx4 v[136:137], v[128:131], off
	global_store_dwordx4 v[136:137], v[132:135], off offset:16

; __device__ __forceinline__ float sigmoidf_(float x) { return 1.0f / (1.0f + __expf(-x)); }
;     __device__ __forceinline__ void operator()(const f32x4 (&acc)[2][2][4][2], const pg8::Unit& u, int wr, int wc, int fr, int fq) const {
;     ...
;             EPI_BEGIN { const int c = col & 2047; const size_t off = (size_t)row * 2048 + c;
;                 if (grp == 0) { const f32x4 b0 = *(const f32x4*)(p0 + c), b1 = *(const f32x4*)(p0 + c + 4);
; #pragma unroll
;                     for (int e = 0; e < 4; ++e) { v0[e] = __expf(-0.6065306597126334f * sigmoidf_(v0[e] + b0[e])); v1[e] = __expf(-0.6065306597126334f * sigmoidf_(v1[e] + b1[e])); }
;                     *(f32x4*)(f0 + off) = v0; *(f32x4*)(f0 + off + 4) = v1;
.LBB0_1300:
	s_waitcnt lgkmcnt(0)
	s_nop 1
	v_mov_b32_e32 v130, v194
	v_mov_b32_e32 v131, v195
	v_mov_b32_e32 v132, v196
	v_mov_b32_e32 v133, v197
	v_mov_b32_e32 v134, v190
	v_mov_b32_e32 v135, v191
	v_mov_b32_e32 v136, v192
	v_mov_b32_e32 v137, v193
	v_add_f32_e32 v128, v28, v134
	v_mul_f32_e32 v128, 0xbfb8aa3b, v128
	v_exp_f32_e32 v128, v128
	s_nop 0
	v_add_f32_e32 v128, 1.0, v128
	v_div_scale_f32 v129, s[18:19], v128, v128, 1.0
	v_rcp_f32_e32 v134, v129
	s_nop 0
	v_fma_f32 v157, -v129, v134, 1.0
	v_fmac_f32_e32 v134, v157, v134
	v_div_scale_f32 v157, vcc, 1.0, v128, 1.0
	v_mul_f32_e32 v164, v157, v134
	v_fma_f32 v165, -v129, v164, v157
	v_fmac_f32_e32 v164, v165, v134
	v_fma_f32 v129, -v129, v164, v157
	v_div_fmas_f32 v129, v129, v134, v164
	v_div_fixup_f32 v128, v129, v128, 1.0
	v_add_f32_e32 v129, v24, v130
	v_mul_f32_e32 v129, 0xbfb8aa3b, v129
	v_exp_f32_e32 v129, v129
	v_mul_f32_e32 v128, 0xbf1b4598, v128
	v_mul_f32_e32 v128, 0x3fb8aa3b, v128
	v_exp_f32_e32 v128, v128
	v_add_f32_e32 v129, 1.0, v129
	v_div_scale_f32 v130, s[18:19], v129, v129, 1.0
	v_rcp_f32_e32 v134, v130
	s_nop 0
	v_fma_f32 v157, -v130, v134, 1.0
	v_fmac_f32_e32 v134, v157, v134
	v_div_scale_f32 v157, vcc, 1.0, v129, 1.0
	v_mul_f32_e32 v164, v157, v134
	v_fma_f32 v165, -v130, v164, v157
	v_fmac_f32_e32 v164, v165, v134
	v_fma_f32 v130, -v130, v164, v157
	v_div_fmas_f32 v130, v130, v134, v164
	v_div_fixup_f32 v129, v130, v129, 1.0
	v_mul_f32_e32 v129, 0xbf1b4598, v129
	v_mul_f32_e32 v129, 0x3fb8aa3b, v129
	v_exp_f32_e32 v134, v129
	v_add_f32_e32 v129, v29, v135
	v_mul_f32_e32 v129, 0xbfb8aa3b, v129
	v_exp_f32_e32 v129, v129
	s_nop 0
	v_add_f32_e32 v129, 1.0, v129
	v_div_scale_f32 v130, s[18:19], v129, v129, 1.0
	v_rcp_f32_e32 v135, v130
	s_nop 0
	v_fma_f32 v157, -v130, v135, 1.0
	v_fmac_f32_e32 v135, v157, v135
	v_div_scale_f32 v157, vcc, 1.0, v129, 1.0
	v_mul_f32_e32 v164, v157, v135
	v_fma_f32 v165, -v130, v164, v157
	v_fmac_f32_e32 v164, v165, v135
	v_fma_f32 v130, -v130, v164, v157
	v_div_fmas_f32 v130, v130, v135, v164
	v_div_fixup_f32 v129, v130, v129, 1.0
	v_add_f32_e32 v130, v25, v131
	v_mul_f32_e32 v130, 0xbfb8aa3b, v130
	v_exp_f32_e32 v130, v130
	v_mul_f32_e32 v129, 0xbf1b4598, v129
	v_mul_f32_e32 v129, 0x3fb8aa3b, v129
	v_exp_f32_e32 v129, v129
	v_add_f32_e32 v130, 1.0, v130
	v_div_scale_f32 v131, s[18:19], v130, v130, 1.0
	v_rcp_f32_e32 v135, v131
	s_nop 0
	v_fma_f32 v157, -v131, v135, 1.0
	v_fmac_f32_e32 v135, v157, v135
	v_div_scale_f32 v157, vcc, 1.0, v130, 1.0
	v_mul_f32_e32 v164, v157, v135
	v_fma_f32 v165, -v131, v164, v157
	v_fmac_f32_e32 v164, v165, v135
	v_fma_f32 v131, -v131, v164, v157
	v_div_fmas_f32 v131, v131, v135, v164
	v_div_fixup_f32 v130, v131, v130, 1.0
	v_mul_f32_e32 v130, 0xbf1b4598, v130
	v_mul_f32_e32 v130, 0x3fb8aa3b, v130
	v_exp_f32_e32 v135, v130
	v_add_f32_e32 v130, v30, v136
	v_mul_f32_e32 v130, 0xbfb8aa3b, v130
	v_exp_f32_e32 v130, v130
	s_nop 0
	v_add_f32_e32 v130, 1.0, v130
	v_div_scale_f32 v131, s[18:19], v130, v130, 1.0
	v_rcp_f32_e32 v136, v131
	s_nop 0
	v_fma_f32 v157, -v131, v136, 1.0
	v_fmac_f32_e32 v136, v157, v136
	v_div_scale_f32 v157, vcc, 1.0, v130, 1.0
	v_mul_f32_e32 v164, v157, v136
	v_fma_f32 v165, -v131, v164, v157
	v_fmac_f32_e32 v164, v165, v136
	v_fma_f32 v131, -v131, v164, v157
	v_div_fmas_f32 v131, v131, v136, v164
	v_div_fixup_f32 v130, v131, v130, 1.0
	v_add_f32_e32 v131, v26, v132
	v_mul_f32_e32 v131, 0xbfb8aa3b, v131
	v_exp_f32_e32 v131, v131
	v_mul_f32_e32 v130, 0xbf1b4598, v130
	v_mul_f32_e32 v130, 0x3fb8aa3b, v130
	v_exp_f32_e32 v130, v130
	v_add_f32_e32 v131, 1.0, v131
	v_div_scale_f32 v132, s[18:19], v131, v131, 1.0
	v_rcp_f32_e32 v136, v132
	s_nop 0
	v_fma_f32 v157, -v132, v136, 1.0
	v_fmac_f32_e32 v136, v157, v136
	v_div_scale_f32 v157, vcc, 1.0, v131, 1.0
	v_mul_f32_e32 v164, v157, v136
	v_fma_f32 v165, -v132, v164, v157
	v_fmac_f32_e32 v164, v165, v136
	v_fma_f32 v132, -v132, v164, v157
	v_div_fmas_f32 v132, v132, v136, v164
	v_div_fixup_f32 v131, v132, v131, 1.0
	v_mul_f32_e32 v131, 0xbf1b4598, v131
	v_mul_f32_e32 v131, 0x3fb8aa3b, v131
	v_exp_f32_e32 v136, v131
	v_add_f32_e32 v131, v31, v137
	v_mul_f32_e32 v131, 0xbfb8aa3b, v131
	v_exp_f32_e32 v131, v131
	s_nop 0
	v_add_f32_e32 v131, 1.0, v131
	v_div_scale_f32 v132, s[18:19], v131, v131, 1.0
	v_rcp_f32_e32 v137, v132
	s_nop 0
	v_fma_f32 v157, -v132, v137, 1.0
	v_fmac_f32_e32 v137, v157, v137
	v_div_scale_f32 v157, vcc, 1.0, v131, 1.0
	v_mul_f32_e32 v164, v157, v137
	v_fma_f32 v165, -v132, v164, v157
	v_fmac_f32_e32 v164, v165, v137
	v_fma_f32 v132, -v132, v164, v157
	v_div_fmas_f32 v132, v132, v137, v164
	v_div_fixup_f32 v131, v132, v131, 1.0
	v_add_f32_e32 v132, v27, v133
	v_mul_f32_e32 v132, 0xbfb8aa3b, v132
	v_exp_f32_e32 v132, v132
	v_mul_f32_e32 v131, 0xbf1b4598, v131
	v_mul_f32_e32 v131, 0x3fb8aa3b, v131
	v_exp_f32_e32 v131, v131
	v_add_f32_e32 v132, 1.0, v132
	v_div_scale_f32 v133, s[18:19], v132, v132, 1.0
	v_rcp_f32_e32 v137, v133
	s_nop 0
	v_fma_f32 v157, -v133, v137, 1.0
	v_fmac_f32_e32 v137, v157, v137
	v_div_scale_f32 v157, vcc, 1.0, v132, 1.0
	v_mul_f32_e32 v164, v157, v137
	v_fma_f32 v165, -v133, v164, v157
	v_fmac_f32_e32 v164, v165, v137
	v_fma_f32 v133, -v133, v164, v157
	v_div_fmas_f32 v133, v133, v137, v164
	v_div_fixup_f32 v132, v133, v132, 1.0
	v_mul_f32_e32 v132, 0xbf1b4598, v132
	v_mul_f32_e32 v132, 0x3fb8aa3b, v132
	v_exp_f32_e32 v137, v132
	v_lshl_add_u64 v[132:133], v[162:163], 2, s[50:51]
	global_store_dwordx4 v[132:133], v[128:131], off
	global_store_dwordx4 v[132:133], v[134:137], off offset:16
	s_and_b64 vcc, exec, s[46:47]
	s_mov_b64 s[18:19], -1
	s_cbranch_vccnz .LBB0_1040

; __device__ __forceinline__ float sigmoidf_(float x) { return 1.0f / (1.0f + __expf(-x)); }
;     __device__ __forceinline__ void operator()(const f32x4 (&acc)[2][2][4][2], const pg8::Unit& u, int wr, int wc, int fr, int fq) const {
;     ...
;                 } else if (grp == 1) { const f32x4 b0 = *(const f32x4*)(p1 + c), b1 = *(const f32x4*)(p1 + c + 4);
; #pragma unroll
;                     for (int e = 0; e < 4; ++e) { v0[e] = sigmoidf_(v0[e] + b0[e]); v1[e] = sigmoidf_(v1[e] + b1[e]); }
;                     *(f32x4*)(f1 + off) = v0; *(f32x4*)(f1 + off + 4) = v1;
.LBB0_1303:
	s_andn2_b64 vcc, exec, s[18:19]
	s_cbranch_vccnz .LBB0_1305
	s_waitcnt lgkmcnt(0)
	s_nop 1
	v_mov_b32_e32 v130, v236
	v_mov_b32_e32 v131, v237
	v_mov_b32_e32 v132, v238
	v_mov_b32_e32 v133, v239
	v_mov_b32_e32 v134, v232
	v_mov_b32_e32 v135, v233
	v_mov_b32_e32 v136, v234
	v_mov_b32_e32 v137, v235
	v_add_f32_e32 v129, v16, v130
	v_add_f32_e32 v130, v17, v131
	v_add_f32_e32 v131, v18, v132
	v_mul_f32_e32 v129, 0xbfb8aa3b, v129
	v_mul_f32_e32 v130, 0xbfb8aa3b, v130
	v_mul_f32_e32 v131, 0xbfb8aa3b, v131
	v_add_f32_e32 v128, v20, v134
	v_exp_f32_e32 v134, v129
	v_add_f32_e32 v129, v21, v135
	v_exp_f32_e32 v135, v130
	v_add_f32_e32 v130, v22, v136
	v_exp_f32_e32 v136, v131
	v_add_f32_e32 v131, v23, v137
	v_mul_f32_e32 v130, 0xbfb8aa3b, v130
	v_mul_f32_e32 v131, 0xbfb8aa3b, v131
	v_exp_f32_e32 v130, v130
	v_exp_f32_e32 v131, v131
	v_mul_f32_e32 v128, 0xbfb8aa3b, v128
	v_mul_f32_e32 v129, 0xbfb8aa3b, v129
	v_exp_f32_e32 v128, v128
	v_pk_add_f32 v[130:131], v[130:131], 1.0 op_sel_hi:[1,0]
	v_exp_f32_e32 v129, v129
	v_div_scale_f32 v132, s[18:19], v131, v131, 1.0
	v_rcp_f32_e32 v137, v132
	v_pk_add_f32 v[128:129], v[128:129], 1.0 op_sel_hi:[1,0]
	v_fma_f32 v157, -v132, v137, 1.0
	v_fmac_f32_e32 v137, v157, v137
	v_div_scale_f32 v157, vcc, 1.0, v131, 1.0
	v_mul_f32_e32 v162, v157, v137
	v_fma_f32 v163, -v132, v162, v157
	v_fmac_f32_e32 v162, v163, v137
	v_fma_f32 v132, -v132, v162, v157
	v_div_fmas_f32 v132, v132, v137, v162
	v_div_fixup_f32 v131, v132, v131, 1.0
	v_div_scale_f32 v132, s[18:19], v130, v130, 1.0
	v_rcp_f32_e32 v137, v132
	s_nop 0
	v_fma_f32 v157, -v132, v137, 1.0
	v_fmac_f32_e32 v137, v157, v137
	v_div_scale_f32 v157, vcc, 1.0, v130, 1.0
	v_mul_f32_e32 v162, v157, v137
	v_fma_f32 v163, -v132, v162, v157
	v_fmac_f32_e32 v162, v163, v137
	v_fma_f32 v132, -v132, v162, v157
	v_div_fmas_f32 v132, v132, v137, v162
	v_div_fixup_f32 v130, v132, v130, 1.0
	v_div_scale_f32 v132, s[18:19], v129, v129, 1.0
	v_rcp_f32_e32 v137, v132
	s_nop 0
	v_fma_f32 v157, -v132, v137, 1.0
	v_fmac_f32_e32 v137, v157, v137
	v_div_scale_f32 v157, vcc, 1.0, v129, 1.0
	v_mul_f32_e32 v162, v157, v137
	v_fma_f32 v163, -v132, v162, v157
	v_fmac_f32_e32 v162, v163, v137
	v_fma_f32 v132, -v132, v162, v157
	v_div_fmas_f32 v132, v132, v137, v162
	v_div_fixup_f32 v129, v132, v129, 1.0
	v_div_scale_f32 v132, s[18:19], v128, v128, 1.0
	v_rcp_f32_e32 v137, v132
	s_nop 0
	v_fma_f32 v157, -v132, v137, 1.0
	v_fmac_f32_e32 v137, v157, v137
	v_div_scale_f32 v157, vcc, 1.0, v128, 1.0
	v_mul_f32_e32 v162, v157, v137
	v_fma_f32 v163, -v132, v162, v157
	v_fmac_f32_e32 v162, v163, v137
	v_fma_f32 v132, -v132, v162, v157
	v_div_fmas_f32 v132, v132, v137, v162
	v_div_fixup_f32 v128, v132, v128, 1.0
	v_add_f32_e32 v132, v19, v133
	v_mul_f32_e32 v132, 0xbfb8aa3b, v132
	v_exp_f32_e32 v137, v132
	v_pk_add_f32 v[132:133], v[134:135], 1.0 op_sel_hi:[1,0]
	v_pk_add_f32 v[134:135], v[136:137], 1.0 op_sel_hi:[1,0]
	s_nop 0
	v_div_scale_f32 v136, s[18:19], v135, v135, 1.0
	v_rcp_f32_e32 v137, v136
	s_nop 0
	v_fma_f32 v157, -v136, v137, 1.0
	v_fmac_f32_e32 v137, v157, v137
	v_div_scale_f32 v157, vcc, 1.0, v135, 1.0
	v_mul_f32_e32 v162, v157, v137
	v_fma_f32 v163, -v136, v162, v157
	v_fmac_f32_e32 v162, v163, v137
	v_fma_f32 v136, -v136, v162, v157
	v_div_fmas_f32 v136, v136, v137, v162
	v_div_fixup_f32 v135, v136, v135, 1.0
	v_div_scale_f32 v136, s[18:19], v134, v134, 1.0
	v_rcp_f32_e32 v137, v136
	s_nop 0
	v_fma_f32 v157, -v136, v137, 1.0
	v_fmac_f32_e32 v137, v157, v137
	v_div_scale_f32 v157, vcc, 1.0, v134, 1.0
	v_mul_f32_e32 v162, v157, v137
	v_fma_f32 v163, -v136, v162, v157
	v_fmac_f32_e32 v162, v163, v137
	v_fma_f32 v136, -v136, v162, v157
	v_div_fmas_f32 v136, v136, v137, v162
	v_div_fixup_f32 v134, v136, v134, 1.0
	v_div_scale_f32 v136, s[18:19], v133, v133, 1.0
	v_rcp_f32_e32 v137, v136
	s_nop 0
	v_fma_f32 v157, -v136, v137, 1.0
	v_fmac_f32_e32 v137, v157, v137
	v_div_scale_f32 v157, vcc, 1.0, v133, 1.0
	v_mul_f32_e32 v162, v157, v137
	v_fma_f32 v163, -v136, v162, v157
	v_fmac_f32_e32 v162, v163, v137
	v_fma_f32 v136, -v136, v162, v157
	v_div_fmas_f32 v136, v136, v137, v162
	v_div_fixup_f32 v133, v136, v133, 1.0
	v_div_scale_f32 v136, s[18:19], v132, v132, 1.0
	v_rcp_f32_e32 v137, v136
	s_nop 0
	v_fma_f32 v157, -v136, v137, 1.0
	v_fmac_f32_e32 v137, v157, v137
	v_div_scale_f32 v157, vcc, 1.0, v132, 1.0
	v_mul_f32_e32 v162, v157, v137
	v_fma_f32 v163, -v136, v162, v157
	v_fmac_f32_e32 v162, v163, v137
	v_fma_f32 v136, -v136, v162, v157
	v_div_fmas_f32 v136, v136, v137, v162
	v_div_fixup_f32 v132, v136, v132, 1.0
	v_lshl_add_u64 v[136:137], v[160:161], 0, v[180:181]
	v_lshl_add_u64 v[136:137], v[136:137], 2, s[20:21]
	global_store_dwordx4 v[136:137], v[128:131], off offset:512
	global_store_dwordx4 v[136:137], v[132:135], off offset:528

; __device__ __forceinline__ float sigmoidf_(float x) { return 1.0f / (1.0f + __expf(-x)); }
;     __device__ __forceinline__ void operator()(const f32x4 (&acc)[2][2][4][2], const pg8::Unit& u, int wr, int wc, int fr, int fq) const {
;     ...
;                 } else if (grp == 1) { const f32x4 b0 = *(const f32x4*)(p1 + c), b1 = *(const f32x4*)(p1 + c + 4);
; #pragma unroll
;                     for (int e = 0; e < 4; ++e) { v0[e] = sigmoidf_(v0[e] + b0[e]); v1[e] = sigmoidf_(v1[e] + b1[e]); }
;                     *(f32x4*)(f1 + off) = v0; *(f32x4*)(f1 + off + 4) = v1;
.LBB0_1308:
	s_andn2_b64 vcc, exec, s[18:19]
	s_cbranch_vccnz .LBB0_1310
	s_waitcnt lgkmcnt(0)
	s_nop 1
	v_mov_b32_e32 v130, v228
	v_mov_b32_e32 v131, v229
	v_mov_b32_e32 v132, v230
	v_mov_b32_e32 v133, v231
	v_mov_b32_e32 v134, v224
	v_mov_b32_e32 v135, v225
	v_mov_b32_e32 v136, v226
	v_mov_b32_e32 v137, v227
	v_add_f32_e32 v129, v8, v130
	v_add_f32_e32 v130, v9, v131
	v_add_f32_e32 v131, v10, v132
	v_mul_f32_e32 v129, 0xbfb8aa3b, v129
	v_mul_f32_e32 v130, 0xbfb8aa3b, v130
	v_mul_f32_e32 v131, 0xbfb8aa3b, v131
	v_add_f32_e32 v128, v12, v134
	v_exp_f32_e32 v134, v129
	v_add_f32_e32 v129, v13, v135
	v_exp_f32_e32 v135, v130
	v_add_f32_e32 v130, v14, v136
	v_exp_f32_e32 v136, v131
	v_add_f32_e32 v131, v15, v137
	v_mul_f32_e32 v130, 0xbfb8aa3b, v130
	v_mul_f32_e32 v131, 0xbfb8aa3b, v131
	v_exp_f32_e32 v130, v130
	v_exp_f32_e32 v131, v131
	v_mul_f32_e32 v128, 0xbfb8aa3b, v128
	v_mul_f32_e32 v129, 0xbfb8aa3b, v129
	v_exp_f32_e32 v128, v128
	v_pk_add_f32 v[130:131], v[130:131], 1.0 op_sel_hi:[1,0]
	v_exp_f32_e32 v129, v129
	v_div_scale_f32 v132, s[18:19], v131, v131, 1.0
	v_rcp_f32_e32 v137, v132
	v_pk_add_f32 v[128:129], v[128:129], 1.0 op_sel_hi:[1,0]
	v_fma_f32 v157, -v132, v137, 1.0
	v_fmac_f32_e32 v137, v157, v137
	v_div_scale_f32 v157, vcc, 1.0, v131, 1.0
	v_mul_f32_e32 v159, v157, v137
	v_fma_f32 v164, -v132, v159, v157
	v_fmac_f32_e32 v159, v164, v137
	v_fma_f32 v132, -v132, v159, v157
	v_div_fmas_f32 v132, v132, v137, v159
	v_div_fixup_f32 v131, v132, v131, 1.0
	v_div_scale_f32 v132, s[18:19], v130, v130, 1.0
	v_rcp_f32_e32 v137, v132
	s_nop 0
	v_fma_f32 v157, -v132, v137, 1.0
	v_fmac_f32_e32 v137, v157, v137
	v_div_scale_f32 v157, vcc, 1.0, v130, 1.0
	v_mul_f32_e32 v159, v157, v137
	v_fma_f32 v164, -v132, v159, v157
	v_fmac_f32_e32 v159, v164, v137
	v_fma_f32 v132, -v132, v159, v157
	v_div_fmas_f32 v132, v132, v137, v159
	v_div_fixup_f32 v130, v132, v130, 1.0
	v_div_scale_f32 v132, s[18:19], v129, v129, 1.0
	v_rcp_f32_e32 v137, v132
	s_nop 0
	v_fma_f32 v157, -v132, v137, 1.0
	v_fmac_f32_e32 v137, v157, v137
	v_div_scale_f32 v157, vcc, 1.0, v129, 1.0
	v_mul_f32_e32 v159, v157, v137
	v_fma_f32 v164, -v132, v159, v157
	v_fmac_f32_e32 v159, v164, v137
	v_fma_f32 v132, -v132, v159, v157
	v_div_fmas_f32 v132, v132, v137, v159
	v_div_fixup_f32 v129, v132, v129, 1.0
	v_div_scale_f32 v132, s[18:19], v128, v128, 1.0
	v_rcp_f32_e32 v137, v132
	s_nop 0
	v_fma_f32 v157, -v132, v137, 1.0
	v_fmac_f32_e32 v137, v157, v137
	v_div_scale_f32 v157, vcc, 1.0, v128, 1.0
	v_mul_f32_e32 v159, v157, v137
	v_fma_f32 v164, -v132, v159, v157
	v_fmac_f32_e32 v159, v164, v137
	v_fma_f32 v132, -v132, v159, v157
	v_div_fmas_f32 v132, v132, v137, v159
	v_div_fixup_f32 v128, v132, v128, 1.0
	v_add_f32_e32 v132, v11, v133
	v_mul_f32_e32 v132, 0xbfb8aa3b, v132
	v_exp_f32_e32 v137, v132
	v_pk_add_f32 v[132:133], v[134:135], 1.0 op_sel_hi:[1,0]
	v_pk_add_f32 v[134:135], v[136:137], 1.0 op_sel_hi:[1,0]
	s_nop 0
	v_div_scale_f32 v136, s[18:19], v135, v135, 1.0
	v_rcp_f32_e32 v137, v136
	s_nop 0
	v_fma_f32 v157, -v136, v137, 1.0
	v_fmac_f32_e32 v137, v157, v137
	v_div_scale_f32 v157, vcc, 1.0, v135, 1.0
	v_mul_f32_e32 v159, v157, v137
	v_fma_f32 v164, -v136, v159, v157
	v_fmac_f32_e32 v159, v164, v137
	v_fma_f32 v136, -v136, v159, v157
	v_div_fmas_f32 v136, v136, v137, v159
	v_div_fixup_f32 v135, v136, v135, 1.0
	v_div_scale_f32 v136, s[18:19], v134, v134, 1.0
	v_rcp_f32_e32 v137, v136
	s_nop 0
	v_fma_f32 v157, -v136, v137, 1.0
	v_fmac_f32_e32 v137, v157, v137
	v_div_scale_f32 v157, vcc, 1.0, v134, 1.0
	v_mul_f32_e32 v159, v157, v137
	v_fma_f32 v164, -v136, v159, v157
	v_fmac_f32_e32 v159, v164, v137
	v_fma_f32 v136, -v136, v159, v157
	v_div_fmas_f32 v136, v136, v137, v159
	v_div_fixup_f32 v134, v136, v134, 1.0
	v_div_scale_f32 v136, s[18:19], v133, v133, 1.0
	v_rcp_f32_e32 v137, v136
	s_nop 0
	v_fma_f32 v157, -v136, v137, 1.0
	v_fmac_f32_e32 v137, v157, v137
	v_div_scale_f32 v157, vcc, 1.0, v133, 1.0
	v_mul_f32_e32 v159, v157, v137
	v_fma_f32 v164, -v136, v159, v157
	v_fmac_f32_e32 v159, v164, v137
	v_fma_f32 v136, -v136, v159, v157
	v_div_fmas_f32 v136, v136, v137, v159
	v_div_fixup_f32 v133, v136, v133, 1.0
	v_div_scale_f32 v136, s[18:19], v132, v132, 1.0
	v_rcp_f32_e32 v137, v136
	s_nop 0
	v_fma_f32 v157, -v136, v137, 1.0
	v_fmac_f32_e32 v137, v157, v137
	v_div_scale_f32 v157, vcc, 1.0, v132, 1.0
	v_mul_f32_e32 v159, v157, v137
	v_fma_f32 v164, -v136, v159, v157
	v_fmac_f32_e32 v159, v164, v137
	v_fma_f32 v136, -v136, v159, v157
	v_div_fmas_f32 v136, v136, v137, v159
	v_div_fixup_f32 v132, v136, v132, 1.0
	v_lshl_add_u64 v[136:137], v[162:163], 2, s[20:21]
	global_store_dwordx4 v[136:137], v[128:131], off
	global_store_dwordx4 v[136:137], v[132:135], off offset:16

; __device__ __forceinline__ float sigmoidf_(float x) { return 1.0f / (1.0f + __expf(-x)); }
;     __device__ __forceinline__ void operator()(const f32x4 (&acc)[2][2][4][2], const pg8::Unit& u, int wr, int wc, int fr, int fq) const {
;     ...
;             EPI_BEGIN { const int c = col & 2047; const size_t off = (size_t)row * 2048 + c;
;                 if (grp == 0) { const f32x4 b0 = *(const f32x4*)(p0 + c), b1 = *(const f32x4*)(p0 + c + 4);
; #pragma unroll
;                     for (int e = 0; e < 4; ++e) { v0[e] = __expf(-0.6065306597126334f * sigmoidf_(v0[e] + b0[e])); v1[e] = __expf(-0.6065306597126334f * sigmoidf_(v1[e] + b1[e])); }
;                     *(f32x4*)(f0 + off) = v0; *(f32x4*)(f0 + off + 4) = v1;
.LBB0_1311:
	s_waitcnt lgkmcnt(0)
	s_nop 1
	v_mov_b32_e32 v130, v194
	v_mov_b32_e32 v131, v195
	v_mov_b32_e32 v132, v196
	v_mov_b32_e32 v133, v197
	v_mov_b32_e32 v134, v190
	v_mov_b32_e32 v135, v191
	v_mov_b32_e32 v136, v192
	v_mov_b32_e32 v137, v193
	v_add_f32_e32 v128, v12, v134
	v_mul_f32_e32 v128, 0xbfb8aa3b, v128
	v_exp_f32_e32 v128, v128
	s_nop 0
	v_add_f32_e32 v128, 1.0, v128
	v_div_scale_f32 v129, s[18:19], v128, v128, 1.0
	v_rcp_f32_e32 v134, v129
	s_nop 0
	v_fma_f32 v157, -v129, v134, 1.0
	v_fmac_f32_e32 v134, v157, v134
	v_div_scale_f32 v157, vcc, 1.0, v128, 1.0
	v_mul_f32_e32 v159, v157, v134
	v_fma_f32 v164, -v129, v159, v157
	v_fmac_f32_e32 v159, v164, v134
	v_fma_f32 v129, -v129, v159, v157
	v_div_fmas_f32 v129, v129, v134, v159
	v_div_fixup_f32 v128, v129, v128, 1.0
	v_add_f32_e32 v129, v8, v130
	v_mul_f32_e32 v129, 0xbfb8aa3b, v129
	v_exp_f32_e32 v129, v129
	v_mul_f32_e32 v128, 0xbf1b4598, v128
	v_mul_f32_e32 v128, 0x3fb8aa3b, v128
	v_exp_f32_e32 v128, v128
	v_add_f32_e32 v129, 1.0, v129
	v_div_scale_f32 v130, s[18:19], v129, v129, 1.0
	v_rcp_f32_e32 v134, v130
	s_nop 0
	v_fma_f32 v157, -v130, v134, 1.0
	v_fmac_f32_e32 v134, v157, v134
	v_div_scale_f32 v157, vcc, 1.0, v129, 1.0
	v_mul_f32_e32 v159, v157, v134
	v_fma_f32 v164, -v130, v159, v157
	v_fmac_f32_e32 v159, v164, v134
	v_fma_f32 v130, -v130, v159, v157
	v_div_fmas_f32 v130, v130, v134, v159
	v_div_fixup_f32 v129, v130, v129, 1.0
	v_mul_f32_e32 v129, 0xbf1b4598, v129
	v_mul_f32_e32 v129, 0x3fb8aa3b, v129
	v_exp_f32_e32 v134, v129
	v_add_f32_e32 v129, v13, v135
	v_mul_f32_e32 v129, 0xbfb8aa3b, v129
	v_exp_f32_e32 v129, v129
	s_nop 0
	v_add_f32_e32 v129, 1.0, v129
	v_div_scale_f32 v130, s[18:19], v129, v129, 1.0
	v_rcp_f32_e32 v135, v130
	s_nop 0
	v_fma_f32 v157, -v130, v135, 1.0
	v_fmac_f32_e32 v135, v157, v135
	v_div_scale_f32 v157, vcc, 1.0, v129, 1.0
	v_mul_f32_e32 v159, v157, v135
	v_fma_f32 v164, -v130, v159, v157
	v_fmac_f32_e32 v159, v164, v135
	v_fma_f32 v130, -v130, v159, v157
	v_div_fmas_f32 v130, v130, v135, v159
	v_div_fixup_f32 v129, v130, v129, 1.0
	v_add_f32_e32 v130, v9, v131
	v_mul_f32_e32 v130, 0xbfb8aa3b, v130
	v_exp_f32_e32 v130, v130
	v_mul_f32_e32 v129, 0xbf1b4598, v129
	v_mul_f32_e32 v129, 0x3fb8aa3b, v129
	v_exp_f32_e32 v129, v129
	v_add_f32_e32 v130, 1.0, v130
	v_div_scale_f32 v131, s[18:19], v130, v130, 1.0
	v_rcp_f32_e32 v135, v131
	s_nop 0
	v_fma_f32 v157, -v131, v135, 1.0
	v_fmac_f32_e32 v135, v157, v135
	v_div_scale_f32 v157, vcc, 1.0, v130, 1.0
	v_mul_f32_e32 v159, v157, v135
	v_fma_f32 v164, -v131, v159, v157
	v_fmac_f32_e32 v159, v164, v135
	v_fma_f32 v131, -v131, v159, v157
	v_div_fmas_f32 v131, v131, v135, v159
	v_div_fixup_f32 v130, v131, v130, 1.0
	v_mul_f32_e32 v130, 0xbf1b4598, v130
	v_mul_f32_e32 v130, 0x3fb8aa3b, v130
	v_exp_f32_e32 v135, v130
	v_add_f32_e32 v130, v14, v136
	v_mul_f32_e32 v130, 0xbfb8aa3b, v130
	v_exp_f32_e32 v130, v130
	s_nop 0
	v_add_f32_e32 v130, 1.0, v130
	v_div_scale_f32 v131, s[18:19], v130, v130, 1.0
	v_rcp_f32_e32 v136, v131
	s_nop 0
	v_fma_f32 v157, -v131, v136, 1.0
	v_fmac_f32_e32 v136, v157, v136
	v_div_scale_f32 v157, vcc, 1.0, v130, 1.0
	v_mul_f32_e32 v159, v157, v136
	v_fma_f32 v164, -v131, v159, v157
	v_fmac_f32_e32 v159, v164, v136
	v_fma_f32 v131, -v131, v159, v157
	v_div_fmas_f32 v131, v131, v136, v159
	v_div_fixup_f32 v130, v131, v130, 1.0
	v_add_f32_e32 v131, v10, v132
	v_mul_f32_e32 v131, 0xbfb8aa3b, v131
	v_exp_f32_e32 v131, v131
	v_mul_f32_e32 v130, 0xbf1b4598, v130
	v_mul_f32_e32 v130, 0x3fb8aa3b, v130
	v_exp_f32_e32 v130, v130
	v_add_f32_e32 v131, 1.0, v131
	v_div_scale_f32 v132, s[18:19], v131, v131, 1.0
	v_rcp_f32_e32 v136, v132
	s_nop 0
	v_fma_f32 v157, -v132, v136, 1.0
	v_fmac_f32_e32 v136, v157, v136
	v_div_scale_f32 v157, vcc, 1.0, v131, 1.0
	v_mul_f32_e32 v159, v157, v136
	v_fma_f32 v164, -v132, v159, v157
	v_fmac_f32_e32 v159, v164, v136
	v_fma_f32 v132, -v132, v159, v157
	v_div_fmas_f32 v132, v132, v136, v159
	v_div_fixup_f32 v131, v132, v131, 1.0
	v_mul_f32_e32 v131, 0xbf1b4598, v131
	v_mul_f32_e32 v131, 0x3fb8aa3b, v131
	v_exp_f32_e32 v136, v131
	v_add_f32_e32 v131, v15, v137
	v_mul_f32_e32 v131, 0xbfb8aa3b, v131
	v_exp_f32_e32 v131, v131
	s_nop 0
	v_add_f32_e32 v131, 1.0, v131
	v_div_scale_f32 v132, s[18:19], v131, v131, 1.0
	v_rcp_f32_e32 v137, v132
	s_nop 0
	v_fma_f32 v157, -v132, v137, 1.0
	v_fmac_f32_e32 v137, v157, v137
	v_div_scale_f32 v157, vcc, 1.0, v131, 1.0
	v_mul_f32_e32 v159, v157, v137
	v_fma_f32 v164, -v132, v159, v157
	v_fmac_f32_e32 v159, v164, v137
	v_fma_f32 v132, -v132, v159, v157
	v_div_fmas_f32 v132, v132, v137, v159
	v_div_fixup_f32 v131, v132, v131, 1.0
	v_add_f32_e32 v132, v11, v133
	v_mul_f32_e32 v132, 0xbfb8aa3b, v132
	v_exp_f32_e32 v132, v132
	v_mul_f32_e32 v131, 0xbf1b4598, v131
	v_mul_f32_e32 v131, 0x3fb8aa3b, v131
	v_exp_f32_e32 v131, v131
	v_add_f32_e32 v132, 1.0, v132
	v_div_scale_f32 v133, s[18:19], v132, v132, 1.0
	v_rcp_f32_e32 v137, v133
	s_nop 0
	v_fma_f32 v157, -v133, v137, 1.0
	v_fmac_f32_e32 v137, v157, v137
	v_div_scale_f32 v157, vcc, 1.0, v132, 1.0
	v_mul_f32_e32 v159, v157, v137
	v_fma_f32 v164, -v133, v159, v157
	v_fmac_f32_e32 v159, v164, v137
	v_fma_f32 v133, -v133, v159, v157
	v_div_fmas_f32 v133, v133, v137, v159
	v_div_fixup_f32 v132, v133, v132, 1.0
	v_mul_f32_e32 v132, 0xbf1b4598, v132
	v_mul_f32_e32 v132, 0x3fb8aa3b, v132
	v_exp_f32_e32 v137, v132
	v_lshl_add_u64 v[132:133], v[162:163], 2, s[50:51]
	global_store_dwordx4 v[132:133], v[128:131], off
	global_store_dwordx4 v[132:133], v[134:137], off offset:16
	s_and_b64 vcc, exec, s[46:47]
	s_mov_b64 s[18:19], -1
	s_cbranch_vccnz .LBB0_1045

; __device__ __forceinline__ float sigmoidf_(float x) { return 1.0f / (1.0f + __expf(-x)); }
;     __device__ __forceinline__ void operator()(const f32x4 (&acc)[2][2][4][2], const pg8::Unit& u, int wr, int wc, int fr, int fq) const {
;     ...
;                 } else if (grp == 1) { const f32x4 b0 = *(const f32x4*)(p1 + c), b1 = *(const f32x4*)(p1 + c + 4);
; #pragma unroll
;                     for (int e = 0; e < 4; ++e) { v0[e] = sigmoidf_(v0[e] + b0[e]); v1[e] = sigmoidf_(v1[e] + b1[e]); }
;                     *(f32x4*)(f1 + off) = v0; *(f32x4*)(f1 + off + 4) = v1;
.LBB0_1314:
	s_andn2_b64 vcc, exec, s[18:19]
	s_cbranch_vccnz .LBB0_1316
	s_waitcnt lgkmcnt(0)
	s_nop 1
	v_mov_b32_e32 v130, v236
	v_mov_b32_e32 v131, v237
	v_mov_b32_e32 v132, v238
	v_mov_b32_e32 v133, v239
	v_mov_b32_e32 v134, v232
	v_mov_b32_e32 v135, v233
	v_mov_b32_e32 v136, v234
	v_mov_b32_e32 v137, v235
	v_add_f32_e32 v129, v0, v130
	v_add_f32_e32 v130, v1, v131
	v_add_f32_e32 v131, v2, v132
	v_mul_f32_e32 v129, 0xbfb8aa3b, v129
	v_mul_f32_e32 v130, 0xbfb8aa3b, v130
	v_mul_f32_e32 v131, 0xbfb8aa3b, v131
	v_add_f32_e32 v128, v4, v134
	v_exp_f32_e32 v134, v129
	v_add_f32_e32 v129, v5, v135
	v_exp_f32_e32 v135, v130
	v_add_f32_e32 v130, v6, v136
	v_exp_f32_e32 v136, v131
	v_add_f32_e32 v131, v7, v137
	v_mul_f32_e32 v130, 0xbfb8aa3b, v130
	v_mul_f32_e32 v131, 0xbfb8aa3b, v131
	v_exp_f32_e32 v130, v130
	v_exp_f32_e32 v131, v131
	v_mul_f32_e32 v128, 0xbfb8aa3b, v128
	v_mul_f32_e32 v129, 0xbfb8aa3b, v129
	v_exp_f32_e32 v128, v128
	v_pk_add_f32 v[130:131], v[130:131], 1.0 op_sel_hi:[1,0]
	v_exp_f32_e32 v129, v129
	v_div_scale_f32 v132, s[18:19], v131, v131, 1.0
	v_rcp_f32_e32 v137, v132
	v_pk_add_f32 v[128:129], v[128:129], 1.0 op_sel_hi:[1,0]
	v_fma_f32 v157, -v132, v137, 1.0
	v_fmac_f32_e32 v137, v157, v137
	v_div_scale_f32 v157, vcc, 1.0, v131, 1.0
	v_mul_f32_e32 v159, v157, v137
	v_fma_f32 v162, -v132, v159, v157
	v_fmac_f32_e32 v159, v162, v137
	v_fma_f32 v132, -v132, v159, v157
	v_div_fmas_f32 v132, v132, v137, v159
	v_div_fixup_f32 v131, v132, v131, 1.0
	v_div_scale_f32 v132, s[18:19], v130, v130, 1.0
	v_rcp_f32_e32 v137, v132
	s_nop 0
	v_fma_f32 v157, -v132, v137, 1.0
	v_fmac_f32_e32 v137, v157, v137
	v_div_scale_f32 v157, vcc, 1.0, v130, 1.0
	v_mul_f32_e32 v159, v157, v137
	v_fma_f32 v162, -v132, v159, v157
	v_fmac_f32_e32 v159, v162, v137
	v_fma_f32 v132, -v132, v159, v157
	v_div_fmas_f32 v132, v132, v137, v159
	v_div_fixup_f32 v130, v132, v130, 1.0
	v_div_scale_f32 v132, s[18:19], v129, v129, 1.0
	v_rcp_f32_e32 v137, v132
	s_nop 0
	v_fma_f32 v157, -v132, v137, 1.0
	v_fmac_f32_e32 v137, v157, v137
	v_div_scale_f32 v157, vcc, 1.0, v129, 1.0
	v_mul_f32_e32 v159, v157, v137
	v_fma_f32 v162, -v132, v159, v157
	v_fmac_f32_e32 v159, v162, v137
	v_fma_f32 v132, -v132, v159, v157
	v_div_fmas_f32 v132, v132, v137, v159
	v_div_fixup_f32 v129, v132, v129, 1.0
	v_div_scale_f32 v132, s[18:19], v128, v128, 1.0
	v_rcp_f32_e32 v137, v132
	s_nop 0
	v_fma_f32 v157, -v132, v137, 1.0
	v_fmac_f32_e32 v137, v157, v137
	v_div_scale_f32 v157, vcc, 1.0, v128, 1.0
	v_mul_f32_e32 v159, v157, v137
	v_fma_f32 v162, -v132, v159, v157
	v_fmac_f32_e32 v159, v162, v137
	v_fma_f32 v132, -v132, v159, v157
	v_div_fmas_f32 v132, v132, v137, v159
	v_div_fixup_f32 v128, v132, v128, 1.0
	v_add_f32_e32 v132, v3, v133
	v_mul_f32_e32 v132, 0xbfb8aa3b, v132
	v_exp_f32_e32 v137, v132
	v_pk_add_f32 v[132:133], v[134:135], 1.0 op_sel_hi:[1,0]
	v_pk_add_f32 v[134:135], v[136:137], 1.0 op_sel_hi:[1,0]
	s_nop 0
	v_div_scale_f32 v136, s[18:19], v135, v135, 1.0
	v_rcp_f32_e32 v137, v136
	s_nop 0
	v_fma_f32 v157, -v136, v137, 1.0
	v_fmac_f32_e32 v137, v157, v137
	v_div_scale_f32 v157, vcc, 1.0, v135, 1.0
	v_mul_f32_e32 v159, v157, v137
	v_fma_f32 v162, -v136, v159, v157
	v_fmac_f32_e32 v159, v162, v137
	v_fma_f32 v136, -v136, v159, v157
	v_div_fmas_f32 v136, v136, v137, v159
	v_div_fixup_f32 v135, v136, v135, 1.0
	v_div_scale_f32 v136, s[18:19], v134, v134, 1.0
	v_rcp_f32_e32 v137, v136
	s_nop 0
	v_fma_f32 v157, -v136, v137, 1.0
	v_fmac_f32_e32 v137, v157, v137
	v_div_scale_f32 v157, vcc, 1.0, v134, 1.0
	v_mul_f32_e32 v159, v157, v137
	v_fma_f32 v162, -v136, v159, v157
	v_fmac_f32_e32 v159, v162, v137
	v_fma_f32 v136, -v136, v159, v157
	v_div_fmas_f32 v136, v136, v137, v159
	v_div_fixup_f32 v134, v136, v134, 1.0
	v_div_scale_f32 v136, s[18:19], v133, v133, 1.0
	v_rcp_f32_e32 v137, v136
	s_nop 0
	v_fma_f32 v157, -v136, v137, 1.0
	v_fmac_f32_e32 v137, v157, v137
	v_div_scale_f32 v157, vcc, 1.0, v133, 1.0
	v_mul_f32_e32 v159, v157, v137
	v_fma_f32 v162, -v136, v159, v157
	v_fmac_f32_e32 v159, v162, v137
	v_fma_f32 v136, -v136, v159, v157
	v_div_fmas_f32 v136, v136, v137, v159
	v_div_fixup_f32 v133, v136, v133, 1.0
	v_div_scale_f32 v136, s[18:19], v132, v132, 1.0
	v_rcp_f32_e32 v137, v136
	s_nop 0
	v_fma_f32 v157, -v136, v137, 1.0
	v_fmac_f32_e32 v137, v157, v137
	v_div_scale_f32 v157, vcc, 1.0, v132, 1.0
	v_mul_f32_e32 v159, v157, v137
	v_fma_f32 v162, -v136, v159, v157
	v_fmac_f32_e32 v159, v162, v137
	v_fma_f32 v136, -v136, v159, v157
	v_div_fmas_f32 v136, v136, v137, v159
	v_div_fixup_f32 v132, v136, v132, 1.0
	v_lshl_add_u64 v[136:137], v[160:161], 0, v[180:181]
	v_lshl_add_u64 v[136:137], v[136:137], 2, s[20:21]
	global_store_dwordx4 v[136:137], v[128:131], off offset:512
	global_store_dwordx4 v[136:137], v[132:135], off offset:528
